# GEMM tile start: the 16 LDS fragment reads of the peeled first K iteration issued before the per-tile index arithmetic
# baseline (speedup 1.0000x reference)
.LBB0_213:
	ds_read_b128 v[104:107], v171
	ds_read_b128 v[108:111], v171 offset:1024
	ds_read_b128 v[112:115], v171 offset:2048
	ds_read_b128 v[116:119], v171 offset:3072
	ds_read_b128 v[160:163], v172
	ds_read_b128 v[164:167], v172 offset:1024
	ds_read_b128 v[178:181], v172 offset:2048
	ds_read_b128 v[182:185], v172 offset:3072
	ds_read_b128 v[186:189], v173
	ds_read_b128 v[190:193], v173 offset:1024
	ds_read_b128 v[194:197], v173 offset:2048
	ds_read_b128 v[198:201], v173 offset:3072
	ds_read_b128 v[206:209], v173 offset:4096
	ds_read_b128 v[210:213], v173 offset:5120
	ds_read_b128 v[214:217], v173 offset:6144
	ds_read_b128 v[218:221], v173 offset:7168
	s_add_i32 s48, s48, 1
	s_mul_i32 s2, s48, s59
	s_mul_hi_u32 s3, s48, s9
	s_add_i32 s3, s3, s2
	s_mul_i32 s2, s48, s9
	s_add_u32 s18, s2, s8
	s_addc_u32 s19, s3, s33
	v_cmp_gt_i64_e32 vcc, s[18:19], v[158:159]
	v_cmp_lt_i64_e64 s[2:3], s[18:19], v[156:157]
	s_cbranch_vccnz .LBB0_219
	s_ashr_i32 s14, s18, 31
	s_lshr_b32 s14, s14, 29
	s_add_i32 s16, s18, s14
	s_and_b32 s14, s16, -8
	s_sub_i32 s17, s18, s14
	s_cmp_gt_i32 s17, 3
	s_mov_b64 s[14:15], -1
	s_cbranch_scc0 .LBB0_216
	s_mul_i32 s14, s17, 0xb5
	s_add_i32 s18, s14, 4
	s_mov_b64 s[14:15], 0

.LBB0_219:
	s_ashr_i32 s17, s16, 31
	s_lshl_b64 s[18:19], s[16:17], 19
	s_add_u32 s18, s42, s18
	s_addc_u32 s19, s43, s19
	s_and_b64 s[20:21], s[2:3], exec
	s_cselect_b32 s17, s19, s25
	s_cselect_b32 s65, s18, s24
	s_ashr_i32 s15, s14, 31
	s_lshl_b64 s[20:21], s[14:15], 19
	s_add_u32 s20, s40, s20
	s_addc_u32 s21, s41, s21
	s_and_b64 s[34:35], s[2:3], exec
	s_cselect_b32 s15, s21, s27
	s_cselect_b32 s66, s20, s26
	s_add_u32 s24, s24, 0x40080
	s_addc_u32 s25, s25, 0
	s_add_u32 s67, s26, 0x100
	s_addc_u32 s68, s27, 0
	s_mov_b32 s69, -2
	s_waitcnt lgkmcnt(0)
	s_add_u32 s26, s24, 0xfffc0080
	s_addc_u32 s27, s25, -1
	s_cmp_eq_u32 s69, 12
	s_cselect_b32 s35, s17, s27
	s_cselect_b32 s34, s65, s26
	s_cselect_b32 s27, s15, s68
	s_cselect_b32 s26, s66, s67
	v_lshl_add_u64 v[202:203], s[24:25], 0, v[152:153]
	s_add_i32 m0, s23, 0xc000
	global_load_lds_dwordx4 v[202:203], off
	v_lshl_add_u64 v[202:203], s[24:25], 0, v[154:155]
	s_add_i32 m0, s23, 0xe000
	s_nop 0
	global_load_lds_dwordx4 v[202:203], off
	s_waitcnt vmcnt(8)
	s_waitcnt lgkmcnt(0)
	s_barrier
	s_waitcnt lgkmcnt(0)
	v_mfma_f32_16x16x32_f16 v[140:143], v[104:107], v[186:189], 0
	v_mfma_f32_16x16x32_f16 v[136:139], v[112:115], v[186:189], 0
	v_mfma_f32_16x16x32_f16 v[124:127], v[104:107], v[194:197], 0
	v_mfma_f32_16x16x32_f16 v[120:123], v[112:115], v[194:197], 0
	v_mfma_f32_16x16x32_f16 v[92:95], v[104:107], v[206:209], 0
	v_mfma_f32_16x16x32_f16 v[88:91], v[112:115], v[206:209], 0
	v_mfma_f32_16x16x32_f16 v[76:79], v[104:107], v[214:217], 0
	v_mfma_f32_16x16x32_f16 v[72:75], v[112:115], v[214:217], 0
	v_mfma_f32_16x16x32_f16 v[140:143], v[108:111], v[190:193], v[140:143]
	v_mfma_f32_16x16x32_f16 v[136:139], v[116:119], v[190:193], v[136:139]
	v_mfma_f32_16x16x32_f16 v[124:127], v[108:111], v[198:201], v[124:127]
	v_mfma_f32_16x16x32_f16 v[120:123], v[116:119], v[198:201], v[120:123]
	v_mfma_f32_16x16x32_f16 v[92:95], v[108:111], v[210:213], v[92:95]
	v_mfma_f32_16x16x32_f16 v[88:91], v[116:119], v[210:213], v[88:91]
	v_mfma_f32_16x16x32_f16 v[76:79], v[108:111], v[218:221], v[76:79]
	v_mfma_f32_16x16x32_f16 v[72:75], v[116:119], v[218:221], v[72:75]
	v_mfma_f32_16x16x32_f16 v[132:135], v[160:163], v[186:189], 0
	v_mfma_f32_16x16x32_f16 v[128:131], v[178:181], v[186:189], 0
	v_mfma_f32_16x16x32_f16 v[100:103], v[160:163], v[194:197], 0
	v_mfma_f32_16x16x32_f16 v[96:99], v[178:181], v[194:197], 0
	v_mfma_f32_16x16x32_f16 v[84:87], v[160:163], v[206:209], 0
	v_mfma_f32_16x16x32_f16 v[80:83], v[178:181], v[206:209], 0
	v_mfma_f32_16x16x32_f16 v[68:71], v[160:163], v[214:217], 0
	v_mfma_f32_16x16x32_f16 v[64:67], v[178:181], v[214:217], 0
	v_mfma_f32_16x16x32_f16 v[132:135], v[164:167], v[190:193], v[132:135]
	v_mfma_f32_16x16x32_f16 v[128:131], v[182:185], v[190:193], v[128:131]
	v_mfma_f32_16x16x32_f16 v[100:103], v[164:167], v[198:201], v[100:103]
	v_mfma_f32_16x16x32_f16 v[96:99], v[182:185], v[198:201], v[96:99]
	v_mfma_f32_16x16x32_f16 v[84:87], v[164:167], v[210:213], v[84:87]
	v_mfma_f32_16x16x32_f16 v[80:83], v[182:185], v[210:213], v[80:83]
	v_mfma_f32_16x16x32_f16 v[68:71], v[164:167], v[218:221], v[68:71]
	v_mfma_f32_16x16x32_f16 v[64:67], v[182:185], v[218:221], v[64:67]
	s_barrier
	s_add_i32 s70, s60, s44
	v_lshl_add_u64 v[202:203], s[26:27], 0, v[146:147]
	s_mov_b32 m0, s70
	ds_read_b128 v[186:189], v173 offset:16384
	ds_read_b128 v[190:193], v173 offset:17408
	ds_read_b128 v[194:197], v173 offset:18432
	ds_read_b128 v[198:201], v173 offset:19456
	ds_read_b128 v[206:209], v173 offset:20480
	ds_read_b128 v[210:213], v173 offset:21504
	ds_read_b128 v[214:217], v173 offset:22528
	ds_read_b128 v[218:221], v173 offset:23552
	global_load_lds_dwordx4 v[202:203], off
	s_add_i32 m0, s70, 0x2000
	s_add_u32 s70, s26, 0x40000
	v_lshl_add_u64 v[222:223], s[26:27], 0, v[150:151]
	s_addc_u32 s71, s27, 0
	s_add_i32 s72, s61, s44
	global_load_lds_dwordx4 v[222:223], off
	v_lshl_add_u64 v[224:225], s[70:71], 0, v[146:147]
	s_mov_b32 m0, s72
	v_lshl_add_u64 v[226:227], s[34:35], 0, v[148:149]
	global_load_lds_dwordx4 v[224:225], off
	v_lshl_add_u64 v[224:225], s[70:71], 0, v[150:151]
	s_add_i32 m0, s72, 0x2000
	s_nop 0
	global_load_lds_dwordx4 v[224:225], off
	v_lshl_add_u64 v[224:225], s[34:35], 0, v[144:145]
	s_mov_b32 m0, s23
	s_nop 0
	global_load_lds_dwordx4 v[224:225], off
	s_mov_b32 m0, s45
	s_nop 0
	global_load_lds_dwordx4 v[226:227], off
	s_waitcnt vmcnt(8)
	s_waitcnt lgkmcnt(0)
	s_barrier
	s_waitcnt lgkmcnt(0)
	v_mfma_f32_16x16x32_f16 v[60:63], v[104:107], v[186:189], 0
	v_mfma_f32_16x16x32_f16 v[56:59], v[112:115], v[186:189], 0
	v_mfma_f32_16x16x32_f16 v[44:47], v[104:107], v[194:197], 0
	v_mfma_f32_16x16x32_f16 v[40:43], v[112:115], v[194:197], 0
	v_mfma_f32_16x16x32_f16 v[28:31], v[104:107], v[206:209], 0
	v_mfma_f32_16x16x32_f16 v[24:27], v[112:115], v[206:209], 0
	v_mfma_f32_16x16x32_f16 v[12:15], v[104:107], v[214:217], 0
	v_mfma_f32_16x16x32_f16 v[8:11], v[112:115], v[214:217], 0
	v_mfma_f32_16x16x32_f16 v[60:63], v[108:111], v[190:193], v[60:63]
	v_mfma_f32_16x16x32_f16 v[56:59], v[116:119], v[190:193], v[56:59]
	v_mfma_f32_16x16x32_f16 v[44:47], v[108:111], v[198:201], v[44:47]
	v_mfma_f32_16x16x32_f16 v[40:43], v[116:119], v[198:201], v[40:43]
	v_mfma_f32_16x16x32_f16 v[28:31], v[108:111], v[210:213], v[28:31]
	v_mfma_f32_16x16x32_f16 v[24:27], v[116:119], v[210:213], v[24:27]
	v_mfma_f32_16x16x32_f16 v[12:15], v[108:111], v[218:221], v[12:15]
	v_mfma_f32_16x16x32_f16 v[8:11], v[116:119], v[218:221], v[8:11]
	v_mfma_f32_16x16x32_f16 v[52:55], v[160:163], v[186:189], 0
	v_mfma_f32_16x16x32_f16 v[48:51], v[178:181], v[186:189], 0
	v_mfma_f32_16x16x32_f16 v[36:39], v[160:163], v[194:197], 0
	v_mfma_f32_16x16x32_f16 v[32:35], v[178:181], v[194:197], 0
	v_mfma_f32_16x16x32_f16 v[20:23], v[160:163], v[206:209], 0
	v_mfma_f32_16x16x32_f16 v[16:19], v[178:181], v[206:209], 0
	v_mfma_f32_16x16x32_f16 v[4:7], v[160:163], v[214:217], 0
	v_mfma_f32_16x16x32_f16 v[0:3], v[178:181], v[214:217], 0
	v_mfma_f32_16x16x32_f16 v[52:55], v[164:167], v[190:193], v[52:55]
	v_mfma_f32_16x16x32_f16 v[48:51], v[182:185], v[190:193], v[48:51]
	v_mfma_f32_16x16x32_f16 v[36:39], v[164:167], v[198:201], v[36:39]
	v_mfma_f32_16x16x32_f16 v[32:35], v[182:185], v[198:201], v[32:35]
	v_mfma_f32_16x16x32_f16 v[20:23], v[164:167], v[210:213], v[20:23]
	v_mfma_f32_16x16x32_f16 v[16:19], v[182:185], v[210:213], v[16:19]
	v_mfma_f32_16x16x32_f16 v[4:7], v[164:167], v[218:221], v[4:7]
	v_mfma_f32_16x16x32_f16 v[0:3], v[182:185], v[218:221], v[0:3]
	s_barrier
	s_add_i32 s70, 0, 0x18000
	s_add_i32 s71, 0, 0x1c000
	v_add_u32_e32 v116, s70, v169
	v_add_u32_e32 v177, s71, v169
	ds_read_b128 v[104:107], v116
	ds_read_b128 v[108:111], v116 offset:1024
	ds_read_b128 v[112:115], v116 offset:2048
	ds_read_b128 v[116:119], v116 offset:3072
	ds_read_b128 v[160:163], v177
	ds_read_b128 v[164:167], v177 offset:1024
	ds_read_b128 v[178:181], v177 offset:2048
	ds_read_b128 v[182:185], v177 offset:3072
	s_add_u32 s34, s34, 0x40000
	s_addc_u32 s35, s35, 0
	s_mov_b32 m0, s46
	v_lshl_add_u64 v[228:229], s[34:35], 0, v[144:145]
	ds_read_b128 v[186:189], v173 offset:32768
	ds_read_b128 v[190:193], v173 offset:33792
	ds_read_b128 v[194:197], v173 offset:34816
	ds_read_b128 v[198:201], v173 offset:35840
	ds_read_b128 v[206:209], v173 offset:36864
	ds_read_b128 v[210:213], v173 offset:37888
	ds_read_b128 v[214:217], v173 offset:38912
	ds_read_b128 v[218:221], v173 offset:39936
	global_load_lds_dwordx4 v[228:229], off
	v_lshl_add_u64 v[228:229], s[34:35], 0, v[148:149]
	s_mov_b32 m0, s47
	s_nop 0
	global_load_lds_dwordx4 v[228:229], off
	s_waitcnt vmcnt(8)
	s_waitcnt lgkmcnt(0)
	s_barrier
	s_waitcnt lgkmcnt(0)
	v_mfma_f32_16x16x32_f16 v[140:143], v[104:107], v[186:189], v[140:143]
	v_mfma_f32_16x16x32_f16 v[136:139], v[112:115], v[186:189], v[136:139]
	v_mfma_f32_16x16x32_f16 v[124:127], v[104:107], v[194:197], v[124:127]
	v_mfma_f32_16x16x32_f16 v[120:123], v[112:115], v[194:197], v[120:123]
	v_mfma_f32_16x16x32_f16 v[92:95], v[104:107], v[206:209], v[92:95]
	v_mfma_f32_16x16x32_f16 v[88:91], v[112:115], v[206:209], v[88:91]
	v_mfma_f32_16x16x32_f16 v[76:79], v[104:107], v[214:217], v[76:79]
	v_mfma_f32_16x16x32_f16 v[72:75], v[112:115], v[214:217], v[72:75]
	v_mfma_f32_16x16x32_f16 v[140:143], v[108:111], v[190:193], v[140:143]
	v_mfma_f32_16x16x32_f16 v[136:139], v[116:119], v[190:193], v[136:139]
	v_mfma_f32_16x16x32_f16 v[124:127], v[108:111], v[198:201], v[124:127]
	v_mfma_f32_16x16x32_f16 v[120:123], v[116:119], v[198:201], v[120:123]
	v_mfma_f32_16x16x32_f16 v[92:95], v[108:111], v[210:213], v[92:95]
	v_mfma_f32_16x16x32_f16 v[88:91], v[116:119], v[210:213], v[88:91]
	v_mfma_f32_16x16x32_f16 v[76:79], v[108:111], v[218:221], v[76:79]
	v_mfma_f32_16x16x32_f16 v[72:75], v[116:119], v[218:221], v[72:75]
	v_mfma_f32_16x16x32_f16 v[132:135], v[160:163], v[186:189], v[132:135]
	v_mfma_f32_16x16x32_f16 v[128:131], v[178:181], v[186:189], v[128:131]
	v_mfma_f32_16x16x32_f16 v[100:103], v[160:163], v[194:197], v[100:103]
	v_mfma_f32_16x16x32_f16 v[96:99], v[178:181], v[194:197], v[96:99]
	v_mfma_f32_16x16x32_f16 v[84:87], v[160:163], v[206:209], v[84:87]
	v_mfma_f32_16x16x32_f16 v[80:83], v[178:181], v[206:209], v[80:83]
	v_mfma_f32_16x16x32_f16 v[68:71], v[160:163], v[214:217], v[68:71]
	v_mfma_f32_16x16x32_f16 v[64:67], v[178:181], v[214:217], v[64:67]
	v_mfma_f32_16x16x32_f16 v[132:135], v[164:167], v[190:193], v[132:135]
	v_mfma_f32_16x16x32_f16 v[128:131], v[182:185], v[190:193], v[128:131]
	v_mfma_f32_16x16x32_f16 v[100:103], v[164:167], v[198:201], v[100:103]
	v_mfma_f32_16x16x32_f16 v[96:99], v[182:185], v[198:201], v[96:99]
	v_mfma_f32_16x16x32_f16 v[84:87], v[164:167], v[210:213], v[84:87]
	v_mfma_f32_16x16x32_f16 v[80:83], v[182:185], v[210:213], v[80:83]
	v_mfma_f32_16x16x32_f16 v[68:71], v[164:167], v[218:221], v[68:71]
	v_mfma_f32_16x16x32_f16 v[64:67], v[182:185], v[218:221], v[64:67]
	s_barrier
	s_add_i32 s34, s70, s44
	v_lshl_add_u64 v[202:203], v[202:203], 0, s[10:11]
	s_mov_b32 m0, s34
	ds_read_b128 v[186:189], v173 offset:49152
	ds_read_b128 v[190:193], v173 offset:50176
	ds_read_b128 v[194:197], v173 offset:51200
	ds_read_b128 v[198:201], v173 offset:52224
	ds_read_b128 v[206:209], v173 offset:53248
	ds_read_b128 v[210:213], v173 offset:54272
	ds_read_b128 v[214:217], v173 offset:55296
	ds_read_b128 v[218:221], v173 offset:56320
	global_load_lds_dwordx4 v[202:203], off
	s_add_i32 m0, s34, 0x2000
	s_add_u32 s26, s26, 0x40080
	v_lshl_add_u64 v[202:203], v[222:223], 0, s[10:11]
	s_addc_u32 s27, s27, 0
	s_add_i32 s34, s71, s44
	global_load_lds_dwordx4 v[202:203], off
	v_lshl_add_u64 v[202:203], s[26:27], 0, v[146:147]
	s_mov_b32 m0, s34
	s_nop 0
	global_load_lds_dwordx4 v[202:203], off
	v_lshl_add_u64 v[202:203], s[26:27], 0, v[150:151]
	s_add_i32 m0, s34, 0x2000
	s_nop 0
	global_load_lds_dwordx4 v[202:203], off
	v_lshl_add_u64 v[202:203], v[224:225], 0, s[10:11]
	s_mov_b32 m0, s57
	s_nop 0
	global_load_lds_dwordx4 v[202:203], off
	v_lshl_add_u64 v[202:203], v[226:227], 0, s[10:11]
	s_mov_b32 m0, s58
	s_nop 0
	global_load_lds_dwordx4 v[202:203], off
	s_waitcnt vmcnt(8)
	s_waitcnt lgkmcnt(0)
	s_barrier
	s_waitcnt lgkmcnt(0)
	v_mfma_f32_16x16x32_f16 v[60:63], v[104:107], v[186:189], v[60:63]
	v_mfma_f32_16x16x32_f16 v[56:59], v[112:115], v[186:189], v[56:59]
	v_mfma_f32_16x16x32_f16 v[44:47], v[104:107], v[194:197], v[44:47]
	v_mfma_f32_16x16x32_f16 v[40:43], v[112:115], v[194:197], v[40:43]
	v_mfma_f32_16x16x32_f16 v[28:31], v[104:107], v[206:209], v[28:31]
	v_mfma_f32_16x16x32_f16 v[24:27], v[112:115], v[206:209], v[24:27]
	v_mfma_f32_16x16x32_f16 v[12:15], v[104:107], v[214:217], v[12:15]
	v_mfma_f32_16x16x32_f16 v[8:11], v[112:115], v[214:217], v[8:11]
	v_mfma_f32_16x16x32_f16 v[60:63], v[108:111], v[190:193], v[60:63]
	v_mfma_f32_16x16x32_f16 v[56:59], v[116:119], v[190:193], v[56:59]
	v_mfma_f32_16x16x32_f16 v[44:47], v[108:111], v[198:201], v[44:47]
	v_mfma_f32_16x16x32_f16 v[40:43], v[116:119], v[198:201], v[40:43]
	v_mfma_f32_16x16x32_f16 v[28:31], v[108:111], v[210:213], v[28:31]
	v_mfma_f32_16x16x32_f16 v[24:27], v[116:119], v[210:213], v[24:27]
	v_mfma_f32_16x16x32_f16 v[12:15], v[108:111], v[218:221], v[12:15]
	v_mfma_f32_16x16x32_f16 v[8:11], v[116:119], v[218:221], v[8:11]
	v_mfma_f32_16x16x32_f16 v[52:55], v[160:163], v[186:189], v[52:55]
	v_mfma_f32_16x16x32_f16 v[48:51], v[178:181], v[186:189], v[48:51]
	v_mfma_f32_16x16x32_f16 v[36:39], v[160:163], v[194:197], v[36:39]
	v_mfma_f32_16x16x32_f16 v[32:35], v[178:181], v[194:197], v[32:35]
	v_mfma_f32_16x16x32_f16 v[20:23], v[160:163], v[206:209], v[20:23]
	v_mfma_f32_16x16x32_f16 v[16:19], v[178:181], v[206:209], v[16:19]
	v_mfma_f32_16x16x32_f16 v[4:7], v[160:163], v[214:217], v[4:7]
	v_mfma_f32_16x16x32_f16 v[0:3], v[178:181], v[214:217], v[0:3]
	v_mfma_f32_16x16x32_f16 v[52:55], v[164:167], v[190:193], v[52:55]
	v_mfma_f32_16x16x32_f16 v[48:51], v[182:185], v[190:193], v[48:51]
	v_mfma_f32_16x16x32_f16 v[36:39], v[164:167], v[198:201], v[36:39]
	v_mfma_f32_16x16x32_f16 v[32:35], v[182:185], v[198:201], v[32:35]
	v_mfma_f32_16x16x32_f16 v[20:23], v[164:167], v[210:213], v[20:23]
	v_mfma_f32_16x16x32_f16 v[16:19], v[182:185], v[210:213], v[16:19]
	v_mfma_f32_16x16x32_f16 v[4:7], v[164:167], v[218:221], v[4:7]
	v_mfma_f32_16x16x32_f16 v[0:3], v[182:185], v[218:221], v[0:3]
	s_barrier
	s_add_i32 s69, s69, 2
	s_add_u32 s24, s24, 0x100
	s_addc_u32 s25, s25, 0
	s_add_u32 s67, s67, 0x100
	s_addc_u32 s68, s68, 0
	s_cmp_gt_u32 s69, 13

.LBB0_330:
	ds_read_b128 v[80:83], v208
	ds_read_b128 v[84:87], v208 offset:1024
	ds_read_b128 v[92:95], v208 offset:2048
	ds_read_b128 v[96:99], v208 offset:3072
	ds_read_b128 v[144:147], v209
	ds_read_b128 v[148:151], v209 offset:1024
	ds_read_b128 v[152:155], v209 offset:2048
	ds_read_b128 v[156:159], v209 offset:3072
	ds_read_b128 v[178:181], v210
	ds_read_b128 v[182:185], v210 offset:1024
	ds_read_b128 v[186:189], v210 offset:2048
	ds_read_b128 v[190:193], v210 offset:3072
	ds_read_b128 v[194:197], v210 offset:4096
	ds_read_b128 v[198:201], v210 offset:5120
	ds_read_b128 v[212:215], v210 offset:6144
	ds_read_b128 v[216:219], v210 offset:7168
	s_add_i32 s46, s46, 1
	s_mul_i32 s0, s46, s57
	s_mul_hi_u32 s1, s46, s9
	s_add_i32 s1, s1, s0
	s_mul_i32 s0, s46, s9
	s_add_u32 s4, s0, s8
	s_addc_u32 s5, s1, s58
	v_cmp_gt_i64_e32 vcc, s[4:5], v[174:175]
	v_cmp_lt_i64_e64 s[0:1], s[4:5], v[172:173]
	s_cbranch_vccnz .LBB0_336
	s_ashr_i32 s5, s4, 31
	s_lshr_b32 s5, s5, 29
	s_add_i32 s20, s4, s5
	s_and_b32 s5, s20, -8
	s_sub_i32 s21, s4, s5
	s_cmp_gt_i32 s21, -1
	s_mov_b64 s[4:5], -1
	s_cbranch_scc0 .LBB0_333
	s_lshl_b32 s26, s21, 5
	s_mov_b64 s[4:5], 0

.LBB0_340:
	s_add_u32 s65, s24, 0x100
	s_addc_u32 s66, s25, 0
	s_mov_b32 s67, -2
	s_waitcnt lgkmcnt(0)
	s_waitcnt lgkmcnt(0)
	s_add_u32 s24, s22, 0x100
	s_addc_u32 s25, s23, 0
	s_cmp_eq_u32 s67, 40
	s_cselect_b32 s35, s1, s25
	s_cselect_b32 s34, s0, s24
	s_cselect_b32 s27, s21, s66
	s_cselect_b32 s26, s20, s65
	v_lshl_add_u64 v[202:203], s[22:23], 0, v[168:169]
	s_add_i32 m0, s40, 0xc000
	global_load_lds_dwordx4 v[202:203], off
	v_lshl_add_u64 v[202:203], s[22:23], 0, v[170:171]
	s_add_i32 m0, s40, 0xe000
	s_nop 0
	global_load_lds_dwordx4 v[202:203], off
	s_waitcnt vmcnt(8)
	s_waitcnt lgkmcnt(0)
	s_barrier
	s_waitcnt lgkmcnt(0)
	v_mfma_f32_16x16x32_f16 v[140:143], v[80:83], v[178:181], 0
	v_mfma_f32_16x16x32_f16 v[136:139], v[92:95], v[178:181], 0
	v_mfma_f32_16x16x32_f16 v[124:127], v[80:83], v[186:189], 0
	v_mfma_f32_16x16x32_f16 v[120:123], v[92:95], v[186:189], 0
	v_mfma_f32_16x16x32_f16 v[108:111], v[80:83], v[194:197], 0
	v_mfma_f32_16x16x32_f16 v[104:107], v[92:95], v[194:197], 0
	v_mfma_f32_16x16x32_f16 v[76:79], v[80:83], v[212:215], 0
	v_mfma_f32_16x16x32_f16 v[72:75], v[92:95], v[212:215], 0
	v_mfma_f32_16x16x32_f16 v[140:143], v[84:87], v[182:185], v[140:143]
	v_mfma_f32_16x16x32_f16 v[136:139], v[96:99], v[182:185], v[136:139]
	v_mfma_f32_16x16x32_f16 v[124:127], v[84:87], v[190:193], v[124:127]
	v_mfma_f32_16x16x32_f16 v[120:123], v[96:99], v[190:193], v[120:123]
	v_mfma_f32_16x16x32_f16 v[108:111], v[84:87], v[198:201], v[108:111]
	v_mfma_f32_16x16x32_f16 v[104:107], v[96:99], v[198:201], v[104:107]
	v_mfma_f32_16x16x32_f16 v[76:79], v[84:87], v[216:219], v[76:79]
	v_mfma_f32_16x16x32_f16 v[72:75], v[96:99], v[216:219], v[72:75]
	v_mfma_f32_16x16x32_f16 v[132:135], v[144:147], v[178:181], 0
	v_mfma_f32_16x16x32_f16 v[128:131], v[152:155], v[178:181], 0
	v_mfma_f32_16x16x32_f16 v[116:119], v[144:147], v[186:189], 0
	v_mfma_f32_16x16x32_f16 v[112:115], v[152:155], v[186:189], 0
	v_mfma_f32_16x16x32_f16 v[100:103], v[144:147], v[194:197], 0
	v_mfma_f32_16x16x32_f16 v[88:91], v[152:155], v[194:197], 0
	v_mfma_f32_16x16x32_f16 v[68:71], v[144:147], v[212:215], 0
	v_mfma_f32_16x16x32_f16 v[64:67], v[152:155], v[212:215], 0
	v_mfma_f32_16x16x32_f16 v[132:135], v[148:151], v[182:185], v[132:135]
	v_mfma_f32_16x16x32_f16 v[128:131], v[156:159], v[182:185], v[128:131]
	v_mfma_f32_16x16x32_f16 v[116:119], v[148:151], v[190:193], v[116:119]
	v_mfma_f32_16x16x32_f16 v[112:115], v[156:159], v[190:193], v[112:115]
	v_mfma_f32_16x16x32_f16 v[100:103], v[148:151], v[198:201], v[100:103]
	v_mfma_f32_16x16x32_f16 v[88:91], v[156:159], v[198:201], v[88:91]
	v_mfma_f32_16x16x32_f16 v[68:71], v[148:151], v[216:219], v[68:71]
	v_mfma_f32_16x16x32_f16 v[64:67], v[156:159], v[216:219], v[64:67]
	s_barrier
	s_add_i32 s22, s59, s33
	v_lshl_add_u64 v[202:203], s[26:27], 0, v[162:163]
	s_mov_b32 m0, s22
	ds_read_b128 v[178:181], v210 offset:16384
	ds_read_b128 v[182:185], v210 offset:17408
	ds_read_b128 v[186:189], v210 offset:18432
	ds_read_b128 v[190:193], v210 offset:19456
	ds_read_b128 v[194:197], v210 offset:20480
	ds_read_b128 v[198:201], v210 offset:21504
	ds_read_b128 v[212:215], v210 offset:22528
	ds_read_b128 v[216:219], v210 offset:23552
	global_load_lds_dwordx4 v[202:203], off
	s_add_i32 m0, s22, 0x2000
	s_add_u32 s22, s26, 0xb0000
	v_lshl_add_u64 v[220:221], s[26:27], 0, v[166:167]
	s_addc_u32 s23, s27, 0
	s_add_i32 s68, s60, s33
	global_load_lds_dwordx4 v[220:221], off
	v_lshl_add_u64 v[222:223], s[22:23], 0, v[162:163]
	s_mov_b32 m0, s68
	v_lshl_add_u64 v[224:225], s[34:35], 0, v[164:165]
	global_load_lds_dwordx4 v[222:223], off
	v_lshl_add_u64 v[222:223], s[22:23], 0, v[166:167]
	s_add_i32 m0, s68, 0x2000
	s_nop 0
	global_load_lds_dwordx4 v[222:223], off
	v_lshl_add_u64 v[222:223], s[34:35], 0, v[160:161]
	s_mov_b32 m0, s40
	s_nop 0
	global_load_lds_dwordx4 v[222:223], off
	s_mov_b32 m0, s41
	s_nop 0
	global_load_lds_dwordx4 v[224:225], off
	s_waitcnt vmcnt(8)
	s_waitcnt lgkmcnt(0)
	s_barrier
	s_waitcnt lgkmcnt(0)
	v_mfma_f32_16x16x32_f16 v[60:63], v[80:83], v[178:181], 0
	v_mfma_f32_16x16x32_f16 v[56:59], v[92:95], v[178:181], 0
	v_mfma_f32_16x16x32_f16 v[44:47], v[80:83], v[186:189], 0
	v_mfma_f32_16x16x32_f16 v[40:43], v[92:95], v[186:189], 0
	v_mfma_f32_16x16x32_f16 v[28:31], v[80:83], v[194:197], 0
	v_mfma_f32_16x16x32_f16 v[24:27], v[92:95], v[194:197], 0
	v_mfma_f32_16x16x32_f16 v[12:15], v[80:83], v[212:215], 0
	v_mfma_f32_16x16x32_f16 v[8:11], v[92:95], v[212:215], 0
	v_mfma_f32_16x16x32_f16 v[60:63], v[84:87], v[182:185], v[60:63]
	v_mfma_f32_16x16x32_f16 v[56:59], v[96:99], v[182:185], v[56:59]
	v_mfma_f32_16x16x32_f16 v[44:47], v[84:87], v[190:193], v[44:47]
	v_mfma_f32_16x16x32_f16 v[40:43], v[96:99], v[190:193], v[40:43]
	v_mfma_f32_16x16x32_f16 v[28:31], v[84:87], v[198:201], v[28:31]
	v_mfma_f32_16x16x32_f16 v[24:27], v[96:99], v[198:201], v[24:27]
	v_mfma_f32_16x16x32_f16 v[12:15], v[84:87], v[216:219], v[12:15]
	v_mfma_f32_16x16x32_f16 v[8:11], v[96:99], v[216:219], v[8:11]
	v_mfma_f32_16x16x32_f16 v[52:55], v[144:147], v[178:181], 0
	v_mfma_f32_16x16x32_f16 v[48:51], v[152:155], v[178:181], 0
	v_mfma_f32_16x16x32_f16 v[36:39], v[144:147], v[186:189], 0
	v_mfma_f32_16x16x32_f16 v[32:35], v[152:155], v[186:189], 0
	v_mfma_f32_16x16x32_f16 v[20:23], v[144:147], v[194:197], 0
	v_mfma_f32_16x16x32_f16 v[16:19], v[152:155], v[194:197], 0
	v_mfma_f32_16x16x32_f16 v[4:7], v[144:147], v[212:215], 0
	v_mfma_f32_16x16x32_f16 v[0:3], v[152:155], v[212:215], 0
	v_mfma_f32_16x16x32_f16 v[52:55], v[148:151], v[182:185], v[52:55]
	v_mfma_f32_16x16x32_f16 v[48:51], v[156:159], v[182:185], v[48:51]
	v_mfma_f32_16x16x32_f16 v[36:39], v[148:151], v[190:193], v[36:39]
	v_mfma_f32_16x16x32_f16 v[32:35], v[156:159], v[190:193], v[32:35]
	v_mfma_f32_16x16x32_f16 v[20:23], v[148:151], v[198:201], v[20:23]
	v_mfma_f32_16x16x32_f16 v[16:19], v[156:159], v[198:201], v[16:19]
	v_mfma_f32_16x16x32_f16 v[4:7], v[148:151], v[216:219], v[4:7]
	v_mfma_f32_16x16x32_f16 v[0:3], v[156:159], v[216:219], v[0:3]
	s_barrier
	s_add_i32 s68, 0, 0x18000
	s_add_i32 s69, 0, 0x1c000
	v_add_u32_e32 v96, s68, v206
	v_add_u32_e32 v156, s69, v206
	ds_read_b128 v[80:83], v96
	ds_read_b128 v[84:87], v96 offset:1024
	ds_read_b128 v[92:95], v96 offset:2048
	ds_read_b128 v[96:99], v96 offset:3072
	ds_read_b128 v[144:147], v156
	ds_read_b128 v[148:151], v156 offset:1024
	ds_read_b128 v[152:155], v156 offset:2048
	ds_read_b128 v[156:159], v156 offset:3072
	s_add_u32 s22, s34, 0xb0000
	s_addc_u32 s23, s35, 0
	s_mov_b32 m0, s44
	v_lshl_add_u64 v[226:227], s[22:23], 0, v[160:161]
	ds_read_b128 v[178:181], v210 offset:32768
	ds_read_b128 v[182:185], v210 offset:33792
	ds_read_b128 v[186:189], v210 offset:34816
	ds_read_b128 v[190:193], v210 offset:35840
	ds_read_b128 v[194:197], v210 offset:36864
	ds_read_b128 v[198:201], v210 offset:37888
	ds_read_b128 v[212:215], v210 offset:38912
	ds_read_b128 v[216:219], v210 offset:39936
	global_load_lds_dwordx4 v[226:227], off
	v_lshl_add_u64 v[226:227], s[22:23], 0, v[164:165]
	s_mov_b32 m0, s45
	s_nop 0
	global_load_lds_dwordx4 v[226:227], off
	s_waitcnt vmcnt(8)
	s_waitcnt lgkmcnt(0)
	s_barrier
	s_waitcnt lgkmcnt(0)
	v_mfma_f32_16x16x32_f16 v[140:143], v[80:83], v[178:181], v[140:143]
	v_mfma_f32_16x16x32_f16 v[136:139], v[92:95], v[178:181], v[136:139]
	v_mfma_f32_16x16x32_f16 v[124:127], v[80:83], v[186:189], v[124:127]
	v_mfma_f32_16x16x32_f16 v[120:123], v[92:95], v[186:189], v[120:123]
	v_mfma_f32_16x16x32_f16 v[108:111], v[80:83], v[194:197], v[108:111]
	v_mfma_f32_16x16x32_f16 v[104:107], v[92:95], v[194:197], v[104:107]
	v_mfma_f32_16x16x32_f16 v[76:79], v[80:83], v[212:215], v[76:79]
	v_mfma_f32_16x16x32_f16 v[72:75], v[92:95], v[212:215], v[72:75]
	v_mfma_f32_16x16x32_f16 v[140:143], v[84:87], v[182:185], v[140:143]
	v_mfma_f32_16x16x32_f16 v[136:139], v[96:99], v[182:185], v[136:139]
	v_mfma_f32_16x16x32_f16 v[124:127], v[84:87], v[190:193], v[124:127]
	v_mfma_f32_16x16x32_f16 v[120:123], v[96:99], v[190:193], v[120:123]
	v_mfma_f32_16x16x32_f16 v[108:111], v[84:87], v[198:201], v[108:111]
	v_mfma_f32_16x16x32_f16 v[104:107], v[96:99], v[198:201], v[104:107]
	v_mfma_f32_16x16x32_f16 v[76:79], v[84:87], v[216:219], v[76:79]
	v_mfma_f32_16x16x32_f16 v[72:75], v[96:99], v[216:219], v[72:75]
	v_mfma_f32_16x16x32_f16 v[132:135], v[144:147], v[178:181], v[132:135]
	v_mfma_f32_16x16x32_f16 v[128:131], v[152:155], v[178:181], v[128:131]
	v_mfma_f32_16x16x32_f16 v[116:119], v[144:147], v[186:189], v[116:119]
	v_mfma_f32_16x16x32_f16 v[112:115], v[152:155], v[186:189], v[112:115]
	v_mfma_f32_16x16x32_f16 v[100:103], v[144:147], v[194:197], v[100:103]
	v_mfma_f32_16x16x32_f16 v[88:91], v[152:155], v[194:197], v[88:91]
	v_mfma_f32_16x16x32_f16 v[68:71], v[144:147], v[212:215], v[68:71]
	v_mfma_f32_16x16x32_f16 v[64:67], v[152:155], v[212:215], v[64:67]
	v_mfma_f32_16x16x32_f16 v[132:135], v[148:151], v[182:185], v[132:135]
	v_mfma_f32_16x16x32_f16 v[128:131], v[156:159], v[182:185], v[128:131]
	v_mfma_f32_16x16x32_f16 v[116:119], v[148:151], v[190:193], v[116:119]
	v_mfma_f32_16x16x32_f16 v[112:115], v[156:159], v[190:193], v[112:115]
	v_mfma_f32_16x16x32_f16 v[100:103], v[148:151], v[198:201], v[100:103]
	v_mfma_f32_16x16x32_f16 v[88:91], v[156:159], v[198:201], v[88:91]
	v_mfma_f32_16x16x32_f16 v[68:71], v[148:151], v[216:219], v[68:71]
	v_mfma_f32_16x16x32_f16 v[64:67], v[156:159], v[216:219], v[64:67]
	s_barrier
	s_add_i32 s22, s68, s33
	v_lshl_add_u64 v[202:203], v[202:203], 0, s[16:17]
	s_mov_b32 m0, s22
	ds_read_b128 v[178:181], v210 offset:49152
	ds_read_b128 v[182:185], v210 offset:50176
	ds_read_b128 v[186:189], v210 offset:51200
	ds_read_b128 v[190:193], v210 offset:52224
	ds_read_b128 v[194:197], v210 offset:53248
	ds_read_b128 v[198:201], v210 offset:54272
	ds_read_b128 v[212:215], v210 offset:55296
	ds_read_b128 v[216:219], v210 offset:56320
	global_load_lds_dwordx4 v[202:203], off
	s_add_i32 m0, s22, 0x2000
	s_add_u32 s22, s26, 0xb0080
	v_lshl_add_u64 v[202:203], v[220:221], 0, s[16:17]
	s_addc_u32 s23, s27, 0
	s_add_i32 s26, s69, s33
	global_load_lds_dwordx4 v[202:203], off
	v_lshl_add_u64 v[202:203], s[22:23], 0, v[162:163]
	s_mov_b32 m0, s26
	s_nop 0
	global_load_lds_dwordx4 v[202:203], off
	v_lshl_add_u64 v[202:203], s[22:23], 0, v[166:167]
	s_add_i32 m0, s26, 0x2000
	s_nop 0
	global_load_lds_dwordx4 v[202:203], off
	v_lshl_add_u64 v[202:203], v[222:223], 0, s[16:17]
	s_mov_b32 m0, s55
	s_nop 0
	global_load_lds_dwordx4 v[202:203], off
	v_lshl_add_u64 v[202:203], v[224:225], 0, s[16:17]
	s_mov_b32 m0, s56
	s_nop 0
	global_load_lds_dwordx4 v[202:203], off
	s_waitcnt vmcnt(8)
	s_waitcnt lgkmcnt(0)
	s_barrier
	s_waitcnt lgkmcnt(0)
	v_mfma_f32_16x16x32_f16 v[60:63], v[80:83], v[178:181], v[60:63]
	v_mfma_f32_16x16x32_f16 v[56:59], v[92:95], v[178:181], v[56:59]
	v_mfma_f32_16x16x32_f16 v[44:47], v[80:83], v[186:189], v[44:47]
	v_mfma_f32_16x16x32_f16 v[40:43], v[92:95], v[186:189], v[40:43]
	v_mfma_f32_16x16x32_f16 v[28:31], v[80:83], v[194:197], v[28:31]
	v_mfma_f32_16x16x32_f16 v[24:27], v[92:95], v[194:197], v[24:27]
	v_mfma_f32_16x16x32_f16 v[12:15], v[80:83], v[212:215], v[12:15]
	v_mfma_f32_16x16x32_f16 v[8:11], v[92:95], v[212:215], v[8:11]
	v_mfma_f32_16x16x32_f16 v[60:63], v[84:87], v[182:185], v[60:63]
	v_mfma_f32_16x16x32_f16 v[56:59], v[96:99], v[182:185], v[56:59]
	v_mfma_f32_16x16x32_f16 v[44:47], v[84:87], v[190:193], v[44:47]
	v_mfma_f32_16x16x32_f16 v[40:43], v[96:99], v[190:193], v[40:43]
	v_mfma_f32_16x16x32_f16 v[28:31], v[84:87], v[198:201], v[28:31]
	v_mfma_f32_16x16x32_f16 v[24:27], v[96:99], v[198:201], v[24:27]
	v_mfma_f32_16x16x32_f16 v[12:15], v[84:87], v[216:219], v[12:15]
	v_mfma_f32_16x16x32_f16 v[8:11], v[96:99], v[216:219], v[8:11]
	v_mfma_f32_16x16x32_f16 v[52:55], v[144:147], v[178:181], v[52:55]
	v_mfma_f32_16x16x32_f16 v[48:51], v[152:155], v[178:181], v[48:51]
	v_mfma_f32_16x16x32_f16 v[36:39], v[144:147], v[186:189], v[36:39]
	v_mfma_f32_16x16x32_f16 v[32:35], v[152:155], v[186:189], v[32:35]
	v_mfma_f32_16x16x32_f16 v[20:23], v[144:147], v[194:197], v[20:23]
	v_mfma_f32_16x16x32_f16 v[16:19], v[152:155], v[194:197], v[16:19]
	v_mfma_f32_16x16x32_f16 v[4:7], v[144:147], v[212:215], v[4:7]
	v_mfma_f32_16x16x32_f16 v[0:3], v[152:155], v[212:215], v[0:3]
	v_mfma_f32_16x16x32_f16 v[52:55], v[148:151], v[182:185], v[52:55]
	v_mfma_f32_16x16x32_f16 v[48:51], v[156:159], v[182:185], v[48:51]
	v_mfma_f32_16x16x32_f16 v[36:39], v[148:151], v[190:193], v[36:39]
	v_mfma_f32_16x16x32_f16 v[32:35], v[156:159], v[190:193], v[32:35]
	v_mfma_f32_16x16x32_f16 v[20:23], v[148:151], v[198:201], v[20:23]
	v_mfma_f32_16x16x32_f16 v[16:19], v[156:159], v[198:201], v[16:19]
	v_mfma_f32_16x16x32_f16 v[4:7], v[148:151], v[216:219], v[4:7]
	v_mfma_f32_16x16x32_f16 v[0:3], v[156:159], v[216:219], v[0:3]
	s_barrier
	s_add_i32 s67, s67, 2
	s_add_u32 s65, s65, 0x100
	s_addc_u32 s66, s66, 0
	s_cmp_gt_u32 s67, 41
	s_mov_b64 s[22:23], s[24:25]

.LBB0_457:
	ds_read_b128 v[128:131], v167
	ds_read_b128 v[132:135], v167 offset:1024
	ds_read_b128 v[136:139], v167 offset:2048
	ds_read_b128 v[140:143], v167 offset:3072
	ds_read_b128 v[160:163], v168
	ds_read_b128 v[172:175], v168 offset:1024
	ds_read_b128 v[178:181], v168 offset:2048
	ds_read_b128 v[182:185], v168 offset:3072
	ds_read_b128 v[186:189], v169
	ds_read_b128 v[190:193], v169 offset:1024
	ds_read_b128 v[194:197], v169 offset:2048
	ds_read_b128 v[198:201], v169 offset:3072
	ds_read_b128 v[206:209], v169 offset:4096
	ds_read_b128 v[210:213], v169 offset:5120
	ds_read_b128 v[214:217], v169 offset:6144
	ds_read_b128 v[218:221], v169 offset:7168
	s_add_i32 s56, s56, 1
	s_mul_i32 s2, s56, s61
	s_mul_hi_u32 s3, s56, s9
	s_add_i32 s3, s3, s2
	s_mul_i32 s2, s56, s9
	s_add_u32 s24, s2, s8
	s_addc_u32 s25, s3, s33
	v_cmp_gt_i64_e32 vcc, s[24:25], v[158:159]
	v_cmp_lt_i64_e64 s[2:3], s[24:25], v[156:157]
	s_cbranch_vccnz .LBB0_463
	s_ashr_i32 s20, s24, 31
	s_lshr_b32 s20, s20, 29
	s_add_i32 s22, s24, s20
	s_and_b32 s20, s22, -8
	s_sub_i32 s23, s24, s20
	s_cmp_gt_i32 s23, -1
	s_mov_b64 s[20:21], -1
	s_cbranch_scc0 .LBB0_460
	s_lshl_b32 s24, s23, 5
	s_mov_b64 s[20:21], 0

.LBB0_463:
	s_ashr_i32 s23, s22, 31
	s_lshl_b64 s[24:25], s[22:23], 19
	s_add_u32 s24, s42, s24
	s_addc_u32 s25, s43, s25
	s_and_b64 s[26:27], s[2:3], exec
	s_cselect_b32 s23, s25, s41
	s_cselect_b32 s69, s24, s40
	s_ashr_i32 s21, s20, 31
	s_lshl_b64 s[26:27], s[20:21], 19
	s_add_u32 s26, s12, s26
	s_addc_u32 s27, s13, s27
	s_and_b64 s[46:47], s[2:3], exec
	s_cselect_b32 s21, s27, s45
	s_cselect_b32 s70, s26, s44
	s_add_u32 s40, s40, 0x40080
	s_addc_u32 s41, s41, 0
	s_add_u32 s71, s44, 0x100
	s_addc_u32 s72, s45, 0
	s_mov_b32 s73, -2
	s_waitcnt lgkmcnt(0)
	s_add_u32 s44, s40, 0xfffc0080
	s_addc_u32 s45, s41, -1
	s_cmp_eq_u32 s73, 12
	s_cselect_b32 s47, s23, s45
	s_cselect_b32 s46, s69, s44
	s_cselect_b32 s45, s21, s72
	s_cselect_b32 s44, s70, s71
	v_lshl_add_u64 v[202:203], s[40:41], 0, v[152:153]
	s_add_i32 m0, s35, 0xc000
	global_load_lds_dwordx4 v[202:203], off
	v_lshl_add_u64 v[202:203], s[40:41], 0, v[154:155]
	s_add_i32 m0, s35, 0xe000
	s_nop 0
	global_load_lds_dwordx4 v[202:203], off
	s_waitcnt vmcnt(8)
	s_waitcnt lgkmcnt(0)
	s_barrier
	s_waitcnt lgkmcnt(0)
	v_mfma_f32_16x16x32_f16 v[124:127], v[128:131], v[186:189], 0
	v_mfma_f32_16x16x32_f16 v[120:123], v[136:139], v[186:189], 0
	v_mfma_f32_16x16x32_f16 v[108:111], v[128:131], v[194:197], 0
	v_mfma_f32_16x16x32_f16 v[104:107], v[136:139], v[194:197], 0
	v_mfma_f32_16x16x32_f16 v[92:95], v[128:131], v[206:209], 0
	v_mfma_f32_16x16x32_f16 v[88:91], v[136:139], v[206:209], 0
	v_mfma_f32_16x16x32_f16 v[84:87], v[128:131], v[214:217], 0
	v_mfma_f32_16x16x32_f16 v[76:79], v[136:139], v[214:217], 0
	v_mfma_f32_16x16x32_f16 v[124:127], v[132:135], v[190:193], v[124:127]
	v_mfma_f32_16x16x32_f16 v[120:123], v[140:143], v[190:193], v[120:123]
	v_mfma_f32_16x16x32_f16 v[108:111], v[132:135], v[198:201], v[108:111]
	v_mfma_f32_16x16x32_f16 v[104:107], v[140:143], v[198:201], v[104:107]
	v_mfma_f32_16x16x32_f16 v[92:95], v[132:135], v[210:213], v[92:95]
	v_mfma_f32_16x16x32_f16 v[88:91], v[140:143], v[210:213], v[88:91]
	v_mfma_f32_16x16x32_f16 v[84:87], v[132:135], v[218:221], v[84:87]
	v_mfma_f32_16x16x32_f16 v[76:79], v[140:143], v[218:221], v[76:79]
	v_mfma_f32_16x16x32_f16 v[116:119], v[160:163], v[186:189], 0
	v_mfma_f32_16x16x32_f16 v[112:115], v[178:181], v[186:189], 0
	v_mfma_f32_16x16x32_f16 v[100:103], v[160:163], v[194:197], 0
	v_mfma_f32_16x16x32_f16 v[96:99], v[178:181], v[194:197], 0
	v_mfma_f32_16x16x32_f16 v[80:83], v[160:163], v[206:209], 0
	v_mfma_f32_16x16x32_f16 v[72:75], v[178:181], v[206:209], 0
	v_mfma_f32_16x16x32_f16 v[68:71], v[160:163], v[214:217], 0
	v_mfma_f32_16x16x32_f16 v[64:67], v[178:181], v[214:217], 0
	v_mfma_f32_16x16x32_f16 v[116:119], v[172:175], v[190:193], v[116:119]
	v_mfma_f32_16x16x32_f16 v[112:115], v[182:185], v[190:193], v[112:115]
	v_mfma_f32_16x16x32_f16 v[100:103], v[172:175], v[198:201], v[100:103]
	v_mfma_f32_16x16x32_f16 v[96:99], v[182:185], v[198:201], v[96:99]
	v_mfma_f32_16x16x32_f16 v[80:83], v[172:175], v[210:213], v[80:83]
	v_mfma_f32_16x16x32_f16 v[72:75], v[182:185], v[210:213], v[72:75]
	v_mfma_f32_16x16x32_f16 v[68:71], v[172:175], v[218:221], v[68:71]
	v_mfma_f32_16x16x32_f16 v[64:67], v[182:185], v[218:221], v[64:67]
	s_barrier
	s_add_i32 s74, s62, s48
	v_lshl_add_u64 v[202:203], s[44:45], 0, v[146:147]
	s_mov_b32 m0, s74
	ds_read_b128 v[186:189], v169 offset:16384
	ds_read_b128 v[190:193], v169 offset:17408
	ds_read_b128 v[194:197], v169 offset:18432
	ds_read_b128 v[198:201], v169 offset:19456
	ds_read_b128 v[206:209], v169 offset:20480
	ds_read_b128 v[210:213], v169 offset:21504
	ds_read_b128 v[214:217], v169 offset:22528
	ds_read_b128 v[218:221], v169 offset:23552
	global_load_lds_dwordx4 v[202:203], off
	s_add_i32 m0, s74, 0x2000
	s_add_u32 s74, s44, 0x40000
	v_lshl_add_u64 v[222:223], s[44:45], 0, v[150:151]
	s_addc_u32 s75, s45, 0
	s_add_i32 s76, s63, s48
	global_load_lds_dwordx4 v[222:223], off
	v_lshl_add_u64 v[224:225], s[74:75], 0, v[146:147]
	s_mov_b32 m0, s76
	v_lshl_add_u64 v[226:227], s[46:47], 0, v[148:149]
	global_load_lds_dwordx4 v[224:225], off
	v_lshl_add_u64 v[224:225], s[74:75], 0, v[150:151]
	s_add_i32 m0, s76, 0x2000
	s_nop 0
	global_load_lds_dwordx4 v[224:225], off
	v_lshl_add_u64 v[224:225], s[46:47], 0, v[144:145]
	s_mov_b32 m0, s35
	s_nop 0
	global_load_lds_dwordx4 v[224:225], off
	s_mov_b32 m0, s49
	s_nop 0
	global_load_lds_dwordx4 v[226:227], off
	s_waitcnt vmcnt(8)
	s_waitcnt lgkmcnt(0)
	s_barrier
	s_waitcnt lgkmcnt(0)
	v_mfma_f32_16x16x32_f16 v[60:63], v[128:131], v[186:189], 0
	v_mfma_f32_16x16x32_f16 v[56:59], v[136:139], v[186:189], 0
	v_mfma_f32_16x16x32_f16 v[44:47], v[128:131], v[194:197], 0
	v_mfma_f32_16x16x32_f16 v[40:43], v[136:139], v[194:197], 0
	v_mfma_f32_16x16x32_f16 v[28:31], v[128:131], v[206:209], 0
	v_mfma_f32_16x16x32_f16 v[24:27], v[136:139], v[206:209], 0
	v_mfma_f32_16x16x32_f16 v[12:15], v[128:131], v[214:217], 0
	v_mfma_f32_16x16x32_f16 v[8:11], v[136:139], v[214:217], 0
	v_mfma_f32_16x16x32_f16 v[60:63], v[132:135], v[190:193], v[60:63]
	v_mfma_f32_16x16x32_f16 v[56:59], v[140:143], v[190:193], v[56:59]
	v_mfma_f32_16x16x32_f16 v[44:47], v[132:135], v[198:201], v[44:47]
	v_mfma_f32_16x16x32_f16 v[40:43], v[140:143], v[198:201], v[40:43]
	v_mfma_f32_16x16x32_f16 v[28:31], v[132:135], v[210:213], v[28:31]
	v_mfma_f32_16x16x32_f16 v[24:27], v[140:143], v[210:213], v[24:27]
	v_mfma_f32_16x16x32_f16 v[12:15], v[132:135], v[218:221], v[12:15]
	v_mfma_f32_16x16x32_f16 v[8:11], v[140:143], v[218:221], v[8:11]
	v_mfma_f32_16x16x32_f16 v[52:55], v[160:163], v[186:189], 0
	v_mfma_f32_16x16x32_f16 v[48:51], v[178:181], v[186:189], 0
	v_mfma_f32_16x16x32_f16 v[36:39], v[160:163], v[194:197], 0
	v_mfma_f32_16x16x32_f16 v[32:35], v[178:181], v[194:197], 0
	v_mfma_f32_16x16x32_f16 v[20:23], v[160:163], v[206:209], 0
	v_mfma_f32_16x16x32_f16 v[16:19], v[178:181], v[206:209], 0
	v_mfma_f32_16x16x32_f16 v[4:7], v[160:163], v[214:217], 0
	v_mfma_f32_16x16x32_f16 v[0:3], v[178:181], v[214:217], 0
	v_mfma_f32_16x16x32_f16 v[52:55], v[172:175], v[190:193], v[52:55]
	v_mfma_f32_16x16x32_f16 v[48:51], v[182:185], v[190:193], v[48:51]
	v_mfma_f32_16x16x32_f16 v[36:39], v[172:175], v[198:201], v[36:39]
	v_mfma_f32_16x16x32_f16 v[32:35], v[182:185], v[198:201], v[32:35]
	v_mfma_f32_16x16x32_f16 v[20:23], v[172:175], v[210:213], v[20:23]
	v_mfma_f32_16x16x32_f16 v[16:19], v[182:185], v[210:213], v[16:19]
	v_mfma_f32_16x16x32_f16 v[4:7], v[172:175], v[218:221], v[4:7]
	v_mfma_f32_16x16x32_f16 v[0:3], v[182:185], v[218:221], v[0:3]
	s_barrier
	s_add_i32 s74, 0, 0x18000
	s_add_i32 s75, 0, 0x1c000
	v_add_u32_e32 v140, s74, v165
	v_add_u32_e32 v177, s75, v165
	ds_read_b128 v[128:131], v140
	ds_read_b128 v[132:135], v140 offset:1024
	ds_read_b128 v[136:139], v140 offset:2048
	ds_read_b128 v[140:143], v140 offset:3072
	ds_read_b128 v[160:163], v177
	ds_read_b128 v[172:175], v177 offset:1024
	ds_read_b128 v[178:181], v177 offset:2048
	ds_read_b128 v[182:185], v177 offset:3072
	s_add_u32 s46, s46, 0x40000
	s_addc_u32 s47, s47, 0
	s_mov_b32 m0, s54
	v_lshl_add_u64 v[228:229], s[46:47], 0, v[144:145]
	ds_read_b128 v[186:189], v169 offset:32768
	ds_read_b128 v[190:193], v169 offset:33792
	ds_read_b128 v[194:197], v169 offset:34816
	ds_read_b128 v[198:201], v169 offset:35840
	ds_read_b128 v[206:209], v169 offset:36864
	ds_read_b128 v[210:213], v169 offset:37888
	ds_read_b128 v[214:217], v169 offset:38912
	ds_read_b128 v[218:221], v169 offset:39936
	global_load_lds_dwordx4 v[228:229], off
	v_lshl_add_u64 v[228:229], s[46:47], 0, v[148:149]
	s_mov_b32 m0, s55
	s_nop 0
	global_load_lds_dwordx4 v[228:229], off
	s_waitcnt vmcnt(8)
	s_waitcnt lgkmcnt(0)
	s_barrier
	s_waitcnt lgkmcnt(0)
	v_mfma_f32_16x16x32_f16 v[124:127], v[128:131], v[186:189], v[124:127]
	v_mfma_f32_16x16x32_f16 v[120:123], v[136:139], v[186:189], v[120:123]
	v_mfma_f32_16x16x32_f16 v[108:111], v[128:131], v[194:197], v[108:111]
	v_mfma_f32_16x16x32_f16 v[104:107], v[136:139], v[194:197], v[104:107]
	v_mfma_f32_16x16x32_f16 v[92:95], v[128:131], v[206:209], v[92:95]
	v_mfma_f32_16x16x32_f16 v[88:91], v[136:139], v[206:209], v[88:91]
	v_mfma_f32_16x16x32_f16 v[84:87], v[128:131], v[214:217], v[84:87]
	v_mfma_f32_16x16x32_f16 v[76:79], v[136:139], v[214:217], v[76:79]
	v_mfma_f32_16x16x32_f16 v[124:127], v[132:135], v[190:193], v[124:127]
	v_mfma_f32_16x16x32_f16 v[120:123], v[140:143], v[190:193], v[120:123]
	v_mfma_f32_16x16x32_f16 v[108:111], v[132:135], v[198:201], v[108:111]
	v_mfma_f32_16x16x32_f16 v[104:107], v[140:143], v[198:201], v[104:107]
	v_mfma_f32_16x16x32_f16 v[92:95], v[132:135], v[210:213], v[92:95]
	v_mfma_f32_16x16x32_f16 v[88:91], v[140:143], v[210:213], v[88:91]
	v_mfma_f32_16x16x32_f16 v[84:87], v[132:135], v[218:221], v[84:87]
	v_mfma_f32_16x16x32_f16 v[76:79], v[140:143], v[218:221], v[76:79]
	v_mfma_f32_16x16x32_f16 v[116:119], v[160:163], v[186:189], v[116:119]
	v_mfma_f32_16x16x32_f16 v[112:115], v[178:181], v[186:189], v[112:115]
	v_mfma_f32_16x16x32_f16 v[100:103], v[160:163], v[194:197], v[100:103]
	v_mfma_f32_16x16x32_f16 v[96:99], v[178:181], v[194:197], v[96:99]
	v_mfma_f32_16x16x32_f16 v[80:83], v[160:163], v[206:209], v[80:83]
	v_mfma_f32_16x16x32_f16 v[72:75], v[178:181], v[206:209], v[72:75]
	v_mfma_f32_16x16x32_f16 v[68:71], v[160:163], v[214:217], v[68:71]
	v_mfma_f32_16x16x32_f16 v[64:67], v[178:181], v[214:217], v[64:67]
	v_mfma_f32_16x16x32_f16 v[116:119], v[172:175], v[190:193], v[116:119]
	v_mfma_f32_16x16x32_f16 v[112:115], v[182:185], v[190:193], v[112:115]
	v_mfma_f32_16x16x32_f16 v[100:103], v[172:175], v[198:201], v[100:103]
	v_mfma_f32_16x16x32_f16 v[96:99], v[182:185], v[198:201], v[96:99]
	v_mfma_f32_16x16x32_f16 v[80:83], v[172:175], v[210:213], v[80:83]
	v_mfma_f32_16x16x32_f16 v[72:75], v[182:185], v[210:213], v[72:75]
	v_mfma_f32_16x16x32_f16 v[68:71], v[172:175], v[218:221], v[68:71]
	v_mfma_f32_16x16x32_f16 v[64:67], v[182:185], v[218:221], v[64:67]
	s_barrier
	s_add_i32 s46, s74, s48
	v_lshl_add_u64 v[202:203], v[202:203], 0, s[4:5]
	s_mov_b32 m0, s46
	ds_read_b128 v[186:189], v169 offset:49152
	ds_read_b128 v[190:193], v169 offset:50176
	ds_read_b128 v[194:197], v169 offset:51200
	ds_read_b128 v[198:201], v169 offset:52224
	ds_read_b128 v[206:209], v169 offset:53248
	ds_read_b128 v[210:213], v169 offset:54272
	ds_read_b128 v[214:217], v169 offset:55296
	ds_read_b128 v[218:221], v169 offset:56320
	global_load_lds_dwordx4 v[202:203], off
	s_add_i32 m0, s46, 0x2000
	s_add_u32 s44, s44, 0x40080
	v_lshl_add_u64 v[202:203], v[222:223], 0, s[4:5]
	s_addc_u32 s45, s45, 0
	s_add_i32 s46, s75, s48
	global_load_lds_dwordx4 v[202:203], off
	v_lshl_add_u64 v[202:203], s[44:45], 0, v[146:147]
	s_mov_b32 m0, s46
	s_nop 0
	global_load_lds_dwordx4 v[202:203], off
	v_lshl_add_u64 v[202:203], s[44:45], 0, v[150:151]
	s_add_i32 m0, s46, 0x2000
	s_nop 0
	global_load_lds_dwordx4 v[202:203], off
	v_lshl_add_u64 v[202:203], v[224:225], 0, s[4:5]
	s_mov_b32 m0, s59
	s_nop 0
	global_load_lds_dwordx4 v[202:203], off
	v_lshl_add_u64 v[202:203], v[226:227], 0, s[4:5]
	s_mov_b32 m0, s60
	s_nop 0
	global_load_lds_dwordx4 v[202:203], off
	s_waitcnt vmcnt(8)
	s_waitcnt lgkmcnt(0)
	s_barrier
	s_waitcnt lgkmcnt(0)
	v_mfma_f32_16x16x32_f16 v[60:63], v[128:131], v[186:189], v[60:63]
	v_mfma_f32_16x16x32_f16 v[56:59], v[136:139], v[186:189], v[56:59]
	v_mfma_f32_16x16x32_f16 v[44:47], v[128:131], v[194:197], v[44:47]
	v_mfma_f32_16x16x32_f16 v[40:43], v[136:139], v[194:197], v[40:43]
	v_mfma_f32_16x16x32_f16 v[28:31], v[128:131], v[206:209], v[28:31]
	v_mfma_f32_16x16x32_f16 v[24:27], v[136:139], v[206:209], v[24:27]
	v_mfma_f32_16x16x32_f16 v[12:15], v[128:131], v[214:217], v[12:15]
	v_mfma_f32_16x16x32_f16 v[8:11], v[136:139], v[214:217], v[8:11]
	v_mfma_f32_16x16x32_f16 v[60:63], v[132:135], v[190:193], v[60:63]
	v_mfma_f32_16x16x32_f16 v[56:59], v[140:143], v[190:193], v[56:59]
	v_mfma_f32_16x16x32_f16 v[44:47], v[132:135], v[198:201], v[44:47]
	v_mfma_f32_16x16x32_f16 v[40:43], v[140:143], v[198:201], v[40:43]
	v_mfma_f32_16x16x32_f16 v[28:31], v[132:135], v[210:213], v[28:31]
	v_mfma_f32_16x16x32_f16 v[24:27], v[140:143], v[210:213], v[24:27]
	v_mfma_f32_16x16x32_f16 v[12:15], v[132:135], v[218:221], v[12:15]
	v_mfma_f32_16x16x32_f16 v[8:11], v[140:143], v[218:221], v[8:11]
	v_mfma_f32_16x16x32_f16 v[52:55], v[160:163], v[186:189], v[52:55]
	v_mfma_f32_16x16x32_f16 v[48:51], v[178:181], v[186:189], v[48:51]
	v_mfma_f32_16x16x32_f16 v[36:39], v[160:163], v[194:197], v[36:39]
	v_mfma_f32_16x16x32_f16 v[32:35], v[178:181], v[194:197], v[32:35]
	v_mfma_f32_16x16x32_f16 v[20:23], v[160:163], v[206:209], v[20:23]
	v_mfma_f32_16x16x32_f16 v[16:19], v[178:181], v[206:209], v[16:19]
	v_mfma_f32_16x16x32_f16 v[4:7], v[160:163], v[214:217], v[4:7]
	v_mfma_f32_16x16x32_f16 v[0:3], v[178:181], v[214:217], v[0:3]
	v_mfma_f32_16x16x32_f16 v[52:55], v[172:175], v[190:193], v[52:55]
	v_mfma_f32_16x16x32_f16 v[48:51], v[182:185], v[190:193], v[48:51]
	v_mfma_f32_16x16x32_f16 v[36:39], v[172:175], v[198:201], v[36:39]
	v_mfma_f32_16x16x32_f16 v[32:35], v[182:185], v[198:201], v[32:35]
	v_mfma_f32_16x16x32_f16 v[20:23], v[172:175], v[210:213], v[20:23]
	v_mfma_f32_16x16x32_f16 v[16:19], v[182:185], v[210:213], v[16:19]
	v_mfma_f32_16x16x32_f16 v[4:7], v[172:175], v[218:221], v[4:7]
	v_mfma_f32_16x16x32_f16 v[0:3], v[182:185], v[218:221], v[0:3]
	s_barrier
	s_add_i32 s73, s73, 2
	s_add_u32 s40, s40, 0x100
	s_addc_u32 s41, s41, 0
	s_add_u32 s71, s71, 0x100
	s_addc_u32 s72, s72, 0
	s_cmp_gt_u32 s73, 13

.LBB0_727:
	ds_read_b128 v[84:87], v208
	ds_read_b128 v[88:91], v208 offset:1024
	ds_read_b128 v[92:95], v208 offset:2048
	ds_read_b128 v[100:103], v208 offset:3072
	ds_read_b128 v[144:147], v209
	ds_read_b128 v[148:151], v209 offset:1024
	ds_read_b128 v[152:155], v209 offset:2048
	ds_read_b128 v[156:159], v209 offset:3072
	ds_read_b128 v[160:163], v210
	ds_read_b128 v[164:167], v210 offset:1024
	ds_read_b128 v[186:189], v210 offset:2048
	ds_read_b128 v[190:193], v210 offset:3072
	ds_read_b128 v[194:197], v210 offset:4096
	ds_read_b128 v[198:201], v210 offset:5120
	ds_read_b128 v[212:215], v210 offset:6144
	ds_read_b128 v[216:219], v210 offset:7168
	s_add_i32 s57, s57, 1
	s_mul_i32 s4, s57, s64
	s_mul_hi_u32 s5, s57, s9
	s_add_i32 s5, s5, s4
	s_mul_i32 s4, s57, s9
	s_add_u32 s20, s4, s8
	s_addc_u32 s21, s5, s65
	v_cmp_gt_i64_e32 vcc, s[20:21], v[184:185]
	v_cmp_lt_i64_e64 s[4:5], s[20:21], v[182:183]
	s_cbranch_vccnz .LBB0_733
	s_ashr_i32 s16, s20, 31
	s_lshr_b32 s16, s16, 29
	s_add_i32 s18, s20, s16
	s_and_b32 s16, s18, -8
	s_sub_i32 s19, s20, s16
	s_cmp_gt_i32 s19, -1
	s_mov_b64 s[16:17], -1
	s_cbranch_scc0 .LBB0_730
	s_lshl_b32 s20, s19, 6
	s_mov_b64 s[16:17], 0

.LBB0_733:
	s_ashr_i32 s19, s18, 31
	s_lshl_b64 s[20:21], s[18:19], 19
	s_add_u32 s20, s33, s20
	s_addc_u32 s21, s46, s21
	s_and_b64 s[22:23], s[4:5], exec
	s_cselect_b32 s19, s21, s35
	s_cselect_b32 s25, s20, s34
	s_ashr_i32 s17, s16, 31
	s_lshl_b64 s[22:23], s[16:17], 19
	s_add_u32 s22, s47, s22
	s_addc_u32 s23, s48, s23
	s_and_b64 s[44:45], s[4:5], exec
	s_cselect_b32 s17, s23, s41
	s_cselect_b32 s68, s22, s40
	s_add_u32 s34, s34, 0x40080
	s_addc_u32 s35, s35, 0
	s_add_u32 s69, s40, 0x100
	s_addc_u32 s70, s41, 0
	s_mov_b32 s71, -2
	s_waitcnt lgkmcnt(0)
	s_waitcnt lgkmcnt(0)
	s_add_u32 s40, s34, 0xfffc0080
	s_addc_u32 s41, s35, -1
	s_cmp_eq_u32 s71, 12
	s_cselect_b32 s45, s19, s41
	s_cselect_b32 s44, s25, s40
	s_cselect_b32 s41, s17, s70
	s_cselect_b32 s40, s68, s69
	v_lshl_add_u64 v[202:203], s[34:35], 0, v[178:179]
	s_add_i32 m0, s27, 0xc000
	global_load_lds_dwordx4 v[202:203], off
	v_lshl_add_u64 v[202:203], s[34:35], 0, v[180:181]
	s_add_i32 m0, s27, 0xe000
	s_nop 0
	global_load_lds_dwordx4 v[202:203], off
	s_waitcnt vmcnt(8)
	s_waitcnt lgkmcnt(0)
	s_barrier
	s_waitcnt lgkmcnt(0)
	v_mfma_f32_16x16x32_f16 v[136:139], v[84:87], v[160:163], 0
	v_mfma_f32_16x16x32_f16 v[128:131], v[92:95], v[160:163], 0
	v_mfma_f32_16x16x32_f16 v[124:127], v[84:87], v[186:189], 0
	v_mfma_f32_16x16x32_f16 v[116:119], v[92:95], v[186:189], 0
	v_mfma_f32_16x16x32_f16 v[108:111], v[84:87], v[194:197], 0
	v_mfma_f32_16x16x32_f16 v[96:99], v[92:95], v[194:197], 0
	v_mfma_f32_16x16x32_f16 v[76:79], v[84:87], v[212:215], 0
	v_mfma_f32_16x16x32_f16 v[68:71], v[92:95], v[212:215], 0
	v_mfma_f32_16x16x32_f16 v[136:139], v[88:91], v[164:167], v[136:139]
	v_mfma_f32_16x16x32_f16 v[128:131], v[100:103], v[164:167], v[128:131]
	v_mfma_f32_16x16x32_f16 v[124:127], v[88:91], v[190:193], v[124:127]
	v_mfma_f32_16x16x32_f16 v[116:119], v[100:103], v[190:193], v[116:119]
	v_mfma_f32_16x16x32_f16 v[108:111], v[88:91], v[198:201], v[108:111]
	v_mfma_f32_16x16x32_f16 v[96:99], v[100:103], v[198:201], v[96:99]
	v_mfma_f32_16x16x32_f16 v[76:79], v[88:91], v[216:219], v[76:79]
	v_mfma_f32_16x16x32_f16 v[68:71], v[100:103], v[216:219], v[68:71]
	v_mfma_f32_16x16x32_f16 v[140:143], v[144:147], v[160:163], 0
	v_mfma_f32_16x16x32_f16 v[132:135], v[152:155], v[160:163], 0
	v_mfma_f32_16x16x32_f16 v[120:123], v[144:147], v[186:189], 0
	v_mfma_f32_16x16x32_f16 v[112:115], v[152:155], v[186:189], 0
	v_mfma_f32_16x16x32_f16 v[104:107], v[144:147], v[194:197], 0
	v_mfma_f32_16x16x32_f16 v[80:83], v[152:155], v[194:197], 0
	v_mfma_f32_16x16x32_f16 v[72:75], v[144:147], v[212:215], 0
	v_mfma_f32_16x16x32_f16 v[64:67], v[152:155], v[212:215], 0
	v_mfma_f32_16x16x32_f16 v[140:143], v[148:151], v[164:167], v[140:143]
	v_mfma_f32_16x16x32_f16 v[132:135], v[156:159], v[164:167], v[132:135]
	v_mfma_f32_16x16x32_f16 v[120:123], v[148:151], v[190:193], v[120:123]
	v_mfma_f32_16x16x32_f16 v[112:115], v[156:159], v[190:193], v[112:115]
	v_mfma_f32_16x16x32_f16 v[104:107], v[148:151], v[198:201], v[104:107]
	v_mfma_f32_16x16x32_f16 v[80:83], v[156:159], v[198:201], v[80:83]
	v_mfma_f32_16x16x32_f16 v[72:75], v[148:151], v[216:219], v[72:75]
	v_mfma_f32_16x16x32_f16 v[64:67], v[156:159], v[216:219], v[64:67]
	s_barrier
	s_add_i32 s72, s66, s49
	v_lshl_add_u64 v[202:203], s[40:41], 0, v[170:171]
	s_mov_b32 m0, s72
	ds_read_b128 v[160:163], v210 offset:16384
	ds_read_b128 v[164:167], v210 offset:17408
	ds_read_b128 v[186:189], v210 offset:18432
	ds_read_b128 v[190:193], v210 offset:19456
	ds_read_b128 v[194:197], v210 offset:20480
	ds_read_b128 v[198:201], v210 offset:21504
	ds_read_b128 v[212:215], v210 offset:22528
	ds_read_b128 v[216:219], v210 offset:23552
	global_load_lds_dwordx4 v[202:203], off
	s_add_i32 m0, s72, 0x2000
	s_add_u32 s72, s40, 0x40000
	v_lshl_add_u64 v[220:221], s[40:41], 0, v[174:175]
	s_addc_u32 s73, s41, 0
	s_add_i32 s74, s67, s49
	global_load_lds_dwordx4 v[220:221], off
	v_lshl_add_u64 v[222:223], s[72:73], 0, v[170:171]
	s_mov_b32 m0, s74
	v_lshl_add_u64 v[224:225], s[44:45], 0, v[172:173]
	global_load_lds_dwordx4 v[222:223], off
	v_lshl_add_u64 v[222:223], s[72:73], 0, v[174:175]
	s_add_i32 m0, s74, 0x2000
	s_nop 0
	global_load_lds_dwordx4 v[222:223], off
	v_lshl_add_u64 v[222:223], s[44:45], 0, v[168:169]
	s_mov_b32 m0, s27
	s_nop 0
	global_load_lds_dwordx4 v[222:223], off
	s_mov_b32 m0, s54
	s_nop 0
	global_load_lds_dwordx4 v[224:225], off
	s_waitcnt vmcnt(8)
	s_waitcnt lgkmcnt(0)
	s_barrier
	s_waitcnt lgkmcnt(0)
	v_mfma_f32_16x16x32_f16 v[60:63], v[84:87], v[160:163], 0
	v_mfma_f32_16x16x32_f16 v[52:55], v[92:95], v[160:163], 0
	v_mfma_f32_16x16x32_f16 v[44:47], v[84:87], v[186:189], 0
	v_mfma_f32_16x16x32_f16 v[36:39], v[92:95], v[186:189], 0
	v_mfma_f32_16x16x32_f16 v[28:31], v[84:87], v[194:197], 0
	v_mfma_f32_16x16x32_f16 v[20:23], v[92:95], v[194:197], 0
	v_mfma_f32_16x16x32_f16 v[12:15], v[84:87], v[212:215], 0
	v_mfma_f32_16x16x32_f16 v[4:7], v[92:95], v[212:215], 0
	v_mfma_f32_16x16x32_f16 v[60:63], v[88:91], v[164:167], v[60:63]
	v_mfma_f32_16x16x32_f16 v[52:55], v[100:103], v[164:167], v[52:55]
	v_mfma_f32_16x16x32_f16 v[44:47], v[88:91], v[190:193], v[44:47]
	v_mfma_f32_16x16x32_f16 v[36:39], v[100:103], v[190:193], v[36:39]
	v_mfma_f32_16x16x32_f16 v[28:31], v[88:91], v[198:201], v[28:31]
	v_mfma_f32_16x16x32_f16 v[20:23], v[100:103], v[198:201], v[20:23]
	v_mfma_f32_16x16x32_f16 v[12:15], v[88:91], v[216:219], v[12:15]
	v_mfma_f32_16x16x32_f16 v[4:7], v[100:103], v[216:219], v[4:7]
	v_mfma_f32_16x16x32_f16 v[56:59], v[144:147], v[160:163], 0
	v_mfma_f32_16x16x32_f16 v[48:51], v[152:155], v[160:163], 0
	v_mfma_f32_16x16x32_f16 v[40:43], v[144:147], v[186:189], 0
	v_mfma_f32_16x16x32_f16 v[32:35], v[152:155], v[186:189], 0
	v_mfma_f32_16x16x32_f16 v[24:27], v[144:147], v[194:197], 0
	v_mfma_f32_16x16x32_f16 v[16:19], v[152:155], v[194:197], 0
	v_mfma_f32_16x16x32_f16 v[8:11], v[144:147], v[212:215], 0
	v_mfma_f32_16x16x32_f16 v[0:3], v[152:155], v[212:215], 0
	v_mfma_f32_16x16x32_f16 v[56:59], v[148:151], v[164:167], v[56:59]
	v_mfma_f32_16x16x32_f16 v[48:51], v[156:159], v[164:167], v[48:51]
	v_mfma_f32_16x16x32_f16 v[40:43], v[148:151], v[190:193], v[40:43]
	v_mfma_f32_16x16x32_f16 v[32:35], v[156:159], v[190:193], v[32:35]
	v_mfma_f32_16x16x32_f16 v[24:27], v[148:151], v[198:201], v[24:27]
	v_mfma_f32_16x16x32_f16 v[16:19], v[156:159], v[198:201], v[16:19]
	v_mfma_f32_16x16x32_f16 v[8:11], v[148:151], v[216:219], v[8:11]
	v_mfma_f32_16x16x32_f16 v[0:3], v[156:159], v[216:219], v[0:3]
	s_barrier
	s_add_i32 s72, 0, 0x18000
	s_add_i32 s73, 0, 0x1c000
	v_add_u32_e32 v100, s72, v206
	v_add_u32_e32 v156, s73, v206
	ds_read_b128 v[84:87], v100
	ds_read_b128 v[88:91], v100 offset:1024
	ds_read_b128 v[92:95], v100 offset:2048
	ds_read_b128 v[100:103], v100 offset:3072
	ds_read_b128 v[144:147], v156
	ds_read_b128 v[148:151], v156 offset:1024
	ds_read_b128 v[152:155], v156 offset:2048
	ds_read_b128 v[156:159], v156 offset:3072
	s_add_u32 s44, s44, 0x40000
	s_addc_u32 s45, s45, 0
	s_mov_b32 m0, s55
	v_lshl_add_u64 v[226:227], s[44:45], 0, v[168:169]
	ds_read_b128 v[160:163], v210 offset:32768
	ds_read_b128 v[164:167], v210 offset:33792
	ds_read_b128 v[186:189], v210 offset:34816
	ds_read_b128 v[190:193], v210 offset:35840
	ds_read_b128 v[194:197], v210 offset:36864
	ds_read_b128 v[198:201], v210 offset:37888
	ds_read_b128 v[212:215], v210 offset:38912
	ds_read_b128 v[216:219], v210 offset:39936
	global_load_lds_dwordx4 v[226:227], off
	v_lshl_add_u64 v[226:227], s[44:45], 0, v[172:173]
	s_mov_b32 m0, s56
	s_nop 0
	global_load_lds_dwordx4 v[226:227], off
	s_waitcnt vmcnt(8)
	s_waitcnt lgkmcnt(0)
	s_barrier
	s_waitcnt lgkmcnt(0)
	v_mfma_f32_16x16x32_f16 v[136:139], v[84:87], v[160:163], v[136:139]
	v_mfma_f32_16x16x32_f16 v[128:131], v[92:95], v[160:163], v[128:131]
	v_mfma_f32_16x16x32_f16 v[124:127], v[84:87], v[186:189], v[124:127]
	v_mfma_f32_16x16x32_f16 v[116:119], v[92:95], v[186:189], v[116:119]
	v_mfma_f32_16x16x32_f16 v[108:111], v[84:87], v[194:197], v[108:111]
	v_mfma_f32_16x16x32_f16 v[96:99], v[92:95], v[194:197], v[96:99]
	v_mfma_f32_16x16x32_f16 v[76:79], v[84:87], v[212:215], v[76:79]
	v_mfma_f32_16x16x32_f16 v[68:71], v[92:95], v[212:215], v[68:71]
	v_mfma_f32_16x16x32_f16 v[136:139], v[88:91], v[164:167], v[136:139]
	v_mfma_f32_16x16x32_f16 v[128:131], v[100:103], v[164:167], v[128:131]
	v_mfma_f32_16x16x32_f16 v[124:127], v[88:91], v[190:193], v[124:127]
	v_mfma_f32_16x16x32_f16 v[116:119], v[100:103], v[190:193], v[116:119]
	v_mfma_f32_16x16x32_f16 v[108:111], v[88:91], v[198:201], v[108:111]
	v_mfma_f32_16x16x32_f16 v[96:99], v[100:103], v[198:201], v[96:99]
	v_mfma_f32_16x16x32_f16 v[76:79], v[88:91], v[216:219], v[76:79]
	v_mfma_f32_16x16x32_f16 v[68:71], v[100:103], v[216:219], v[68:71]
	v_mfma_f32_16x16x32_f16 v[140:143], v[144:147], v[160:163], v[140:143]
	v_mfma_f32_16x16x32_f16 v[132:135], v[152:155], v[160:163], v[132:135]
	v_mfma_f32_16x16x32_f16 v[120:123], v[144:147], v[186:189], v[120:123]
	v_mfma_f32_16x16x32_f16 v[112:115], v[152:155], v[186:189], v[112:115]
	v_mfma_f32_16x16x32_f16 v[104:107], v[144:147], v[194:197], v[104:107]
	v_mfma_f32_16x16x32_f16 v[80:83], v[152:155], v[194:197], v[80:83]
	v_mfma_f32_16x16x32_f16 v[72:75], v[144:147], v[212:215], v[72:75]
	v_mfma_f32_16x16x32_f16 v[64:67], v[152:155], v[212:215], v[64:67]
	v_mfma_f32_16x16x32_f16 v[140:143], v[148:151], v[164:167], v[140:143]
	v_mfma_f32_16x16x32_f16 v[132:135], v[156:159], v[164:167], v[132:135]
	v_mfma_f32_16x16x32_f16 v[120:123], v[148:151], v[190:193], v[120:123]
	v_mfma_f32_16x16x32_f16 v[112:115], v[156:159], v[190:193], v[112:115]
	v_mfma_f32_16x16x32_f16 v[104:107], v[148:151], v[198:201], v[104:107]
	v_mfma_f32_16x16x32_f16 v[80:83], v[156:159], v[198:201], v[80:83]
	v_mfma_f32_16x16x32_f16 v[72:75], v[148:151], v[216:219], v[72:75]
	v_mfma_f32_16x16x32_f16 v[64:67], v[156:159], v[216:219], v[64:67]
	s_barrier
	s_add_i32 s44, s72, s49
	v_lshl_add_u64 v[202:203], v[202:203], 0, s[12:13]
	s_mov_b32 m0, s44
	ds_read_b128 v[160:163], v210 offset:49152
	ds_read_b128 v[164:167], v210 offset:50176
	ds_read_b128 v[186:189], v210 offset:51200
	ds_read_b128 v[190:193], v210 offset:52224
	ds_read_b128 v[194:197], v210 offset:53248
	ds_read_b128 v[198:201], v210 offset:54272
	ds_read_b128 v[212:215], v210 offset:55296
	ds_read_b128 v[216:219], v210 offset:56320
	global_load_lds_dwordx4 v[202:203], off
	s_add_i32 m0, s44, 0x2000
	s_add_u32 s40, s40, 0x40080
	v_lshl_add_u64 v[202:203], v[220:221], 0, s[12:13]
	s_addc_u32 s41, s41, 0
	s_add_i32 s44, s73, s49
	global_load_lds_dwordx4 v[202:203], off
	v_lshl_add_u64 v[202:203], s[40:41], 0, v[170:171]
	s_mov_b32 m0, s44
	s_nop 0
	global_load_lds_dwordx4 v[202:203], off
	v_lshl_add_u64 v[202:203], s[40:41], 0, v[174:175]
	s_add_i32 m0, s44, 0x2000
	s_nop 0
	global_load_lds_dwordx4 v[202:203], off
	v_lshl_add_u64 v[202:203], v[222:223], 0, s[12:13]
	s_mov_b32 m0, s62
	s_nop 0
	global_load_lds_dwordx4 v[202:203], off
	v_lshl_add_u64 v[202:203], v[224:225], 0, s[12:13]
	s_mov_b32 m0, s63
	s_nop 0
	global_load_lds_dwordx4 v[202:203], off
	s_waitcnt vmcnt(8)
	s_waitcnt lgkmcnt(0)
	s_barrier
	s_waitcnt lgkmcnt(0)
	v_mfma_f32_16x16x32_f16 v[60:63], v[84:87], v[160:163], v[60:63]
	v_mfma_f32_16x16x32_f16 v[52:55], v[92:95], v[160:163], v[52:55]
	v_mfma_f32_16x16x32_f16 v[44:47], v[84:87], v[186:189], v[44:47]
	v_mfma_f32_16x16x32_f16 v[36:39], v[92:95], v[186:189], v[36:39]
	v_mfma_f32_16x16x32_f16 v[28:31], v[84:87], v[194:197], v[28:31]
	v_mfma_f32_16x16x32_f16 v[20:23], v[92:95], v[194:197], v[20:23]
	v_mfma_f32_16x16x32_f16 v[12:15], v[84:87], v[212:215], v[12:15]
	v_mfma_f32_16x16x32_f16 v[4:7], v[92:95], v[212:215], v[4:7]
	v_mfma_f32_16x16x32_f16 v[60:63], v[88:91], v[164:167], v[60:63]
	v_mfma_f32_16x16x32_f16 v[52:55], v[100:103], v[164:167], v[52:55]
	v_mfma_f32_16x16x32_f16 v[44:47], v[88:91], v[190:193], v[44:47]
	v_mfma_f32_16x16x32_f16 v[36:39], v[100:103], v[190:193], v[36:39]
	v_mfma_f32_16x16x32_f16 v[28:31], v[88:91], v[198:201], v[28:31]
	v_mfma_f32_16x16x32_f16 v[20:23], v[100:103], v[198:201], v[20:23]
	v_mfma_f32_16x16x32_f16 v[12:15], v[88:91], v[216:219], v[12:15]
	v_mfma_f32_16x16x32_f16 v[4:7], v[100:103], v[216:219], v[4:7]
	v_mfma_f32_16x16x32_f16 v[56:59], v[144:147], v[160:163], v[56:59]
	v_mfma_f32_16x16x32_f16 v[48:51], v[152:155], v[160:163], v[48:51]
	v_mfma_f32_16x16x32_f16 v[40:43], v[144:147], v[186:189], v[40:43]
	v_mfma_f32_16x16x32_f16 v[32:35], v[152:155], v[186:189], v[32:35]
	v_mfma_f32_16x16x32_f16 v[24:27], v[144:147], v[194:197], v[24:27]
	v_mfma_f32_16x16x32_f16 v[16:19], v[152:155], v[194:197], v[16:19]
	v_mfma_f32_16x16x32_f16 v[8:11], v[144:147], v[212:215], v[8:11]
	v_mfma_f32_16x16x32_f16 v[0:3], v[152:155], v[212:215], v[0:3]
	v_mfma_f32_16x16x32_f16 v[56:59], v[148:151], v[164:167], v[56:59]
	v_mfma_f32_16x16x32_f16 v[48:51], v[156:159], v[164:167], v[48:51]
	v_mfma_f32_16x16x32_f16 v[40:43], v[148:151], v[190:193], v[40:43]
	v_mfma_f32_16x16x32_f16 v[32:35], v[156:159], v[190:193], v[32:35]
	v_mfma_f32_16x16x32_f16 v[24:27], v[148:151], v[198:201], v[24:27]
	v_mfma_f32_16x16x32_f16 v[16:19], v[156:159], v[198:201], v[16:19]
	v_mfma_f32_16x16x32_f16 v[8:11], v[148:151], v[216:219], v[8:11]
	v_mfma_f32_16x16x32_f16 v[0:3], v[156:159], v[216:219], v[0:3]
	s_barrier
	s_add_i32 s71, s71, 2
	s_add_u32 s34, s34, 0x100
	s_addc_u32 s35, s35, 0
	s_add_u32 s69, s69, 0x100
	s_addc_u32 s70, s70, 0
	s_cmp_gt_u32 s71, 13

.LBB0_866:
	ds_read_b128 v[104:107], v171
	ds_read_b128 v[108:111], v171 offset:1024
	ds_read_b128 v[112:115], v171 offset:2048
	ds_read_b128 v[116:119], v171 offset:3072
	ds_read_b128 v[160:163], v172
	ds_read_b128 v[164:167], v172 offset:1024
	ds_read_b128 v[178:181], v172 offset:2048
	ds_read_b128 v[182:185], v172 offset:3072
	ds_read_b128 v[186:189], v173
	ds_read_b128 v[190:193], v173 offset:1024
	ds_read_b128 v[194:197], v173 offset:2048
	ds_read_b128 v[198:201], v173 offset:3072
	ds_read_b128 v[206:209], v173 offset:4096
	ds_read_b128 v[210:213], v173 offset:5120
	ds_read_b128 v[214:217], v173 offset:6144
	ds_read_b128 v[218:221], v173 offset:7168
	s_add_i32 s48, s48, 1
	s_mul_i32 s2, s48, s57
	s_mul_hi_u32 s3, s48, s9
	s_add_i32 s3, s3, s2
	s_mul_i32 s2, s48, s9
	s_add_u32 s18, s2, s8
	s_addc_u32 s19, s3, s33
	v_cmp_gt_i64_e32 vcc, s[18:19], v[158:159]
	v_cmp_lt_i64_e64 s[2:3], s[18:19], v[156:157]
	s_cbranch_vccnz .LBB0_872
	s_ashr_i32 s14, s18, 31
	s_lshr_b32 s14, s14, 29
	s_add_i32 s16, s18, s14
	s_and_b32 s14, s16, -8
	s_sub_i32 s17, s18, s14
	s_cmp_gt_i32 s17, 3
	s_mov_b64 s[14:15], -1
	s_cbranch_scc0 .LBB0_869
	s_mul_i32 s14, s17, 0xb5
	s_add_i32 s18, s14, 4
	s_mov_b64 s[14:15], 0

.LBB0_872:
	s_ashr_i32 s17, s16, 31
	s_lshl_b64 s[18:19], s[16:17], 19
	s_add_u32 s18, s42, s18
	s_addc_u32 s19, s43, s19
	s_and_b64 s[20:21], s[2:3], exec
	s_cselect_b32 s17, s19, s25
	s_cselect_b32 s63, s18, s24
	s_ashr_i32 s15, s14, 31
	s_lshl_b64 s[20:21], s[14:15], 19
	s_add_u32 s20, s40, s20
	s_addc_u32 s21, s41, s21
	s_and_b64 s[34:35], s[2:3], exec
	s_cselect_b32 s15, s21, s27
	s_cselect_b32 s64, s20, s26
	s_add_u32 s24, s24, 0x40080
	s_addc_u32 s25, s25, 0
	s_add_u32 s65, s26, 0x100
	s_addc_u32 s66, s27, 0
	s_mov_b32 s67, -2
	s_add_u32 s26, s24, 0xfffc0080
	s_addc_u32 s27, s25, -1
	s_cmp_eq_u32 s67, 12
	s_cselect_b32 s35, s17, s27
	s_cselect_b32 s34, s63, s26
	s_cselect_b32 s27, s15, s66
	s_cselect_b32 s26, s64, s65
	v_lshl_add_u64 v[202:203], s[24:25], 0, v[152:153]
	s_add_i32 m0, s23, 0xc000
	global_load_lds_dwordx4 v[202:203], off
	v_lshl_add_u64 v[202:203], s[24:25], 0, v[154:155]
	s_add_i32 m0, s23, 0xe000
	s_nop 0
	global_load_lds_dwordx4 v[202:203], off
	s_waitcnt vmcnt(8)
	s_waitcnt lgkmcnt(0)
	s_barrier
	s_waitcnt lgkmcnt(0)
	v_mfma_f32_16x16x32_f16 v[140:143], v[104:107], v[186:189], 0
	v_mfma_f32_16x16x32_f16 v[136:139], v[112:115], v[186:189], 0
	v_mfma_f32_16x16x32_f16 v[124:127], v[104:107], v[194:197], 0
	v_mfma_f32_16x16x32_f16 v[120:123], v[112:115], v[194:197], 0
	v_mfma_f32_16x16x32_f16 v[92:95], v[104:107], v[206:209], 0
	v_mfma_f32_16x16x32_f16 v[88:91], v[112:115], v[206:209], 0
	v_mfma_f32_16x16x32_f16 v[76:79], v[104:107], v[214:217], 0
	v_mfma_f32_16x16x32_f16 v[72:75], v[112:115], v[214:217], 0
	v_mfma_f32_16x16x32_f16 v[140:143], v[108:111], v[190:193], v[140:143]
	v_mfma_f32_16x16x32_f16 v[136:139], v[116:119], v[190:193], v[136:139]
	v_mfma_f32_16x16x32_f16 v[124:127], v[108:111], v[198:201], v[124:127]
	v_mfma_f32_16x16x32_f16 v[120:123], v[116:119], v[198:201], v[120:123]
	v_mfma_f32_16x16x32_f16 v[92:95], v[108:111], v[210:213], v[92:95]
	v_mfma_f32_16x16x32_f16 v[88:91], v[116:119], v[210:213], v[88:91]
	v_mfma_f32_16x16x32_f16 v[76:79], v[108:111], v[218:221], v[76:79]
	v_mfma_f32_16x16x32_f16 v[72:75], v[116:119], v[218:221], v[72:75]
	v_mfma_f32_16x16x32_f16 v[132:135], v[160:163], v[186:189], 0
	v_mfma_f32_16x16x32_f16 v[128:131], v[178:181], v[186:189], 0
	v_mfma_f32_16x16x32_f16 v[100:103], v[160:163], v[194:197], 0
	v_mfma_f32_16x16x32_f16 v[96:99], v[178:181], v[194:197], 0
	v_mfma_f32_16x16x32_f16 v[84:87], v[160:163], v[206:209], 0
	v_mfma_f32_16x16x32_f16 v[80:83], v[178:181], v[206:209], 0
	v_mfma_f32_16x16x32_f16 v[68:71], v[160:163], v[214:217], 0
	v_mfma_f32_16x16x32_f16 v[64:67], v[178:181], v[214:217], 0
	v_mfma_f32_16x16x32_f16 v[132:135], v[164:167], v[190:193], v[132:135]
	v_mfma_f32_16x16x32_f16 v[128:131], v[182:185], v[190:193], v[128:131]
	v_mfma_f32_16x16x32_f16 v[100:103], v[164:167], v[198:201], v[100:103]
	v_mfma_f32_16x16x32_f16 v[96:99], v[182:185], v[198:201], v[96:99]
	v_mfma_f32_16x16x32_f16 v[84:87], v[164:167], v[210:213], v[84:87]
	v_mfma_f32_16x16x32_f16 v[80:83], v[182:185], v[210:213], v[80:83]
	v_mfma_f32_16x16x32_f16 v[68:71], v[164:167], v[218:221], v[68:71]
	v_mfma_f32_16x16x32_f16 v[64:67], v[182:185], v[218:221], v[64:67]
	s_barrier
	s_add_i32 s68, s58, s44
	v_lshl_add_u64 v[202:203], s[26:27], 0, v[146:147]
	s_mov_b32 m0, s68
	ds_read_b128 v[186:189], v173 offset:16384
	ds_read_b128 v[190:193], v173 offset:17408
	ds_read_b128 v[194:197], v173 offset:18432
	ds_read_b128 v[198:201], v173 offset:19456
	ds_read_b128 v[206:209], v173 offset:20480
	ds_read_b128 v[210:213], v173 offset:21504
	ds_read_b128 v[214:217], v173 offset:22528
	ds_read_b128 v[218:221], v173 offset:23552
	global_load_lds_dwordx4 v[202:203], off
	s_add_i32 m0, s68, 0x2000
	s_add_u32 s68, s26, 0x40000
	v_lshl_add_u64 v[222:223], s[26:27], 0, v[150:151]
	s_addc_u32 s69, s27, 0
	s_add_i32 s70, s59, s44
	global_load_lds_dwordx4 v[222:223], off
	v_lshl_add_u64 v[224:225], s[68:69], 0, v[146:147]
	s_mov_b32 m0, s70
	v_lshl_add_u64 v[226:227], s[34:35], 0, v[148:149]
	global_load_lds_dwordx4 v[224:225], off
	v_lshl_add_u64 v[224:225], s[68:69], 0, v[150:151]
	s_add_i32 m0, s70, 0x2000
	s_nop 0
	global_load_lds_dwordx4 v[224:225], off
	v_lshl_add_u64 v[224:225], s[34:35], 0, v[144:145]
	s_mov_b32 m0, s23
	s_nop 0
	global_load_lds_dwordx4 v[224:225], off
	s_mov_b32 m0, s45
	s_nop 0
	global_load_lds_dwordx4 v[226:227], off
	s_waitcnt vmcnt(8)
	s_waitcnt lgkmcnt(0)
	s_barrier
	s_waitcnt lgkmcnt(0)
	v_mfma_f32_16x16x32_f16 v[60:63], v[104:107], v[186:189], 0
	v_mfma_f32_16x16x32_f16 v[56:59], v[112:115], v[186:189], 0
	v_mfma_f32_16x16x32_f16 v[44:47], v[104:107], v[194:197], 0
	v_mfma_f32_16x16x32_f16 v[40:43], v[112:115], v[194:197], 0
	v_mfma_f32_16x16x32_f16 v[28:31], v[104:107], v[206:209], 0
	v_mfma_f32_16x16x32_f16 v[24:27], v[112:115], v[206:209], 0
	v_mfma_f32_16x16x32_f16 v[12:15], v[104:107], v[214:217], 0
	v_mfma_f32_16x16x32_f16 v[8:11], v[112:115], v[214:217], 0
	v_mfma_f32_16x16x32_f16 v[60:63], v[108:111], v[190:193], v[60:63]
	v_mfma_f32_16x16x32_f16 v[56:59], v[116:119], v[190:193], v[56:59]
	v_mfma_f32_16x16x32_f16 v[44:47], v[108:111], v[198:201], v[44:47]
	v_mfma_f32_16x16x32_f16 v[40:43], v[116:119], v[198:201], v[40:43]
	v_mfma_f32_16x16x32_f16 v[28:31], v[108:111], v[210:213], v[28:31]
	v_mfma_f32_16x16x32_f16 v[24:27], v[116:119], v[210:213], v[24:27]
	v_mfma_f32_16x16x32_f16 v[12:15], v[108:111], v[218:221], v[12:15]
	v_mfma_f32_16x16x32_f16 v[8:11], v[116:119], v[218:221], v[8:11]
	v_mfma_f32_16x16x32_f16 v[52:55], v[160:163], v[186:189], 0
	v_mfma_f32_16x16x32_f16 v[48:51], v[178:181], v[186:189], 0
	v_mfma_f32_16x16x32_f16 v[36:39], v[160:163], v[194:197], 0
	v_mfma_f32_16x16x32_f16 v[32:35], v[178:181], v[194:197], 0
	v_mfma_f32_16x16x32_f16 v[20:23], v[160:163], v[206:209], 0
	v_mfma_f32_16x16x32_f16 v[16:19], v[178:181], v[206:209], 0
	v_mfma_f32_16x16x32_f16 v[4:7], v[160:163], v[214:217], 0
	v_mfma_f32_16x16x32_f16 v[0:3], v[178:181], v[214:217], 0
	v_mfma_f32_16x16x32_f16 v[52:55], v[164:167], v[190:193], v[52:55]
	v_mfma_f32_16x16x32_f16 v[48:51], v[182:185], v[190:193], v[48:51]
	v_mfma_f32_16x16x32_f16 v[36:39], v[164:167], v[198:201], v[36:39]
	v_mfma_f32_16x16x32_f16 v[32:35], v[182:185], v[198:201], v[32:35]
	v_mfma_f32_16x16x32_f16 v[20:23], v[164:167], v[210:213], v[20:23]
	v_mfma_f32_16x16x32_f16 v[16:19], v[182:185], v[210:213], v[16:19]
	v_mfma_f32_16x16x32_f16 v[4:7], v[164:167], v[218:221], v[4:7]
	v_mfma_f32_16x16x32_f16 v[0:3], v[182:185], v[218:221], v[0:3]
	s_barrier
	s_add_i32 s68, 0, 0x18000
	s_add_i32 s69, 0, 0x1c000
	v_add_u32_e32 v116, s68, v169
	v_add_u32_e32 v177, s69, v169
	ds_read_b128 v[104:107], v116
	ds_read_b128 v[108:111], v116 offset:1024
	ds_read_b128 v[112:115], v116 offset:2048
	ds_read_b128 v[116:119], v116 offset:3072
	ds_read_b128 v[160:163], v177
	ds_read_b128 v[164:167], v177 offset:1024
	ds_read_b128 v[178:181], v177 offset:2048
	ds_read_b128 v[182:185], v177 offset:3072
	s_add_u32 s34, s34, 0x40000
	s_addc_u32 s35, s35, 0
	s_mov_b32 m0, s46
	v_lshl_add_u64 v[228:229], s[34:35], 0, v[144:145]
	ds_read_b128 v[186:189], v173 offset:32768
	ds_read_b128 v[190:193], v173 offset:33792
	ds_read_b128 v[194:197], v173 offset:34816
	ds_read_b128 v[198:201], v173 offset:35840
	ds_read_b128 v[206:209], v173 offset:36864
	ds_read_b128 v[210:213], v173 offset:37888
	ds_read_b128 v[214:217], v173 offset:38912
	ds_read_b128 v[218:221], v173 offset:39936
	global_load_lds_dwordx4 v[228:229], off
	v_lshl_add_u64 v[228:229], s[34:35], 0, v[148:149]
	s_mov_b32 m0, s47
	s_nop 0
	global_load_lds_dwordx4 v[228:229], off
	s_waitcnt vmcnt(8)
	s_waitcnt lgkmcnt(0)
	s_barrier
	s_waitcnt lgkmcnt(0)
	v_mfma_f32_16x16x32_f16 v[140:143], v[104:107], v[186:189], v[140:143]
	v_mfma_f32_16x16x32_f16 v[136:139], v[112:115], v[186:189], v[136:139]
	v_mfma_f32_16x16x32_f16 v[124:127], v[104:107], v[194:197], v[124:127]
	v_mfma_f32_16x16x32_f16 v[120:123], v[112:115], v[194:197], v[120:123]
	v_mfma_f32_16x16x32_f16 v[92:95], v[104:107], v[206:209], v[92:95]
	v_mfma_f32_16x16x32_f16 v[88:91], v[112:115], v[206:209], v[88:91]
	v_mfma_f32_16x16x32_f16 v[76:79], v[104:107], v[214:217], v[76:79]
	v_mfma_f32_16x16x32_f16 v[72:75], v[112:115], v[214:217], v[72:75]
	v_mfma_f32_16x16x32_f16 v[140:143], v[108:111], v[190:193], v[140:143]
	v_mfma_f32_16x16x32_f16 v[136:139], v[116:119], v[190:193], v[136:139]
	v_mfma_f32_16x16x32_f16 v[124:127], v[108:111], v[198:201], v[124:127]
	v_mfma_f32_16x16x32_f16 v[120:123], v[116:119], v[198:201], v[120:123]
	v_mfma_f32_16x16x32_f16 v[92:95], v[108:111], v[210:213], v[92:95]
	v_mfma_f32_16x16x32_f16 v[88:91], v[116:119], v[210:213], v[88:91]
	v_mfma_f32_16x16x32_f16 v[76:79], v[108:111], v[218:221], v[76:79]
	v_mfma_f32_16x16x32_f16 v[72:75], v[116:119], v[218:221], v[72:75]
	v_mfma_f32_16x16x32_f16 v[132:135], v[160:163], v[186:189], v[132:135]
	v_mfma_f32_16x16x32_f16 v[128:131], v[178:181], v[186:189], v[128:131]
	v_mfma_f32_16x16x32_f16 v[100:103], v[160:163], v[194:197], v[100:103]
	v_mfma_f32_16x16x32_f16 v[96:99], v[178:181], v[194:197], v[96:99]
	v_mfma_f32_16x16x32_f16 v[84:87], v[160:163], v[206:209], v[84:87]
	v_mfma_f32_16x16x32_f16 v[80:83], v[178:181], v[206:209], v[80:83]
	v_mfma_f32_16x16x32_f16 v[68:71], v[160:163], v[214:217], v[68:71]
	v_mfma_f32_16x16x32_f16 v[64:67], v[178:181], v[214:217], v[64:67]
	v_mfma_f32_16x16x32_f16 v[132:135], v[164:167], v[190:193], v[132:135]
	v_mfma_f32_16x16x32_f16 v[128:131], v[182:185], v[190:193], v[128:131]
	v_mfma_f32_16x16x32_f16 v[100:103], v[164:167], v[198:201], v[100:103]
	v_mfma_f32_16x16x32_f16 v[96:99], v[182:185], v[198:201], v[96:99]
	v_mfma_f32_16x16x32_f16 v[84:87], v[164:167], v[210:213], v[84:87]
	v_mfma_f32_16x16x32_f16 v[80:83], v[182:185], v[210:213], v[80:83]
	v_mfma_f32_16x16x32_f16 v[68:71], v[164:167], v[218:221], v[68:71]
	v_mfma_f32_16x16x32_f16 v[64:67], v[182:185], v[218:221], v[64:67]
	s_barrier
	s_add_i32 s34, s68, s44
	v_lshl_add_u64 v[202:203], v[202:203], 0, s[10:11]
	s_mov_b32 m0, s34
	ds_read_b128 v[186:189], v173 offset:49152
	ds_read_b128 v[190:193], v173 offset:50176
	ds_read_b128 v[194:197], v173 offset:51200
	ds_read_b128 v[198:201], v173 offset:52224
	ds_read_b128 v[206:209], v173 offset:53248
	ds_read_b128 v[210:213], v173 offset:54272
	ds_read_b128 v[214:217], v173 offset:55296
	ds_read_b128 v[218:221], v173 offset:56320
	global_load_lds_dwordx4 v[202:203], off
	s_add_i32 m0, s34, 0x2000
	s_add_u32 s26, s26, 0x40080
	v_lshl_add_u64 v[202:203], v[222:223], 0, s[10:11]
	s_addc_u32 s27, s27, 0
	s_add_i32 s34, s69, s44
	global_load_lds_dwordx4 v[202:203], off
	v_lshl_add_u64 v[202:203], s[26:27], 0, v[146:147]
	s_mov_b32 m0, s34
	s_nop 0
	global_load_lds_dwordx4 v[202:203], off
	v_lshl_add_u64 v[202:203], s[26:27], 0, v[150:151]
	s_add_i32 m0, s34, 0x2000
	s_nop 0
	global_load_lds_dwordx4 v[202:203], off
	v_lshl_add_u64 v[202:203], v[224:225], 0, s[10:11]
	s_mov_b32 m0, s55
	s_nop 0
	global_load_lds_dwordx4 v[202:203], off
	v_lshl_add_u64 v[202:203], v[226:227], 0, s[10:11]
	s_mov_b32 m0, s56
	s_nop 0
	global_load_lds_dwordx4 v[202:203], off
	s_waitcnt vmcnt(8)
	s_waitcnt lgkmcnt(0)
	s_barrier
	s_waitcnt lgkmcnt(0)
	v_mfma_f32_16x16x32_f16 v[60:63], v[104:107], v[186:189], v[60:63]
	v_mfma_f32_16x16x32_f16 v[56:59], v[112:115], v[186:189], v[56:59]
	v_mfma_f32_16x16x32_f16 v[44:47], v[104:107], v[194:197], v[44:47]
	v_mfma_f32_16x16x32_f16 v[40:43], v[112:115], v[194:197], v[40:43]
	v_mfma_f32_16x16x32_f16 v[28:31], v[104:107], v[206:209], v[28:31]
	v_mfma_f32_16x16x32_f16 v[24:27], v[112:115], v[206:209], v[24:27]
	v_mfma_f32_16x16x32_f16 v[12:15], v[104:107], v[214:217], v[12:15]
	v_mfma_f32_16x16x32_f16 v[8:11], v[112:115], v[214:217], v[8:11]
	v_mfma_f32_16x16x32_f16 v[60:63], v[108:111], v[190:193], v[60:63]
	v_mfma_f32_16x16x32_f16 v[56:59], v[116:119], v[190:193], v[56:59]
	v_mfma_f32_16x16x32_f16 v[44:47], v[108:111], v[198:201], v[44:47]
	v_mfma_f32_16x16x32_f16 v[40:43], v[116:119], v[198:201], v[40:43]
	v_mfma_f32_16x16x32_f16 v[28:31], v[108:111], v[210:213], v[28:31]
	v_mfma_f32_16x16x32_f16 v[24:27], v[116:119], v[210:213], v[24:27]
	v_mfma_f32_16x16x32_f16 v[12:15], v[108:111], v[218:221], v[12:15]
	v_mfma_f32_16x16x32_f16 v[8:11], v[116:119], v[218:221], v[8:11]
	v_mfma_f32_16x16x32_f16 v[52:55], v[160:163], v[186:189], v[52:55]
	v_mfma_f32_16x16x32_f16 v[48:51], v[178:181], v[186:189], v[48:51]
	v_mfma_f32_16x16x32_f16 v[36:39], v[160:163], v[194:197], v[36:39]
	v_mfma_f32_16x16x32_f16 v[32:35], v[178:181], v[194:197], v[32:35]
	v_mfma_f32_16x16x32_f16 v[20:23], v[160:163], v[206:209], v[20:23]
	v_mfma_f32_16x16x32_f16 v[16:19], v[178:181], v[206:209], v[16:19]
	v_mfma_f32_16x16x32_f16 v[4:7], v[160:163], v[214:217], v[4:7]
	v_mfma_f32_16x16x32_f16 v[0:3], v[178:181], v[214:217], v[0:3]
	v_mfma_f32_16x16x32_f16 v[52:55], v[164:167], v[190:193], v[52:55]
	v_mfma_f32_16x16x32_f16 v[48:51], v[182:185], v[190:193], v[48:51]
	v_mfma_f32_16x16x32_f16 v[36:39], v[164:167], v[198:201], v[36:39]
	v_mfma_f32_16x16x32_f16 v[32:35], v[182:185], v[198:201], v[32:35]
	v_mfma_f32_16x16x32_f16 v[20:23], v[164:167], v[210:213], v[20:23]
	v_mfma_f32_16x16x32_f16 v[16:19], v[182:185], v[210:213], v[16:19]
	v_mfma_f32_16x16x32_f16 v[4:7], v[164:167], v[218:221], v[4:7]
	v_mfma_f32_16x16x32_f16 v[0:3], v[182:185], v[218:221], v[0:3]
	s_barrier
	s_add_i32 s67, s67, 2
	s_add_u32 s24, s24, 0x100
	s_addc_u32 s25, s25, 0
	s_add_u32 s65, s65, 0x100
	s_addc_u32 s66, s66, 0
	s_cmp_gt_u32 s67, 13

.LBB0_993:
	s_add_u32 s65, s24, 0x100
	s_addc_u32 s66, s25, 0
	s_mov_b32 s67, -2
	s_waitcnt lgkmcnt(0)
	s_add_u32 s24, s22, 0x100
	s_addc_u32 s25, s23, 0
	s_cmp_eq_u32 s67, 40
	s_cselect_b32 s35, s1, s25
	s_cselect_b32 s34, s0, s24
	s_cselect_b32 s27, s21, s66
	s_cselect_b32 s26, s20, s65
	v_lshl_add_u64 v[202:203], s[22:23], 0, v[168:169]
	s_add_i32 m0, s40, 0xc000
	global_load_lds_dwordx4 v[202:203], off
	v_lshl_add_u64 v[202:203], s[22:23], 0, v[170:171]
	s_add_i32 m0, s40, 0xe000
	s_nop 0
	global_load_lds_dwordx4 v[202:203], off
	s_waitcnt vmcnt(8)
	s_waitcnt lgkmcnt(0)
	s_barrier
	s_waitcnt lgkmcnt(0)
	v_mfma_f32_16x16x32_f16 v[140:143], v[80:83], v[178:181], 0
	v_mfma_f32_16x16x32_f16 v[136:139], v[92:95], v[178:181], 0
	v_mfma_f32_16x16x32_f16 v[124:127], v[80:83], v[186:189], 0
	v_mfma_f32_16x16x32_f16 v[120:123], v[92:95], v[186:189], 0
	v_mfma_f32_16x16x32_f16 v[108:111], v[80:83], v[194:197], 0
	v_mfma_f32_16x16x32_f16 v[104:107], v[92:95], v[194:197], 0
	v_mfma_f32_16x16x32_f16 v[76:79], v[80:83], v[212:215], 0
	v_mfma_f32_16x16x32_f16 v[72:75], v[92:95], v[212:215], 0
	v_mfma_f32_16x16x32_f16 v[140:143], v[84:87], v[182:185], v[140:143]
	v_mfma_f32_16x16x32_f16 v[136:139], v[96:99], v[182:185], v[136:139]
	v_mfma_f32_16x16x32_f16 v[124:127], v[84:87], v[190:193], v[124:127]
	v_mfma_f32_16x16x32_f16 v[120:123], v[96:99], v[190:193], v[120:123]
	v_mfma_f32_16x16x32_f16 v[108:111], v[84:87], v[198:201], v[108:111]
	v_mfma_f32_16x16x32_f16 v[104:107], v[96:99], v[198:201], v[104:107]
	v_mfma_f32_16x16x32_f16 v[76:79], v[84:87], v[216:219], v[76:79]
	v_mfma_f32_16x16x32_f16 v[72:75], v[96:99], v[216:219], v[72:75]
	v_mfma_f32_16x16x32_f16 v[132:135], v[144:147], v[178:181], 0
	v_mfma_f32_16x16x32_f16 v[128:131], v[152:155], v[178:181], 0
	v_mfma_f32_16x16x32_f16 v[116:119], v[144:147], v[186:189], 0
	v_mfma_f32_16x16x32_f16 v[112:115], v[152:155], v[186:189], 0
	v_mfma_f32_16x16x32_f16 v[100:103], v[144:147], v[194:197], 0
	v_mfma_f32_16x16x32_f16 v[88:91], v[152:155], v[194:197], 0
	v_mfma_f32_16x16x32_f16 v[68:71], v[144:147], v[212:215], 0
	v_mfma_f32_16x16x32_f16 v[64:67], v[152:155], v[212:215], 0
	v_mfma_f32_16x16x32_f16 v[132:135], v[148:151], v[182:185], v[132:135]
	v_mfma_f32_16x16x32_f16 v[128:131], v[156:159], v[182:185], v[128:131]
	v_mfma_f32_16x16x32_f16 v[116:119], v[148:151], v[190:193], v[116:119]
	v_mfma_f32_16x16x32_f16 v[112:115], v[156:159], v[190:193], v[112:115]
	v_mfma_f32_16x16x32_f16 v[100:103], v[148:151], v[198:201], v[100:103]
	v_mfma_f32_16x16x32_f16 v[88:91], v[156:159], v[198:201], v[88:91]
	v_mfma_f32_16x16x32_f16 v[68:71], v[148:151], v[216:219], v[68:71]
	v_mfma_f32_16x16x32_f16 v[64:67], v[156:159], v[216:219], v[64:67]
	s_barrier
	s_add_i32 s22, s59, s33
	v_lshl_add_u64 v[202:203], s[26:27], 0, v[162:163]
	s_mov_b32 m0, s22
	ds_read_b128 v[178:181], v210 offset:16384
	ds_read_b128 v[182:185], v210 offset:17408
	ds_read_b128 v[186:189], v210 offset:18432
	ds_read_b128 v[190:193], v210 offset:19456
	ds_read_b128 v[194:197], v210 offset:20480
	ds_read_b128 v[198:201], v210 offset:21504
	ds_read_b128 v[212:215], v210 offset:22528
	ds_read_b128 v[216:219], v210 offset:23552
	global_load_lds_dwordx4 v[202:203], off
	s_add_i32 m0, s22, 0x2000
	s_add_u32 s22, s26, 0xb0000
	v_lshl_add_u64 v[220:221], s[26:27], 0, v[166:167]
	s_addc_u32 s23, s27, 0
	s_add_i32 s68, s60, s33
	global_load_lds_dwordx4 v[220:221], off
	v_lshl_add_u64 v[222:223], s[22:23], 0, v[162:163]
	s_mov_b32 m0, s68
	v_lshl_add_u64 v[224:225], s[34:35], 0, v[164:165]
	global_load_lds_dwordx4 v[222:223], off
	v_lshl_add_u64 v[222:223], s[22:23], 0, v[166:167]
	s_add_i32 m0, s68, 0x2000
	s_nop 0
	global_load_lds_dwordx4 v[222:223], off
	v_lshl_add_u64 v[222:223], s[34:35], 0, v[160:161]
	s_mov_b32 m0, s40
	s_nop 0
	global_load_lds_dwordx4 v[222:223], off
	s_mov_b32 m0, s41
	s_nop 0
	global_load_lds_dwordx4 v[224:225], off
	s_waitcnt vmcnt(8)
	s_waitcnt lgkmcnt(0)
	s_barrier
	s_waitcnt lgkmcnt(0)
	v_mfma_f32_16x16x32_f16 v[60:63], v[80:83], v[178:181], 0
	v_mfma_f32_16x16x32_f16 v[56:59], v[92:95], v[178:181], 0
	v_mfma_f32_16x16x32_f16 v[44:47], v[80:83], v[186:189], 0
	v_mfma_f32_16x16x32_f16 v[40:43], v[92:95], v[186:189], 0
	v_mfma_f32_16x16x32_f16 v[28:31], v[80:83], v[194:197], 0
	v_mfma_f32_16x16x32_f16 v[24:27], v[92:95], v[194:197], 0
	v_mfma_f32_16x16x32_f16 v[12:15], v[80:83], v[212:215], 0
	v_mfma_f32_16x16x32_f16 v[8:11], v[92:95], v[212:215], 0
	v_mfma_f32_16x16x32_f16 v[60:63], v[84:87], v[182:185], v[60:63]
	v_mfma_f32_16x16x32_f16 v[56:59], v[96:99], v[182:185], v[56:59]
	v_mfma_f32_16x16x32_f16 v[44:47], v[84:87], v[190:193], v[44:47]
	v_mfma_f32_16x16x32_f16 v[40:43], v[96:99], v[190:193], v[40:43]
	v_mfma_f32_16x16x32_f16 v[28:31], v[84:87], v[198:201], v[28:31]
	v_mfma_f32_16x16x32_f16 v[24:27], v[96:99], v[198:201], v[24:27]
	v_mfma_f32_16x16x32_f16 v[12:15], v[84:87], v[216:219], v[12:15]
	v_mfma_f32_16x16x32_f16 v[8:11], v[96:99], v[216:219], v[8:11]
	v_mfma_f32_16x16x32_f16 v[52:55], v[144:147], v[178:181], 0
	v_mfma_f32_16x16x32_f16 v[48:51], v[152:155], v[178:181], 0
	v_mfma_f32_16x16x32_f16 v[36:39], v[144:147], v[186:189], 0
	v_mfma_f32_16x16x32_f16 v[32:35], v[152:155], v[186:189], 0
	v_mfma_f32_16x16x32_f16 v[20:23], v[144:147], v[194:197], 0
	v_mfma_f32_16x16x32_f16 v[16:19], v[152:155], v[194:197], 0
	v_mfma_f32_16x16x32_f16 v[4:7], v[144:147], v[212:215], 0
	v_mfma_f32_16x16x32_f16 v[0:3], v[152:155], v[212:215], 0
	v_mfma_f32_16x16x32_f16 v[52:55], v[148:151], v[182:185], v[52:55]
	v_mfma_f32_16x16x32_f16 v[48:51], v[156:159], v[182:185], v[48:51]
	v_mfma_f32_16x16x32_f16 v[36:39], v[148:151], v[190:193], v[36:39]
	v_mfma_f32_16x16x32_f16 v[32:35], v[156:159], v[190:193], v[32:35]
	v_mfma_f32_16x16x32_f16 v[20:23], v[148:151], v[198:201], v[20:23]
	v_mfma_f32_16x16x32_f16 v[16:19], v[156:159], v[198:201], v[16:19]
	v_mfma_f32_16x16x32_f16 v[4:7], v[148:151], v[216:219], v[4:7]
	v_mfma_f32_16x16x32_f16 v[0:3], v[156:159], v[216:219], v[0:3]
	s_barrier
	s_add_i32 s68, 0, 0x18000
	s_add_i32 s69, 0, 0x1c000
	v_add_u32_e32 v96, s68, v206
	v_add_u32_e32 v156, s69, v206
	ds_read_b128 v[80:83], v96
	ds_read_b128 v[84:87], v96 offset:1024
	ds_read_b128 v[92:95], v96 offset:2048
	ds_read_b128 v[96:99], v96 offset:3072
	ds_read_b128 v[144:147], v156
	ds_read_b128 v[148:151], v156 offset:1024
	ds_read_b128 v[152:155], v156 offset:2048
	ds_read_b128 v[156:159], v156 offset:3072
	s_add_u32 s22, s34, 0xb0000
	s_addc_u32 s23, s35, 0
	s_mov_b32 m0, s44
	v_lshl_add_u64 v[226:227], s[22:23], 0, v[160:161]
	ds_read_b128 v[178:181], v210 offset:32768
	ds_read_b128 v[182:185], v210 offset:33792
	ds_read_b128 v[186:189], v210 offset:34816
	ds_read_b128 v[190:193], v210 offset:35840
	ds_read_b128 v[194:197], v210 offset:36864
	ds_read_b128 v[198:201], v210 offset:37888
	ds_read_b128 v[212:215], v210 offset:38912
	ds_read_b128 v[216:219], v210 offset:39936
	global_load_lds_dwordx4 v[226:227], off
	v_lshl_add_u64 v[226:227], s[22:23], 0, v[164:165]
	s_mov_b32 m0, s45
	s_nop 0
	global_load_lds_dwordx4 v[226:227], off
	s_waitcnt vmcnt(8)
	s_waitcnt lgkmcnt(0)
	s_barrier
	s_waitcnt lgkmcnt(0)
	v_mfma_f32_16x16x32_f16 v[140:143], v[80:83], v[178:181], v[140:143]
	v_mfma_f32_16x16x32_f16 v[136:139], v[92:95], v[178:181], v[136:139]
	v_mfma_f32_16x16x32_f16 v[124:127], v[80:83], v[186:189], v[124:127]
	v_mfma_f32_16x16x32_f16 v[120:123], v[92:95], v[186:189], v[120:123]
	v_mfma_f32_16x16x32_f16 v[108:111], v[80:83], v[194:197], v[108:111]
	v_mfma_f32_16x16x32_f16 v[104:107], v[92:95], v[194:197], v[104:107]
	v_mfma_f32_16x16x32_f16 v[76:79], v[80:83], v[212:215], v[76:79]
	v_mfma_f32_16x16x32_f16 v[72:75], v[92:95], v[212:215], v[72:75]
	v_mfma_f32_16x16x32_f16 v[140:143], v[84:87], v[182:185], v[140:143]
	v_mfma_f32_16x16x32_f16 v[136:139], v[96:99], v[182:185], v[136:139]
	v_mfma_f32_16x16x32_f16 v[124:127], v[84:87], v[190:193], v[124:127]
	v_mfma_f32_16x16x32_f16 v[120:123], v[96:99], v[190:193], v[120:123]
	v_mfma_f32_16x16x32_f16 v[108:111], v[84:87], v[198:201], v[108:111]
	v_mfma_f32_16x16x32_f16 v[104:107], v[96:99], v[198:201], v[104:107]
	v_mfma_f32_16x16x32_f16 v[76:79], v[84:87], v[216:219], v[76:79]
	v_mfma_f32_16x16x32_f16 v[72:75], v[96:99], v[216:219], v[72:75]
	v_mfma_f32_16x16x32_f16 v[132:135], v[144:147], v[178:181], v[132:135]
	v_mfma_f32_16x16x32_f16 v[128:131], v[152:155], v[178:181], v[128:131]
	v_mfma_f32_16x16x32_f16 v[116:119], v[144:147], v[186:189], v[116:119]
	v_mfma_f32_16x16x32_f16 v[112:115], v[152:155], v[186:189], v[112:115]
	v_mfma_f32_16x16x32_f16 v[100:103], v[144:147], v[194:197], v[100:103]
	v_mfma_f32_16x16x32_f16 v[88:91], v[152:155], v[194:197], v[88:91]
	v_mfma_f32_16x16x32_f16 v[68:71], v[144:147], v[212:215], v[68:71]
	v_mfma_f32_16x16x32_f16 v[64:67], v[152:155], v[212:215], v[64:67]
	v_mfma_f32_16x16x32_f16 v[132:135], v[148:151], v[182:185], v[132:135]
	v_mfma_f32_16x16x32_f16 v[128:131], v[156:159], v[182:185], v[128:131]
	v_mfma_f32_16x16x32_f16 v[116:119], v[148:151], v[190:193], v[116:119]
	v_mfma_f32_16x16x32_f16 v[112:115], v[156:159], v[190:193], v[112:115]
	v_mfma_f32_16x16x32_f16 v[100:103], v[148:151], v[198:201], v[100:103]
	v_mfma_f32_16x16x32_f16 v[88:91], v[156:159], v[198:201], v[88:91]
	v_mfma_f32_16x16x32_f16 v[68:71], v[148:151], v[216:219], v[68:71]
	v_mfma_f32_16x16x32_f16 v[64:67], v[156:159], v[216:219], v[64:67]
	s_barrier
	s_add_i32 s22, s68, s33
	v_lshl_add_u64 v[202:203], v[202:203], 0, s[16:17]
	s_mov_b32 m0, s22
	ds_read_b128 v[178:181], v210 offset:49152
	ds_read_b128 v[182:185], v210 offset:50176
	ds_read_b128 v[186:189], v210 offset:51200
	ds_read_b128 v[190:193], v210 offset:52224
	ds_read_b128 v[194:197], v210 offset:53248
	ds_read_b128 v[198:201], v210 offset:54272
	ds_read_b128 v[212:215], v210 offset:55296
	ds_read_b128 v[216:219], v210 offset:56320
	global_load_lds_dwordx4 v[202:203], off
	s_add_i32 m0, s22, 0x2000
	s_add_u32 s22, s26, 0xb0080
	v_lshl_add_u64 v[202:203], v[220:221], 0, s[16:17]
	s_addc_u32 s23, s27, 0
	s_add_i32 s26, s69, s33
	global_load_lds_dwordx4 v[202:203], off
	v_lshl_add_u64 v[202:203], s[22:23], 0, v[162:163]
	s_mov_b32 m0, s26
	s_nop 0
	global_load_lds_dwordx4 v[202:203], off
	v_lshl_add_u64 v[202:203], s[22:23], 0, v[166:167]
	s_add_i32 m0, s26, 0x2000
	s_nop 0
	global_load_lds_dwordx4 v[202:203], off
	v_lshl_add_u64 v[202:203], v[222:223], 0, s[16:17]
	s_mov_b32 m0, s55
	s_nop 0
	global_load_lds_dwordx4 v[202:203], off
	v_lshl_add_u64 v[202:203], v[224:225], 0, s[16:17]
	s_mov_b32 m0, s56
	s_nop 0
	global_load_lds_dwordx4 v[202:203], off
	s_waitcnt vmcnt(8)
	s_waitcnt lgkmcnt(0)
	s_barrier
	s_waitcnt lgkmcnt(0)
	v_mfma_f32_16x16x32_f16 v[60:63], v[80:83], v[178:181], v[60:63]
	v_mfma_f32_16x16x32_f16 v[56:59], v[92:95], v[178:181], v[56:59]
	v_mfma_f32_16x16x32_f16 v[44:47], v[80:83], v[186:189], v[44:47]
	v_mfma_f32_16x16x32_f16 v[40:43], v[92:95], v[186:189], v[40:43]
	v_mfma_f32_16x16x32_f16 v[28:31], v[80:83], v[194:197], v[28:31]
	v_mfma_f32_16x16x32_f16 v[24:27], v[92:95], v[194:197], v[24:27]
	v_mfma_f32_16x16x32_f16 v[12:15], v[80:83], v[212:215], v[12:15]
	v_mfma_f32_16x16x32_f16 v[8:11], v[92:95], v[212:215], v[8:11]
	v_mfma_f32_16x16x32_f16 v[60:63], v[84:87], v[182:185], v[60:63]
	v_mfma_f32_16x16x32_f16 v[56:59], v[96:99], v[182:185], v[56:59]
	v_mfma_f32_16x16x32_f16 v[44:47], v[84:87], v[190:193], v[44:47]
	v_mfma_f32_16x16x32_f16 v[40:43], v[96:99], v[190:193], v[40:43]
	v_mfma_f32_16x16x32_f16 v[28:31], v[84:87], v[198:201], v[28:31]
	v_mfma_f32_16x16x32_f16 v[24:27], v[96:99], v[198:201], v[24:27]
	v_mfma_f32_16x16x32_f16 v[12:15], v[84:87], v[216:219], v[12:15]
	v_mfma_f32_16x16x32_f16 v[8:11], v[96:99], v[216:219], v[8:11]
	v_mfma_f32_16x16x32_f16 v[52:55], v[144:147], v[178:181], v[52:55]
	v_mfma_f32_16x16x32_f16 v[48:51], v[152:155], v[178:181], v[48:51]
	v_mfma_f32_16x16x32_f16 v[36:39], v[144:147], v[186:189], v[36:39]
	v_mfma_f32_16x16x32_f16 v[32:35], v[152:155], v[186:189], v[32:35]
	v_mfma_f32_16x16x32_f16 v[20:23], v[144:147], v[194:197], v[20:23]
	v_mfma_f32_16x16x32_f16 v[16:19], v[152:155], v[194:197], v[16:19]
	v_mfma_f32_16x16x32_f16 v[4:7], v[144:147], v[212:215], v[4:7]
	v_mfma_f32_16x16x32_f16 v[0:3], v[152:155], v[212:215], v[0:3]
	v_mfma_f32_16x16x32_f16 v[52:55], v[148:151], v[182:185], v[52:55]
	v_mfma_f32_16x16x32_f16 v[48:51], v[156:159], v[182:185], v[48:51]
	v_mfma_f32_16x16x32_f16 v[36:39], v[148:151], v[190:193], v[36:39]
	v_mfma_f32_16x16x32_f16 v[32:35], v[156:159], v[190:193], v[32:35]
	v_mfma_f32_16x16x32_f16 v[20:23], v[148:151], v[198:201], v[20:23]
	v_mfma_f32_16x16x32_f16 v[16:19], v[156:159], v[198:201], v[16:19]
	v_mfma_f32_16x16x32_f16 v[4:7], v[148:151], v[216:219], v[4:7]
	v_mfma_f32_16x16x32_f16 v[0:3], v[156:159], v[216:219], v[0:3]
	s_barrier
	s_add_i32 s67, s67, 2
	s_add_u32 s65, s65, 0x100
	s_addc_u32 s66, s66, 0
	s_cmp_gt_u32 s67, 41
	s_mov_b64 s[22:23], s[24:25]

.LBB0_1209:
	ds_read_b128 v[80:83], v208
	ds_read_b128 v[84:87], v208 offset:1024
	ds_read_b128 v[92:95], v208 offset:2048
	ds_read_b128 v[96:99], v208 offset:3072
	ds_read_b128 v[144:147], v209
	ds_read_b128 v[148:151], v209 offset:1024
	ds_read_b128 v[152:155], v209 offset:2048
	ds_read_b128 v[156:159], v209 offset:3072
	ds_read_b128 v[178:181], v210
	ds_read_b128 v[182:185], v210 offset:1024
	ds_read_b128 v[186:189], v210 offset:2048
	ds_read_b128 v[190:193], v210 offset:3072
	ds_read_b128 v[194:197], v210 offset:4096
	ds_read_b128 v[198:201], v210 offset:5120
	ds_read_b128 v[212:215], v210 offset:6144
	ds_read_b128 v[216:219], v210 offset:7168
	s_add_i32 s46, s46, 1
	s_mul_i32 s0, s46, s53
	s_mul_hi_u32 s1, s46, s9
	s_add_i32 s1, s1, s0
	s_mul_i32 s0, s46, s9
	s_add_u32 s4, s0, s8
	s_addc_u32 s5, s1, s54
	v_cmp_gt_i64_e32 vcc, s[4:5], v[174:175]
	v_cmp_lt_i64_e64 s[0:1], s[4:5], v[172:173]
	s_cbranch_vccnz .LBB0_1215
	s_ashr_i32 s5, s4, 31
	s_lshr_b32 s5, s5, 29
	s_add_i32 s20, s4, s5
	s_and_b32 s5, s20, -8
	s_sub_i32 s21, s4, s5
	s_cmp_gt_i32 s21, -1
	s_mov_b64 s[4:5], -1
	s_cbranch_scc0 .LBB0_1212
	s_lshl_b32 s26, s21, 5
	s_mov_b64 s[4:5], 0

.LBB0_1219:
	s_add_u32 s61, s24, 0x100
	s_addc_u32 s62, s25, 0
	s_mov_b32 s63, -2
	s_waitcnt lgkmcnt(0)
	s_add_u32 s24, s22, 0x100
	s_addc_u32 s25, s23, 0
	s_cmp_eq_u32 s63, 40
	s_cselect_b32 s35, s1, s25
	s_cselect_b32 s34, s0, s24
	s_cselect_b32 s27, s21, s62
	s_cselect_b32 s26, s20, s61
	v_lshl_add_u64 v[202:203], s[22:23], 0, v[168:169]
	s_add_i32 m0, s40, 0xc000
	global_load_lds_dwordx4 v[202:203], off
	v_lshl_add_u64 v[202:203], s[22:23], 0, v[170:171]
	s_add_i32 m0, s40, 0xe000
	s_nop 0
	global_load_lds_dwordx4 v[202:203], off
	s_waitcnt vmcnt(8)
	s_waitcnt lgkmcnt(0)
	s_barrier
	s_waitcnt lgkmcnt(0)
	v_mfma_f32_16x16x32_f16 v[140:143], v[80:83], v[178:181], 0
	v_mfma_f32_16x16x32_f16 v[136:139], v[92:95], v[178:181], 0
	v_mfma_f32_16x16x32_f16 v[124:127], v[80:83], v[186:189], 0
	v_mfma_f32_16x16x32_f16 v[120:123], v[92:95], v[186:189], 0
	v_mfma_f32_16x16x32_f16 v[108:111], v[80:83], v[194:197], 0
	v_mfma_f32_16x16x32_f16 v[104:107], v[92:95], v[194:197], 0
	v_mfma_f32_16x16x32_f16 v[76:79], v[80:83], v[212:215], 0
	v_mfma_f32_16x16x32_f16 v[72:75], v[92:95], v[212:215], 0
	v_mfma_f32_16x16x32_f16 v[140:143], v[84:87], v[182:185], v[140:143]
	v_mfma_f32_16x16x32_f16 v[136:139], v[96:99], v[182:185], v[136:139]
	v_mfma_f32_16x16x32_f16 v[124:127], v[84:87], v[190:193], v[124:127]
	v_mfma_f32_16x16x32_f16 v[120:123], v[96:99], v[190:193], v[120:123]
	v_mfma_f32_16x16x32_f16 v[108:111], v[84:87], v[198:201], v[108:111]
	v_mfma_f32_16x16x32_f16 v[104:107], v[96:99], v[198:201], v[104:107]
	v_mfma_f32_16x16x32_f16 v[76:79], v[84:87], v[216:219], v[76:79]
	v_mfma_f32_16x16x32_f16 v[72:75], v[96:99], v[216:219], v[72:75]
	v_mfma_f32_16x16x32_f16 v[132:135], v[144:147], v[178:181], 0
	v_mfma_f32_16x16x32_f16 v[128:131], v[152:155], v[178:181], 0
	v_mfma_f32_16x16x32_f16 v[116:119], v[144:147], v[186:189], 0
	v_mfma_f32_16x16x32_f16 v[112:115], v[152:155], v[186:189], 0
	v_mfma_f32_16x16x32_f16 v[100:103], v[144:147], v[194:197], 0
	v_mfma_f32_16x16x32_f16 v[88:91], v[152:155], v[194:197], 0
	v_mfma_f32_16x16x32_f16 v[68:71], v[144:147], v[212:215], 0
	v_mfma_f32_16x16x32_f16 v[64:67], v[152:155], v[212:215], 0
	v_mfma_f32_16x16x32_f16 v[132:135], v[148:151], v[182:185], v[132:135]
	v_mfma_f32_16x16x32_f16 v[128:131], v[156:159], v[182:185], v[128:131]
	v_mfma_f32_16x16x32_f16 v[116:119], v[148:151], v[190:193], v[116:119]
	v_mfma_f32_16x16x32_f16 v[112:115], v[156:159], v[190:193], v[112:115]
	v_mfma_f32_16x16x32_f16 v[100:103], v[148:151], v[198:201], v[100:103]
	v_mfma_f32_16x16x32_f16 v[88:91], v[156:159], v[198:201], v[88:91]
	v_mfma_f32_16x16x32_f16 v[68:71], v[148:151], v[216:219], v[68:71]
	v_mfma_f32_16x16x32_f16 v[64:67], v[156:159], v[216:219], v[64:67]
	s_barrier
	s_add_i32 s22, s55, s33
	v_lshl_add_u64 v[202:203], s[26:27], 0, v[162:163]
	s_mov_b32 m0, s22
	ds_read_b128 v[178:181], v210 offset:16384
	ds_read_b128 v[182:185], v210 offset:17408
	ds_read_b128 v[186:189], v210 offset:18432
	ds_read_b128 v[190:193], v210 offset:19456
	ds_read_b128 v[194:197], v210 offset:20480
	ds_read_b128 v[198:201], v210 offset:21504
	ds_read_b128 v[212:215], v210 offset:22528
	ds_read_b128 v[216:219], v210 offset:23552
	global_load_lds_dwordx4 v[202:203], off
	s_add_i32 m0, s22, 0x2000
	s_add_u32 s22, s26, 0xb0000
	v_lshl_add_u64 v[220:221], s[26:27], 0, v[166:167]
	s_addc_u32 s23, s27, 0
	s_add_i32 s64, s56, s33
	global_load_lds_dwordx4 v[220:221], off
	v_lshl_add_u64 v[222:223], s[22:23], 0, v[162:163]
	s_mov_b32 m0, s64
	v_lshl_add_u64 v[224:225], s[34:35], 0, v[164:165]
	global_load_lds_dwordx4 v[222:223], off
	v_lshl_add_u64 v[222:223], s[22:23], 0, v[166:167]
	s_add_i32 m0, s64, 0x2000
	s_nop 0
	global_load_lds_dwordx4 v[222:223], off
	v_lshl_add_u64 v[222:223], s[34:35], 0, v[160:161]
	s_mov_b32 m0, s40
	s_nop 0
	global_load_lds_dwordx4 v[222:223], off
	s_mov_b32 m0, s41
	s_nop 0
	global_load_lds_dwordx4 v[224:225], off
	s_waitcnt vmcnt(8)
	s_waitcnt lgkmcnt(0)
	s_barrier
	s_waitcnt lgkmcnt(0)
	v_mfma_f32_16x16x32_f16 v[60:63], v[80:83], v[178:181], 0
	v_mfma_f32_16x16x32_f16 v[56:59], v[92:95], v[178:181], 0
	v_mfma_f32_16x16x32_f16 v[44:47], v[80:83], v[186:189], 0
	v_mfma_f32_16x16x32_f16 v[40:43], v[92:95], v[186:189], 0
	v_mfma_f32_16x16x32_f16 v[28:31], v[80:83], v[194:197], 0
	v_mfma_f32_16x16x32_f16 v[24:27], v[92:95], v[194:197], 0
	v_mfma_f32_16x16x32_f16 v[12:15], v[80:83], v[212:215], 0
	v_mfma_f32_16x16x32_f16 v[8:11], v[92:95], v[212:215], 0
	v_mfma_f32_16x16x32_f16 v[60:63], v[84:87], v[182:185], v[60:63]
	v_mfma_f32_16x16x32_f16 v[56:59], v[96:99], v[182:185], v[56:59]
	v_mfma_f32_16x16x32_f16 v[44:47], v[84:87], v[190:193], v[44:47]
	v_mfma_f32_16x16x32_f16 v[40:43], v[96:99], v[190:193], v[40:43]
	v_mfma_f32_16x16x32_f16 v[28:31], v[84:87], v[198:201], v[28:31]
	v_mfma_f32_16x16x32_f16 v[24:27], v[96:99], v[198:201], v[24:27]
	v_mfma_f32_16x16x32_f16 v[12:15], v[84:87], v[216:219], v[12:15]
	v_mfma_f32_16x16x32_f16 v[8:11], v[96:99], v[216:219], v[8:11]
	v_mfma_f32_16x16x32_f16 v[52:55], v[144:147], v[178:181], 0
	v_mfma_f32_16x16x32_f16 v[48:51], v[152:155], v[178:181], 0
	v_mfma_f32_16x16x32_f16 v[36:39], v[144:147], v[186:189], 0
	v_mfma_f32_16x16x32_f16 v[32:35], v[152:155], v[186:189], 0
	v_mfma_f32_16x16x32_f16 v[20:23], v[144:147], v[194:197], 0
	v_mfma_f32_16x16x32_f16 v[16:19], v[152:155], v[194:197], 0
	v_mfma_f32_16x16x32_f16 v[4:7], v[144:147], v[212:215], 0
	v_mfma_f32_16x16x32_f16 v[0:3], v[152:155], v[212:215], 0
	v_mfma_f32_16x16x32_f16 v[52:55], v[148:151], v[182:185], v[52:55]
	v_mfma_f32_16x16x32_f16 v[48:51], v[156:159], v[182:185], v[48:51]
	v_mfma_f32_16x16x32_f16 v[36:39], v[148:151], v[190:193], v[36:39]
	v_mfma_f32_16x16x32_f16 v[32:35], v[156:159], v[190:193], v[32:35]
	v_mfma_f32_16x16x32_f16 v[20:23], v[148:151], v[198:201], v[20:23]
	v_mfma_f32_16x16x32_f16 v[16:19], v[156:159], v[198:201], v[16:19]
	v_mfma_f32_16x16x32_f16 v[4:7], v[148:151], v[216:219], v[4:7]
	v_mfma_f32_16x16x32_f16 v[0:3], v[156:159], v[216:219], v[0:3]
	s_barrier
	s_add_i32 s64, 0, 0x18000
	s_add_i32 s65, 0, 0x1c000
	v_add_u32_e32 v96, s64, v206
	v_add_u32_e32 v156, s65, v206
	ds_read_b128 v[80:83], v96
	ds_read_b128 v[84:87], v96 offset:1024
	ds_read_b128 v[92:95], v96 offset:2048
	ds_read_b128 v[96:99], v96 offset:3072
	ds_read_b128 v[144:147], v156
	ds_read_b128 v[148:151], v156 offset:1024
	ds_read_b128 v[152:155], v156 offset:2048
	ds_read_b128 v[156:159], v156 offset:3072
	s_add_u32 s22, s34, 0xb0000
	s_addc_u32 s23, s35, 0
	s_mov_b32 m0, s44
	v_lshl_add_u64 v[226:227], s[22:23], 0, v[160:161]
	ds_read_b128 v[178:181], v210 offset:32768
	ds_read_b128 v[182:185], v210 offset:33792
	ds_read_b128 v[186:189], v210 offset:34816
	ds_read_b128 v[190:193], v210 offset:35840
	ds_read_b128 v[194:197], v210 offset:36864
	ds_read_b128 v[198:201], v210 offset:37888
	ds_read_b128 v[212:215], v210 offset:38912
	ds_read_b128 v[216:219], v210 offset:39936
	global_load_lds_dwordx4 v[226:227], off
	v_lshl_add_u64 v[226:227], s[22:23], 0, v[164:165]
	s_mov_b32 m0, s45
	s_nop 0
	global_load_lds_dwordx4 v[226:227], off
	s_waitcnt vmcnt(8)
	s_waitcnt lgkmcnt(0)
	s_barrier
	s_waitcnt lgkmcnt(0)
	v_mfma_f32_16x16x32_f16 v[140:143], v[80:83], v[178:181], v[140:143]
	v_mfma_f32_16x16x32_f16 v[136:139], v[92:95], v[178:181], v[136:139]
	v_mfma_f32_16x16x32_f16 v[124:127], v[80:83], v[186:189], v[124:127]
	v_mfma_f32_16x16x32_f16 v[120:123], v[92:95], v[186:189], v[120:123]
	v_mfma_f32_16x16x32_f16 v[108:111], v[80:83], v[194:197], v[108:111]
	v_mfma_f32_16x16x32_f16 v[104:107], v[92:95], v[194:197], v[104:107]
	v_mfma_f32_16x16x32_f16 v[76:79], v[80:83], v[212:215], v[76:79]
	v_mfma_f32_16x16x32_f16 v[72:75], v[92:95], v[212:215], v[72:75]
	v_mfma_f32_16x16x32_f16 v[140:143], v[84:87], v[182:185], v[140:143]
	v_mfma_f32_16x16x32_f16 v[136:139], v[96:99], v[182:185], v[136:139]
	v_mfma_f32_16x16x32_f16 v[124:127], v[84:87], v[190:193], v[124:127]
	v_mfma_f32_16x16x32_f16 v[120:123], v[96:99], v[190:193], v[120:123]
	v_mfma_f32_16x16x32_f16 v[108:111], v[84:87], v[198:201], v[108:111]
	v_mfma_f32_16x16x32_f16 v[104:107], v[96:99], v[198:201], v[104:107]
	v_mfma_f32_16x16x32_f16 v[76:79], v[84:87], v[216:219], v[76:79]
	v_mfma_f32_16x16x32_f16 v[72:75], v[96:99], v[216:219], v[72:75]
	v_mfma_f32_16x16x32_f16 v[132:135], v[144:147], v[178:181], v[132:135]
	v_mfma_f32_16x16x32_f16 v[128:131], v[152:155], v[178:181], v[128:131]
	v_mfma_f32_16x16x32_f16 v[116:119], v[144:147], v[186:189], v[116:119]
	v_mfma_f32_16x16x32_f16 v[112:115], v[152:155], v[186:189], v[112:115]
	v_mfma_f32_16x16x32_f16 v[100:103], v[144:147], v[194:197], v[100:103]
	v_mfma_f32_16x16x32_f16 v[88:91], v[152:155], v[194:197], v[88:91]
	v_mfma_f32_16x16x32_f16 v[68:71], v[144:147], v[212:215], v[68:71]
	v_mfma_f32_16x16x32_f16 v[64:67], v[152:155], v[212:215], v[64:67]
	v_mfma_f32_16x16x32_f16 v[132:135], v[148:151], v[182:185], v[132:135]
	v_mfma_f32_16x16x32_f16 v[128:131], v[156:159], v[182:185], v[128:131]
	v_mfma_f32_16x16x32_f16 v[116:119], v[148:151], v[190:193], v[116:119]
	v_mfma_f32_16x16x32_f16 v[112:115], v[156:159], v[190:193], v[112:115]
	v_mfma_f32_16x16x32_f16 v[100:103], v[148:151], v[198:201], v[100:103]
	v_mfma_f32_16x16x32_f16 v[88:91], v[156:159], v[198:201], v[88:91]
	v_mfma_f32_16x16x32_f16 v[68:71], v[148:151], v[216:219], v[68:71]
	v_mfma_f32_16x16x32_f16 v[64:67], v[156:159], v[216:219], v[64:67]
	s_barrier
	s_add_i32 s22, s64, s33
	v_lshl_add_u64 v[202:203], v[202:203], 0, s[16:17]
	s_mov_b32 m0, s22
	ds_read_b128 v[178:181], v210 offset:49152
	ds_read_b128 v[182:185], v210 offset:50176
	ds_read_b128 v[186:189], v210 offset:51200
	ds_read_b128 v[190:193], v210 offset:52224
	ds_read_b128 v[194:197], v210 offset:53248
	ds_read_b128 v[198:201], v210 offset:54272
	ds_read_b128 v[212:215], v210 offset:55296
	ds_read_b128 v[216:219], v210 offset:56320
	global_load_lds_dwordx4 v[202:203], off
	s_add_i32 m0, s22, 0x2000
	s_add_u32 s22, s26, 0xb0080
	v_lshl_add_u64 v[202:203], v[220:221], 0, s[16:17]
	s_addc_u32 s23, s27, 0
	s_add_i32 s26, s65, s33
	global_load_lds_dwordx4 v[202:203], off
	v_lshl_add_u64 v[202:203], s[22:23], 0, v[162:163]
	s_mov_b32 m0, s26
	s_nop 0
	global_load_lds_dwordx4 v[202:203], off
	v_lshl_add_u64 v[202:203], s[22:23], 0, v[166:167]
	s_add_i32 m0, s26, 0x2000
	s_nop 0
	global_load_lds_dwordx4 v[202:203], off
	v_lshl_add_u64 v[202:203], v[222:223], 0, s[16:17]
	s_mov_b32 m0, s51
	s_nop 0
	global_load_lds_dwordx4 v[202:203], off
	v_lshl_add_u64 v[202:203], v[224:225], 0, s[16:17]
	s_mov_b32 m0, s52
	s_nop 0
	global_load_lds_dwordx4 v[202:203], off
	s_waitcnt vmcnt(8)
	s_waitcnt lgkmcnt(0)
	s_barrier
	s_waitcnt lgkmcnt(0)
	v_mfma_f32_16x16x32_f16 v[60:63], v[80:83], v[178:181], v[60:63]
	v_mfma_f32_16x16x32_f16 v[56:59], v[92:95], v[178:181], v[56:59]
	v_mfma_f32_16x16x32_f16 v[44:47], v[80:83], v[186:189], v[44:47]
	v_mfma_f32_16x16x32_f16 v[40:43], v[92:95], v[186:189], v[40:43]
	v_mfma_f32_16x16x32_f16 v[28:31], v[80:83], v[194:197], v[28:31]
	v_mfma_f32_16x16x32_f16 v[24:27], v[92:95], v[194:197], v[24:27]
	v_mfma_f32_16x16x32_f16 v[12:15], v[80:83], v[212:215], v[12:15]
	v_mfma_f32_16x16x32_f16 v[8:11], v[92:95], v[212:215], v[8:11]
	v_mfma_f32_16x16x32_f16 v[60:63], v[84:87], v[182:185], v[60:63]
	v_mfma_f32_16x16x32_f16 v[56:59], v[96:99], v[182:185], v[56:59]
	v_mfma_f32_16x16x32_f16 v[44:47], v[84:87], v[190:193], v[44:47]
	v_mfma_f32_16x16x32_f16 v[40:43], v[96:99], v[190:193], v[40:43]
	v_mfma_f32_16x16x32_f16 v[28:31], v[84:87], v[198:201], v[28:31]
	v_mfma_f32_16x16x32_f16 v[24:27], v[96:99], v[198:201], v[24:27]
	v_mfma_f32_16x16x32_f16 v[12:15], v[84:87], v[216:219], v[12:15]
	v_mfma_f32_16x16x32_f16 v[8:11], v[96:99], v[216:219], v[8:11]
	v_mfma_f32_16x16x32_f16 v[52:55], v[144:147], v[178:181], v[52:55]
	v_mfma_f32_16x16x32_f16 v[48:51], v[152:155], v[178:181], v[48:51]
	v_mfma_f32_16x16x32_f16 v[36:39], v[144:147], v[186:189], v[36:39]
	v_mfma_f32_16x16x32_f16 v[32:35], v[152:155], v[186:189], v[32:35]
	v_mfma_f32_16x16x32_f16 v[20:23], v[144:147], v[194:197], v[20:23]
	v_mfma_f32_16x16x32_f16 v[16:19], v[152:155], v[194:197], v[16:19]
	v_mfma_f32_16x16x32_f16 v[4:7], v[144:147], v[212:215], v[4:7]
	v_mfma_f32_16x16x32_f16 v[0:3], v[152:155], v[212:215], v[0:3]
	v_mfma_f32_16x16x32_f16 v[52:55], v[148:151], v[182:185], v[52:55]
	v_mfma_f32_16x16x32_f16 v[48:51], v[156:159], v[182:185], v[48:51]
	v_mfma_f32_16x16x32_f16 v[36:39], v[148:151], v[190:193], v[36:39]
	v_mfma_f32_16x16x32_f16 v[32:35], v[156:159], v[190:193], v[32:35]
	v_mfma_f32_16x16x32_f16 v[20:23], v[148:151], v[198:201], v[20:23]
	v_mfma_f32_16x16x32_f16 v[16:19], v[156:159], v[198:201], v[16:19]
	v_mfma_f32_16x16x32_f16 v[4:7], v[148:151], v[216:219], v[4:7]
	v_mfma_f32_16x16x32_f16 v[0:3], v[156:159], v[216:219], v[0:3]
	s_barrier
	s_add_i32 s63, s63, 2
	s_add_u32 s61, s61, 0x100
	s_addc_u32 s62, s62, 0
	s_cmp_gt_u32 s63, 41
	s_mov_b64 s[22:23], s[24:25]

.LBB0_1330:
	ds_read_b128 v[128:131], v167
	ds_read_b128 v[132:135], v167 offset:1024
	ds_read_b128 v[136:139], v167 offset:2048
	ds_read_b128 v[140:143], v167 offset:3072
	ds_read_b128 v[160:163], v168
	ds_read_b128 v[172:175], v168 offset:1024
	ds_read_b128 v[178:181], v168 offset:2048
	ds_read_b128 v[182:185], v168 offset:3072
	ds_read_b128 v[186:189], v169
	ds_read_b128 v[190:193], v169 offset:1024
	ds_read_b128 v[194:197], v169 offset:2048
	ds_read_b128 v[198:201], v169 offset:3072
	ds_read_b128 v[206:209], v169 offset:4096
	ds_read_b128 v[210:213], v169 offset:5120
	ds_read_b128 v[214:217], v169 offset:6144
	ds_read_b128 v[218:221], v169 offset:7168
	s_add_i32 s58, s58, 1
	s_mul_i32 s2, s58, s63
	s_mul_hi_u32 s3, s58, s9
	s_add_i32 s3, s3, s2
	s_mul_i32 s2, s58, s9
	s_add_u32 s40, s2, s8
	s_addc_u32 s41, s3, s52
	v_cmp_gt_i64_e32 vcc, s[40:41], v[158:159]
	v_cmp_lt_i64_e64 s[2:3], s[40:41], v[156:157]
	s_cbranch_vccnz .LBB0_1332
	s_ashr_i32 s26, s40, 31
	s_lshr_b32 s26, s26, 29
	s_add_i32 s26, s40, s26
	s_ashr_i32 s27, s26, 3
	s_and_b32 s26, s26, -8
	s_sub_i32 s26, s40, s26
	s_cmp_lt_i32 s26, 0
	s_cselect_b32 s34, s53, 0x60
	s_mul_i32 s26, s26, s34
	s_add_i32 s26, s26, s27
	s_mul_hi_i32 s27, s26, 0x2aaaaaab
	s_lshr_b32 s34, s27, 31
	s_ashr_i32 s27, s27, 4
	s_add_i32 s27, s27, s34
	s_lshl_b32 s34, s27, 3
	s_sub_i32 s35, 64, s34
	s_min_i32 s35, s35, 8
	s_abs_i32 s40, s35
	v_cvt_f32_u32_e32 v0, s40
	s_sub_i32 s44, 0, s40
	s_mulk_i32 s27, 0x60
	s_sub_i32 s27, s26, s27
	v_rcp_iflag_f32_e32 v0, v0
	s_abs_i32 s26, s27
	s_xor_b32 s41, s27, s35
	s_ashr_i32 s41, s41, 31
	v_mul_f32_e32 v0, 0x4f7ffffe, v0
	v_cvt_u32_f32_e32 v0, v0
	s_nop 0
	v_readfirstlane_b32 s45, v0
	s_mul_i32 s44, s44, s45
	s_mul_hi_u32 s44, s45, s44
	s_add_i32 s45, s45, s44
	s_mul_hi_u32 s44, s26, s45
	s_mul_i32 s45, s44, s40
	s_sub_i32 s26, s26, s45
	s_add_i32 s50, s44, 1
	s_sub_i32 s45, s26, s40
	s_cmp_ge_u32 s26, s40
	s_cselect_b32 s44, s50, s44
	s_cselect_b32 s26, s45, s26
	s_add_i32 s45, s44, 1
	s_cmp_ge_u32 s26, s40
	s_cselect_b32 s26, s45, s44
	s_xor_b32 s26, s26, s41
	s_sub_i32 s26, s26, s41
	s_mul_i32 s35, s26, s35
	s_sub_i32 s27, s27, s35
	s_add_i32 s34, s34, s27
.LBB0_1332:
	s_ashr_i32 s35, s34, 31
	s_lshl_b64 s[40:41], s[34:35], 19
	s_add_u32 s40, s42, s40
	s_addc_u32 s41, s43, s41
	s_and_b64 s[44:45], s[2:3], exec
	s_cselect_b32 s35, s41, s47
	s_cselect_b32 s72, s40, s46
	s_ashr_i32 s27, s26, 31
	s_lshl_b64 s[44:45], s[26:27], 19
	s_add_u32 s44, s22, s44
	s_addc_u32 s45, s23, s45
	s_and_b64 s[50:51], s[2:3], exec
	s_cselect_b32 s27, s45, s49
	s_cselect_b32 s73, s44, s48
	s_add_u32 s46, s46, 0x40080
	s_addc_u32 s47, s47, 0
	s_add_u32 s74, s48, 0x100
	s_addc_u32 s75, s49, 0
	s_mov_b32 s76, -2
	s_add_u32 s48, s46, 0xfffc0080
	s_addc_u32 s49, s47, -1
	s_cmp_eq_u32 s76, 12
	s_cselect_b32 s51, s35, s49
	s_cselect_b32 s50, s72, s48
	s_cselect_b32 s49, s27, s75
	s_cselect_b32 s48, s73, s74
	v_lshl_add_u64 v[202:203], s[46:47], 0, v[152:153]
	s_add_i32 m0, s54, 0xc000
	global_load_lds_dwordx4 v[202:203], off
	v_lshl_add_u64 v[202:203], s[46:47], 0, v[154:155]
	s_add_i32 m0, s54, 0xe000
	s_nop 0
	global_load_lds_dwordx4 v[202:203], off
	s_waitcnt vmcnt(8)
	s_waitcnt lgkmcnt(0)
	s_barrier
	s_waitcnt lgkmcnt(0)
	v_mfma_f32_16x16x32_f16 v[124:127], v[128:131], v[186:189], 0
	v_mfma_f32_16x16x32_f16 v[120:123], v[136:139], v[186:189], 0
	v_mfma_f32_16x16x32_f16 v[108:111], v[128:131], v[194:197], 0
	v_mfma_f32_16x16x32_f16 v[104:107], v[136:139], v[194:197], 0
	v_mfma_f32_16x16x32_f16 v[92:95], v[128:131], v[206:209], 0
	v_mfma_f32_16x16x32_f16 v[88:91], v[136:139], v[206:209], 0
	v_mfma_f32_16x16x32_f16 v[84:87], v[128:131], v[214:217], 0
	v_mfma_f32_16x16x32_f16 v[76:79], v[136:139], v[214:217], 0
	v_mfma_f32_16x16x32_f16 v[124:127], v[132:135], v[190:193], v[124:127]
	v_mfma_f32_16x16x32_f16 v[120:123], v[140:143], v[190:193], v[120:123]
	v_mfma_f32_16x16x32_f16 v[108:111], v[132:135], v[198:201], v[108:111]
	v_mfma_f32_16x16x32_f16 v[104:107], v[140:143], v[198:201], v[104:107]
	v_mfma_f32_16x16x32_f16 v[92:95], v[132:135], v[210:213], v[92:95]
	v_mfma_f32_16x16x32_f16 v[88:91], v[140:143], v[210:213], v[88:91]
	v_mfma_f32_16x16x32_f16 v[84:87], v[132:135], v[218:221], v[84:87]
	v_mfma_f32_16x16x32_f16 v[76:79], v[140:143], v[218:221], v[76:79]
	v_mfma_f32_16x16x32_f16 v[116:119], v[160:163], v[186:189], 0
	v_mfma_f32_16x16x32_f16 v[112:115], v[178:181], v[186:189], 0
	v_mfma_f32_16x16x32_f16 v[100:103], v[160:163], v[194:197], 0
	v_mfma_f32_16x16x32_f16 v[96:99], v[178:181], v[194:197], 0
	v_mfma_f32_16x16x32_f16 v[80:83], v[160:163], v[206:209], 0
	v_mfma_f32_16x16x32_f16 v[72:75], v[178:181], v[206:209], 0
	v_mfma_f32_16x16x32_f16 v[68:71], v[160:163], v[214:217], 0
	v_mfma_f32_16x16x32_f16 v[64:67], v[178:181], v[214:217], 0
	v_mfma_f32_16x16x32_f16 v[116:119], v[172:175], v[190:193], v[116:119]
	v_mfma_f32_16x16x32_f16 v[112:115], v[182:185], v[190:193], v[112:115]
	v_mfma_f32_16x16x32_f16 v[100:103], v[172:175], v[198:201], v[100:103]
	v_mfma_f32_16x16x32_f16 v[96:99], v[182:185], v[198:201], v[96:99]
	v_mfma_f32_16x16x32_f16 v[80:83], v[172:175], v[210:213], v[80:83]
	v_mfma_f32_16x16x32_f16 v[72:75], v[182:185], v[210:213], v[72:75]
	v_mfma_f32_16x16x32_f16 v[68:71], v[172:175], v[218:221], v[68:71]
	v_mfma_f32_16x16x32_f16 v[64:67], v[182:185], v[218:221], v[64:67]
	s_barrier
	s_add_i32 s77, s64, s33
	v_lshl_add_u64 v[202:203], s[48:49], 0, v[148:149]
	s_mov_b32 m0, s77
	ds_read_b128 v[186:189], v169 offset:16384
	ds_read_b128 v[190:193], v169 offset:17408
	ds_read_b128 v[194:197], v169 offset:18432
	ds_read_b128 v[198:201], v169 offset:19456
	ds_read_b128 v[206:209], v169 offset:20480
	ds_read_b128 v[210:213], v169 offset:21504
	ds_read_b128 v[214:217], v169 offset:22528
	ds_read_b128 v[218:221], v169 offset:23552
	global_load_lds_dwordx4 v[202:203], off
	s_add_i32 m0, s77, 0x2000
	s_add_u32 s78, s48, 0x40000
	v_lshl_add_u64 v[222:223], s[48:49], 0, v[144:145]
	s_addc_u32 s79, s49, 0
	s_add_i32 s77, s65, s33
	global_load_lds_dwordx4 v[222:223], off
	v_lshl_add_u64 v[224:225], s[78:79], 0, v[148:149]
	s_mov_b32 m0, s77
	v_lshl_add_u64 v[226:227], s[50:51], 0, v[146:147]
	global_load_lds_dwordx4 v[224:225], off
	v_lshl_add_u64 v[224:225], s[78:79], 0, v[144:145]
	s_add_i32 m0, s77, 0x2000
	s_nop 0
	global_load_lds_dwordx4 v[224:225], off
	v_lshl_add_u64 v[224:225], s[50:51], 0, v[150:151]
	s_mov_b32 m0, s54
	s_nop 0
	global_load_lds_dwordx4 v[224:225], off
	s_mov_b32 m0, s55
	s_nop 0
	global_load_lds_dwordx4 v[226:227], off
	s_waitcnt vmcnt(8)
	s_waitcnt lgkmcnt(0)
	s_barrier
	s_waitcnt lgkmcnt(0)
	v_mfma_f32_16x16x32_f16 v[60:63], v[128:131], v[186:189], 0
	v_mfma_f32_16x16x32_f16 v[56:59], v[136:139], v[186:189], 0
	v_mfma_f32_16x16x32_f16 v[44:47], v[128:131], v[194:197], 0
	v_mfma_f32_16x16x32_f16 v[40:43], v[136:139], v[194:197], 0
	v_mfma_f32_16x16x32_f16 v[28:31], v[128:131], v[206:209], 0
	v_mfma_f32_16x16x32_f16 v[24:27], v[136:139], v[206:209], 0
	v_mfma_f32_16x16x32_f16 v[12:15], v[128:131], v[214:217], 0
	v_mfma_f32_16x16x32_f16 v[8:11], v[136:139], v[214:217], 0
	v_mfma_f32_16x16x32_f16 v[60:63], v[132:135], v[190:193], v[60:63]
	v_mfma_f32_16x16x32_f16 v[56:59], v[140:143], v[190:193], v[56:59]
	v_mfma_f32_16x16x32_f16 v[44:47], v[132:135], v[198:201], v[44:47]
	v_mfma_f32_16x16x32_f16 v[40:43], v[140:143], v[198:201], v[40:43]
	v_mfma_f32_16x16x32_f16 v[28:31], v[132:135], v[210:213], v[28:31]
	v_mfma_f32_16x16x32_f16 v[24:27], v[140:143], v[210:213], v[24:27]
	v_mfma_f32_16x16x32_f16 v[12:15], v[132:135], v[218:221], v[12:15]
	v_mfma_f32_16x16x32_f16 v[8:11], v[140:143], v[218:221], v[8:11]
	v_mfma_f32_16x16x32_f16 v[52:55], v[160:163], v[186:189], 0
	v_mfma_f32_16x16x32_f16 v[48:51], v[178:181], v[186:189], 0
	v_mfma_f32_16x16x32_f16 v[36:39], v[160:163], v[194:197], 0
	v_mfma_f32_16x16x32_f16 v[32:35], v[178:181], v[194:197], 0
	v_mfma_f32_16x16x32_f16 v[20:23], v[160:163], v[206:209], 0
	v_mfma_f32_16x16x32_f16 v[16:19], v[178:181], v[206:209], 0
	v_mfma_f32_16x16x32_f16 v[4:7], v[160:163], v[214:217], 0
	v_mfma_f32_16x16x32_f16 v[0:3], v[178:181], v[214:217], 0
	v_mfma_f32_16x16x32_f16 v[52:55], v[172:175], v[190:193], v[52:55]
	v_mfma_f32_16x16x32_f16 v[48:51], v[182:185], v[190:193], v[48:51]
	v_mfma_f32_16x16x32_f16 v[36:39], v[172:175], v[198:201], v[36:39]
	v_mfma_f32_16x16x32_f16 v[32:35], v[182:185], v[198:201], v[32:35]
	v_mfma_f32_16x16x32_f16 v[20:23], v[172:175], v[210:213], v[20:23]
	v_mfma_f32_16x16x32_f16 v[16:19], v[182:185], v[210:213], v[16:19]
	v_mfma_f32_16x16x32_f16 v[4:7], v[172:175], v[218:221], v[4:7]
	v_mfma_f32_16x16x32_f16 v[0:3], v[182:185], v[218:221], v[0:3]
	s_barrier
	s_add_i32 s77, 0, 0x18000
	s_add_i32 s78, 0, 0x1c000
	v_add_u32_e32 v140, s77, v165
	v_add_u32_e32 v177, s78, v165
	ds_read_b128 v[128:131], v140
	ds_read_b128 v[132:135], v140 offset:1024
	ds_read_b128 v[136:139], v140 offset:2048
	ds_read_b128 v[140:143], v140 offset:3072
	ds_read_b128 v[160:163], v177
	ds_read_b128 v[172:175], v177 offset:1024
	ds_read_b128 v[178:181], v177 offset:2048
	ds_read_b128 v[182:185], v177 offset:3072
	s_add_u32 s50, s50, 0x40000
	s_addc_u32 s51, s51, 0
	s_mov_b32 m0, s56
	v_lshl_add_u64 v[228:229], s[50:51], 0, v[150:151]
	ds_read_b128 v[186:189], v169 offset:32768
	ds_read_b128 v[190:193], v169 offset:33792
	ds_read_b128 v[194:197], v169 offset:34816
	ds_read_b128 v[198:201], v169 offset:35840
	ds_read_b128 v[206:209], v169 offset:36864
	ds_read_b128 v[210:213], v169 offset:37888
	ds_read_b128 v[214:217], v169 offset:38912
	ds_read_b128 v[218:221], v169 offset:39936
	global_load_lds_dwordx4 v[228:229], off
	v_lshl_add_u64 v[228:229], s[50:51], 0, v[146:147]
	s_mov_b32 m0, s57
	s_nop 0
	global_load_lds_dwordx4 v[228:229], off
	s_waitcnt vmcnt(8)
	s_waitcnt lgkmcnt(0)
	s_barrier
	s_waitcnt lgkmcnt(0)
	v_mfma_f32_16x16x32_f16 v[124:127], v[128:131], v[186:189], v[124:127]
	v_mfma_f32_16x16x32_f16 v[120:123], v[136:139], v[186:189], v[120:123]
	v_mfma_f32_16x16x32_f16 v[108:111], v[128:131], v[194:197], v[108:111]
	v_mfma_f32_16x16x32_f16 v[104:107], v[136:139], v[194:197], v[104:107]
	v_mfma_f32_16x16x32_f16 v[92:95], v[128:131], v[206:209], v[92:95]
	v_mfma_f32_16x16x32_f16 v[88:91], v[136:139], v[206:209], v[88:91]
	v_mfma_f32_16x16x32_f16 v[84:87], v[128:131], v[214:217], v[84:87]
	v_mfma_f32_16x16x32_f16 v[76:79], v[136:139], v[214:217], v[76:79]
	v_mfma_f32_16x16x32_f16 v[124:127], v[132:135], v[190:193], v[124:127]
	v_mfma_f32_16x16x32_f16 v[120:123], v[140:143], v[190:193], v[120:123]
	v_mfma_f32_16x16x32_f16 v[108:111], v[132:135], v[198:201], v[108:111]
	v_mfma_f32_16x16x32_f16 v[104:107], v[140:143], v[198:201], v[104:107]
	v_mfma_f32_16x16x32_f16 v[92:95], v[132:135], v[210:213], v[92:95]
	v_mfma_f32_16x16x32_f16 v[88:91], v[140:143], v[210:213], v[88:91]
	v_mfma_f32_16x16x32_f16 v[84:87], v[132:135], v[218:221], v[84:87]
	v_mfma_f32_16x16x32_f16 v[76:79], v[140:143], v[218:221], v[76:79]
	v_mfma_f32_16x16x32_f16 v[116:119], v[160:163], v[186:189], v[116:119]
	v_mfma_f32_16x16x32_f16 v[112:115], v[178:181], v[186:189], v[112:115]
	v_mfma_f32_16x16x32_f16 v[100:103], v[160:163], v[194:197], v[100:103]
	v_mfma_f32_16x16x32_f16 v[96:99], v[178:181], v[194:197], v[96:99]
	v_mfma_f32_16x16x32_f16 v[80:83], v[160:163], v[206:209], v[80:83]
	v_mfma_f32_16x16x32_f16 v[72:75], v[178:181], v[206:209], v[72:75]
	v_mfma_f32_16x16x32_f16 v[68:71], v[160:163], v[214:217], v[68:71]
	v_mfma_f32_16x16x32_f16 v[64:67], v[178:181], v[214:217], v[64:67]
	v_mfma_f32_16x16x32_f16 v[116:119], v[172:175], v[190:193], v[116:119]
	v_mfma_f32_16x16x32_f16 v[112:115], v[182:185], v[190:193], v[112:115]
	v_mfma_f32_16x16x32_f16 v[100:103], v[172:175], v[198:201], v[100:103]
	v_mfma_f32_16x16x32_f16 v[96:99], v[182:185], v[198:201], v[96:99]
	v_mfma_f32_16x16x32_f16 v[80:83], v[172:175], v[210:213], v[80:83]
	v_mfma_f32_16x16x32_f16 v[72:75], v[182:185], v[210:213], v[72:75]
	v_mfma_f32_16x16x32_f16 v[68:71], v[172:175], v[218:221], v[68:71]
	v_mfma_f32_16x16x32_f16 v[64:67], v[182:185], v[218:221], v[64:67]
	s_barrier
	s_add_i32 s50, s77, s33
	v_lshl_add_u64 v[202:203], v[202:203], 0, s[12:13]
	s_mov_b32 m0, s50
	ds_read_b128 v[186:189], v169 offset:49152
	ds_read_b128 v[190:193], v169 offset:50176
	ds_read_b128 v[194:197], v169 offset:51200
	ds_read_b128 v[198:201], v169 offset:52224
	ds_read_b128 v[206:209], v169 offset:53248
	ds_read_b128 v[210:213], v169 offset:54272
	ds_read_b128 v[214:217], v169 offset:55296
	ds_read_b128 v[218:221], v169 offset:56320
	global_load_lds_dwordx4 v[202:203], off
	s_add_i32 m0, s50, 0x2000
	s_add_u32 s48, s48, 0x40080
	v_lshl_add_u64 v[202:203], v[222:223], 0, s[12:13]
	s_addc_u32 s49, s49, 0
	s_add_i32 s50, s78, s33
	global_load_lds_dwordx4 v[202:203], off
	v_lshl_add_u64 v[202:203], s[48:49], 0, v[148:149]
	s_mov_b32 m0, s50
	s_nop 0
	global_load_lds_dwordx4 v[202:203], off
	v_lshl_add_u64 v[202:203], s[48:49], 0, v[144:145]
	s_add_i32 m0, s50, 0x2000
	s_nop 0
	global_load_lds_dwordx4 v[202:203], off
	v_lshl_add_u64 v[202:203], v[224:225], 0, s[12:13]
	s_mov_b32 m0, s61
	s_nop 0
	global_load_lds_dwordx4 v[202:203], off
	v_lshl_add_u64 v[202:203], v[226:227], 0, s[12:13]
	s_mov_b32 m0, s62
	s_nop 0
	global_load_lds_dwordx4 v[202:203], off
	s_waitcnt vmcnt(8)
	s_waitcnt lgkmcnt(0)
	s_barrier
	s_waitcnt lgkmcnt(0)
	v_mfma_f32_16x16x32_f16 v[60:63], v[128:131], v[186:189], v[60:63]
	v_mfma_f32_16x16x32_f16 v[56:59], v[136:139], v[186:189], v[56:59]
	v_mfma_f32_16x16x32_f16 v[44:47], v[128:131], v[194:197], v[44:47]
	v_mfma_f32_16x16x32_f16 v[40:43], v[136:139], v[194:197], v[40:43]
	v_mfma_f32_16x16x32_f16 v[28:31], v[128:131], v[206:209], v[28:31]
	v_mfma_f32_16x16x32_f16 v[24:27], v[136:139], v[206:209], v[24:27]
	v_mfma_f32_16x16x32_f16 v[12:15], v[128:131], v[214:217], v[12:15]
	v_mfma_f32_16x16x32_f16 v[8:11], v[136:139], v[214:217], v[8:11]
	v_mfma_f32_16x16x32_f16 v[60:63], v[132:135], v[190:193], v[60:63]
	v_mfma_f32_16x16x32_f16 v[56:59], v[140:143], v[190:193], v[56:59]
	v_mfma_f32_16x16x32_f16 v[44:47], v[132:135], v[198:201], v[44:47]
	v_mfma_f32_16x16x32_f16 v[40:43], v[140:143], v[198:201], v[40:43]
	v_mfma_f32_16x16x32_f16 v[28:31], v[132:135], v[210:213], v[28:31]
	v_mfma_f32_16x16x32_f16 v[24:27], v[140:143], v[210:213], v[24:27]
	v_mfma_f32_16x16x32_f16 v[12:15], v[132:135], v[218:221], v[12:15]
	v_mfma_f32_16x16x32_f16 v[8:11], v[140:143], v[218:221], v[8:11]
	v_mfma_f32_16x16x32_f16 v[52:55], v[160:163], v[186:189], v[52:55]
	v_mfma_f32_16x16x32_f16 v[48:51], v[178:181], v[186:189], v[48:51]
	v_mfma_f32_16x16x32_f16 v[36:39], v[160:163], v[194:197], v[36:39]
	v_mfma_f32_16x16x32_f16 v[32:35], v[178:181], v[194:197], v[32:35]
	v_mfma_f32_16x16x32_f16 v[20:23], v[160:163], v[206:209], v[20:23]
	v_mfma_f32_16x16x32_f16 v[16:19], v[178:181], v[206:209], v[16:19]
	v_mfma_f32_16x16x32_f16 v[4:7], v[160:163], v[214:217], v[4:7]
	v_mfma_f32_16x16x32_f16 v[0:3], v[178:181], v[214:217], v[0:3]
	v_mfma_f32_16x16x32_f16 v[52:55], v[172:175], v[190:193], v[52:55]
	v_mfma_f32_16x16x32_f16 v[48:51], v[182:185], v[190:193], v[48:51]
	v_mfma_f32_16x16x32_f16 v[36:39], v[172:175], v[198:201], v[36:39]
	v_mfma_f32_16x16x32_f16 v[32:35], v[182:185], v[198:201], v[32:35]
	v_mfma_f32_16x16x32_f16 v[20:23], v[172:175], v[210:213], v[20:23]
	v_mfma_f32_16x16x32_f16 v[16:19], v[182:185], v[210:213], v[16:19]
	v_mfma_f32_16x16x32_f16 v[4:7], v[172:175], v[218:221], v[4:7]
	v_mfma_f32_16x16x32_f16 v[0:3], v[182:185], v[218:221], v[0:3]
	s_barrier
	s_add_i32 s76, s76, 2
	s_add_u32 s46, s46, 0x100
	s_addc_u32 s47, s47, 0
	s_add_u32 s74, s74, 0x100
	s_addc_u32 s75, s75, 0
	s_cmp_gt_u32 s76, 13

.LBB0_1491:
	ds_read_b128 v[80:83], v208
	ds_read_b128 v[84:87], v208 offset:1024
	ds_read_b128 v[88:91], v208 offset:2048
	ds_read_b128 v[92:95], v208 offset:3072
	ds_read_b128 v[96:99], v209
	ds_read_b128 v[104:107], v209 offset:1024
	ds_read_b128 v[108:111], v209 offset:2048
	ds_read_b128 v[112:115], v209 offset:3072
	ds_read_b128 v[160:163], v210
	ds_read_b128 v[164:167], v210 offset:1024
	ds_read_b128 v[168:171], v210 offset:2048
	ds_read_b128 v[172:175], v210 offset:3072
	ds_read_b128 v[194:197], v210 offset:4096
	ds_read_b128 v[198:201], v210 offset:5120
	ds_read_b128 v[212:215], v210 offset:6144
	ds_read_b128 v[216:219], v210 offset:7168
	s_add_i32 s51, s51, 1
	s_mul_i32 s4, s51, s58
	s_mul_hi_u32 s5, s51, s9
	s_add_i32 s5, s5, s4
	s_mul_i32 s4, s51, s9
	s_add_u32 s20, s4, s8
	s_addc_u32 s21, s5, s59
	v_cmp_gt_i64_e32 vcc, s[20:21], v[192:193]
	v_cmp_lt_i64_e64 s[4:5], s[20:21], v[190:191]
	s_cbranch_vccnz .LBB0_1497
	s_ashr_i32 s16, s20, 31
	s_lshr_b32 s16, s16, 29
	s_add_i32 s18, s20, s16
	s_and_b32 s16, s18, -8
	s_sub_i32 s19, s20, s16
	s_cmp_gt_i32 s19, -1
	s_mov_b64 s[16:17], -1
	s_cbranch_scc0 .LBB0_1494
	s_lshl_b32 s20, s19, 5
	s_mov_b64 s[16:17], 0

.LBB0_1497:
	s_ashr_i32 s19, s18, 31
	s_lshl_b64 s[20:21], s[18:19], 19
	s_add_u32 s20, s36, s20
	s_addc_u32 s21, s37, s21
	s_and_b64 s[22:23], s[4:5], exec
	s_cselect_b32 s19, s21, s35
	s_cselect_b32 s25, s20, s34
	s_ashr_i32 s17, s16, 31
	s_lshl_b64 s[22:23], s[16:17], 19
	s_add_u32 s22, s33, s22
	s_addc_u32 s23, s46, s23
	s_and_b64 s[44:45], s[4:5], exec
	s_cselect_b32 s17, s23, s41
	s_cselect_b32 s62, s22, s40
	s_add_u32 s34, s34, 0x40080
	s_addc_u32 s35, s35, 0
	s_add_u32 s63, s40, 0x100
	s_addc_u32 s64, s41, 0
	s_mov_b32 s65, -2
	s_waitcnt lgkmcnt(0)
	s_add_u32 s40, s34, 0xfffc0080
	s_addc_u32 s41, s35, -1
	s_cmp_eq_u32 s65, 12
	s_cselect_b32 s45, s19, s41
	s_cselect_b32 s44, s25, s40
	s_cselect_b32 s41, s17, s64
	s_cselect_b32 s40, s62, s63
	v_lshl_add_u64 v[202:203], s[34:35], 0, v[186:187]
	s_add_i32 m0, s27, 0xc000
	global_load_lds_dwordx4 v[202:203], off
	v_lshl_add_u64 v[202:203], s[34:35], 0, v[188:189]
	s_add_i32 m0, s27, 0xe000
	s_nop 0
	global_load_lds_dwordx4 v[202:203], off
	s_waitcnt vmcnt(8)
	s_waitcnt lgkmcnt(0)
	s_barrier
	s_waitcnt lgkmcnt(0)
	v_mfma_f32_16x16x32_f16 v[156:159], v[80:83], v[160:163], 0
	v_mfma_f32_16x16x32_f16 v[152:155], v[88:91], v[160:163], 0
	v_mfma_f32_16x16x32_f16 v[140:143], v[80:83], v[168:171], 0
	v_mfma_f32_16x16x32_f16 v[136:139], v[88:91], v[168:171], 0
	v_mfma_f32_16x16x32_f16 v[124:127], v[80:83], v[194:197], 0
	v_mfma_f32_16x16x32_f16 v[120:123], v[88:91], v[194:197], 0
	v_mfma_f32_16x16x32_f16 v[76:79], v[80:83], v[212:215], 0
	v_mfma_f32_16x16x32_f16 v[72:75], v[88:91], v[212:215], 0
	v_mfma_f32_16x16x32_f16 v[156:159], v[84:87], v[164:167], v[156:159]
	v_mfma_f32_16x16x32_f16 v[152:155], v[92:95], v[164:167], v[152:155]
	v_mfma_f32_16x16x32_f16 v[140:143], v[84:87], v[172:175], v[140:143]
	v_mfma_f32_16x16x32_f16 v[136:139], v[92:95], v[172:175], v[136:139]
	v_mfma_f32_16x16x32_f16 v[124:127], v[84:87], v[198:201], v[124:127]
	v_mfma_f32_16x16x32_f16 v[120:123], v[92:95], v[198:201], v[120:123]
	v_mfma_f32_16x16x32_f16 v[76:79], v[84:87], v[216:219], v[76:79]
	v_mfma_f32_16x16x32_f16 v[72:75], v[92:95], v[216:219], v[72:75]
	v_mfma_f32_16x16x32_f16 v[148:151], v[96:99], v[160:163], 0
	v_mfma_f32_16x16x32_f16 v[144:147], v[108:111], v[160:163], 0
	v_mfma_f32_16x16x32_f16 v[132:135], v[96:99], v[168:171], 0
	v_mfma_f32_16x16x32_f16 v[128:131], v[108:111], v[168:171], 0
	v_mfma_f32_16x16x32_f16 v[116:119], v[96:99], v[194:197], 0
	v_mfma_f32_16x16x32_f16 v[100:103], v[108:111], v[194:197], 0
	v_mfma_f32_16x16x32_f16 v[68:71], v[96:99], v[212:215], 0
	v_mfma_f32_16x16x32_f16 v[64:67], v[108:111], v[212:215], 0
	v_mfma_f32_16x16x32_f16 v[148:151], v[104:107], v[164:167], v[148:151]
	v_mfma_f32_16x16x32_f16 v[144:147], v[112:115], v[164:167], v[144:147]
	v_mfma_f32_16x16x32_f16 v[132:135], v[104:107], v[172:175], v[132:135]
	v_mfma_f32_16x16x32_f16 v[128:131], v[112:115], v[172:175], v[128:131]
	v_mfma_f32_16x16x32_f16 v[116:119], v[104:107], v[198:201], v[116:119]
	v_mfma_f32_16x16x32_f16 v[100:103], v[112:115], v[198:201], v[100:103]
	v_mfma_f32_16x16x32_f16 v[68:71], v[104:107], v[216:219], v[68:71]
	v_mfma_f32_16x16x32_f16 v[64:67], v[112:115], v[216:219], v[64:67]
	s_barrier
	s_add_i32 s66, s60, s47
	v_lshl_add_u64 v[202:203], s[40:41], 0, v[180:181]
	s_mov_b32 m0, s66
	ds_read_b128 v[160:163], v210 offset:16384
	ds_read_b128 v[164:167], v210 offset:17408
	ds_read_b128 v[168:171], v210 offset:18432
	ds_read_b128 v[172:175], v210 offset:19456
	ds_read_b128 v[194:197], v210 offset:20480
	ds_read_b128 v[198:201], v210 offset:21504
	ds_read_b128 v[212:215], v210 offset:22528
	ds_read_b128 v[216:219], v210 offset:23552
	global_load_lds_dwordx4 v[202:203], off
	s_add_i32 m0, s66, 0x2000
	s_add_u32 s66, s40, 0x40000
	v_lshl_add_u64 v[220:221], s[40:41], 0, v[184:185]
	s_addc_u32 s67, s41, 0
	s_add_i32 s68, s61, s47
	global_load_lds_dwordx4 v[220:221], off
	v_lshl_add_u64 v[222:223], s[66:67], 0, v[180:181]
	s_mov_b32 m0, s68
	v_lshl_add_u64 v[224:225], s[44:45], 0, v[182:183]
	global_load_lds_dwordx4 v[222:223], off
	v_lshl_add_u64 v[222:223], s[66:67], 0, v[184:185]
	s_add_i32 m0, s68, 0x2000
	s_nop 0
	global_load_lds_dwordx4 v[222:223], off
	v_lshl_add_u64 v[222:223], s[44:45], 0, v[178:179]
	s_mov_b32 m0, s27
	s_nop 0
	global_load_lds_dwordx4 v[222:223], off
	s_mov_b32 m0, s48
	s_nop 0
	global_load_lds_dwordx4 v[224:225], off
	s_waitcnt vmcnt(8)
	s_waitcnt lgkmcnt(0)
	s_barrier
	s_waitcnt lgkmcnt(0)
	v_mfma_f32_16x16x32_f16 v[60:63], v[80:83], v[160:163], 0
	v_mfma_f32_16x16x32_f16 v[56:59], v[88:91], v[160:163], 0
	v_mfma_f32_16x16x32_f16 v[44:47], v[80:83], v[168:171], 0
	v_mfma_f32_16x16x32_f16 v[40:43], v[88:91], v[168:171], 0
	v_mfma_f32_16x16x32_f16 v[28:31], v[80:83], v[194:197], 0
	v_mfma_f32_16x16x32_f16 v[24:27], v[88:91], v[194:197], 0
	v_mfma_f32_16x16x32_f16 v[12:15], v[80:83], v[212:215], 0
	v_mfma_f32_16x16x32_f16 v[8:11], v[88:91], v[212:215], 0
	v_mfma_f32_16x16x32_f16 v[60:63], v[84:87], v[164:167], v[60:63]
	v_mfma_f32_16x16x32_f16 v[56:59], v[92:95], v[164:167], v[56:59]
	v_mfma_f32_16x16x32_f16 v[44:47], v[84:87], v[172:175], v[44:47]
	v_mfma_f32_16x16x32_f16 v[40:43], v[92:95], v[172:175], v[40:43]
	v_mfma_f32_16x16x32_f16 v[28:31], v[84:87], v[198:201], v[28:31]
	v_mfma_f32_16x16x32_f16 v[24:27], v[92:95], v[198:201], v[24:27]
	v_mfma_f32_16x16x32_f16 v[12:15], v[84:87], v[216:219], v[12:15]
	v_mfma_f32_16x16x32_f16 v[8:11], v[92:95], v[216:219], v[8:11]
	v_mfma_f32_16x16x32_f16 v[52:55], v[96:99], v[160:163], 0
	v_mfma_f32_16x16x32_f16 v[48:51], v[108:111], v[160:163], 0
	v_mfma_f32_16x16x32_f16 v[36:39], v[96:99], v[168:171], 0
	v_mfma_f32_16x16x32_f16 v[32:35], v[108:111], v[168:171], 0
	v_mfma_f32_16x16x32_f16 v[20:23], v[96:99], v[194:197], 0
	v_mfma_f32_16x16x32_f16 v[16:19], v[108:111], v[194:197], 0
	v_mfma_f32_16x16x32_f16 v[4:7], v[96:99], v[212:215], 0
	v_mfma_f32_16x16x32_f16 v[0:3], v[108:111], v[212:215], 0
	v_mfma_f32_16x16x32_f16 v[52:55], v[104:107], v[164:167], v[52:55]
	v_mfma_f32_16x16x32_f16 v[48:51], v[112:115], v[164:167], v[48:51]
	v_mfma_f32_16x16x32_f16 v[36:39], v[104:107], v[172:175], v[36:39]
	v_mfma_f32_16x16x32_f16 v[32:35], v[112:115], v[172:175], v[32:35]
	v_mfma_f32_16x16x32_f16 v[20:23], v[104:107], v[198:201], v[20:23]
	v_mfma_f32_16x16x32_f16 v[16:19], v[112:115], v[198:201], v[16:19]
	v_mfma_f32_16x16x32_f16 v[4:7], v[104:107], v[216:219], v[4:7]
	v_mfma_f32_16x16x32_f16 v[0:3], v[112:115], v[216:219], v[0:3]
	s_barrier
	s_add_i32 s66, 0, 0x18000
	s_add_i32 s67, 0, 0x1c000
	v_add_u32_e32 v92, s66, v206
	v_add_u32_e32 v112, s67, v206
	ds_read_b128 v[80:83], v92
	ds_read_b128 v[84:87], v92 offset:1024
	ds_read_b128 v[88:91], v92 offset:2048
	ds_read_b128 v[92:95], v92 offset:3072
	ds_read_b128 v[96:99], v112
	ds_read_b128 v[104:107], v112 offset:1024
	ds_read_b128 v[108:111], v112 offset:2048
	ds_read_b128 v[112:115], v112 offset:3072
	s_add_u32 s44, s44, 0x40000
	s_addc_u32 s45, s45, 0
	s_mov_b32 m0, s49
	v_lshl_add_u64 v[226:227], s[44:45], 0, v[178:179]
	ds_read_b128 v[160:163], v210 offset:32768
	ds_read_b128 v[164:167], v210 offset:33792
	ds_read_b128 v[168:171], v210 offset:34816
	ds_read_b128 v[172:175], v210 offset:35840
	ds_read_b128 v[194:197], v210 offset:36864
	ds_read_b128 v[198:201], v210 offset:37888
	ds_read_b128 v[212:215], v210 offset:38912
	ds_read_b128 v[216:219], v210 offset:39936
	global_load_lds_dwordx4 v[226:227], off
	v_lshl_add_u64 v[226:227], s[44:45], 0, v[182:183]
	s_mov_b32 m0, s50
	s_nop 0
	global_load_lds_dwordx4 v[226:227], off
	s_waitcnt vmcnt(8)
	s_waitcnt lgkmcnt(0)
	s_barrier
	s_waitcnt lgkmcnt(0)
	v_mfma_f32_16x16x32_f16 v[156:159], v[80:83], v[160:163], v[156:159]
	v_mfma_f32_16x16x32_f16 v[152:155], v[88:91], v[160:163], v[152:155]
	v_mfma_f32_16x16x32_f16 v[140:143], v[80:83], v[168:171], v[140:143]
	v_mfma_f32_16x16x32_f16 v[136:139], v[88:91], v[168:171], v[136:139]
	v_mfma_f32_16x16x32_f16 v[124:127], v[80:83], v[194:197], v[124:127]
	v_mfma_f32_16x16x32_f16 v[120:123], v[88:91], v[194:197], v[120:123]
	v_mfma_f32_16x16x32_f16 v[76:79], v[80:83], v[212:215], v[76:79]
	v_mfma_f32_16x16x32_f16 v[72:75], v[88:91], v[212:215], v[72:75]
	v_mfma_f32_16x16x32_f16 v[156:159], v[84:87], v[164:167], v[156:159]
	v_mfma_f32_16x16x32_f16 v[152:155], v[92:95], v[164:167], v[152:155]
	v_mfma_f32_16x16x32_f16 v[140:143], v[84:87], v[172:175], v[140:143]
	v_mfma_f32_16x16x32_f16 v[136:139], v[92:95], v[172:175], v[136:139]
	v_mfma_f32_16x16x32_f16 v[124:127], v[84:87], v[198:201], v[124:127]
	v_mfma_f32_16x16x32_f16 v[120:123], v[92:95], v[198:201], v[120:123]
	v_mfma_f32_16x16x32_f16 v[76:79], v[84:87], v[216:219], v[76:79]
	v_mfma_f32_16x16x32_f16 v[72:75], v[92:95], v[216:219], v[72:75]
	v_mfma_f32_16x16x32_f16 v[148:151], v[96:99], v[160:163], v[148:151]
	v_mfma_f32_16x16x32_f16 v[144:147], v[108:111], v[160:163], v[144:147]
	v_mfma_f32_16x16x32_f16 v[132:135], v[96:99], v[168:171], v[132:135]
	v_mfma_f32_16x16x32_f16 v[128:131], v[108:111], v[168:171], v[128:131]
	v_mfma_f32_16x16x32_f16 v[116:119], v[96:99], v[194:197], v[116:119]
	v_mfma_f32_16x16x32_f16 v[100:103], v[108:111], v[194:197], v[100:103]
	v_mfma_f32_16x16x32_f16 v[68:71], v[96:99], v[212:215], v[68:71]
	v_mfma_f32_16x16x32_f16 v[64:67], v[108:111], v[212:215], v[64:67]
	v_mfma_f32_16x16x32_f16 v[148:151], v[104:107], v[164:167], v[148:151]
	v_mfma_f32_16x16x32_f16 v[144:147], v[112:115], v[164:167], v[144:147]
	v_mfma_f32_16x16x32_f16 v[132:135], v[104:107], v[172:175], v[132:135]
	v_mfma_f32_16x16x32_f16 v[128:131], v[112:115], v[172:175], v[128:131]
	v_mfma_f32_16x16x32_f16 v[116:119], v[104:107], v[198:201], v[116:119]
	v_mfma_f32_16x16x32_f16 v[100:103], v[112:115], v[198:201], v[100:103]
	v_mfma_f32_16x16x32_f16 v[68:71], v[104:107], v[216:219], v[68:71]
	v_mfma_f32_16x16x32_f16 v[64:67], v[112:115], v[216:219], v[64:67]
	s_barrier
	s_add_i32 s44, s66, s47
	v_lshl_add_u64 v[202:203], v[202:203], 0, s[12:13]
	s_mov_b32 m0, s44
	ds_read_b128 v[160:163], v210 offset:49152
	ds_read_b128 v[164:167], v210 offset:50176
	ds_read_b128 v[168:171], v210 offset:51200
	ds_read_b128 v[172:175], v210 offset:52224
	ds_read_b128 v[194:197], v210 offset:53248
	ds_read_b128 v[198:201], v210 offset:54272
	ds_read_b128 v[212:215], v210 offset:55296
	ds_read_b128 v[216:219], v210 offset:56320
	global_load_lds_dwordx4 v[202:203], off
	s_add_i32 m0, s44, 0x2000
	s_add_u32 s40, s40, 0x40080
	v_lshl_add_u64 v[202:203], v[220:221], 0, s[12:13]
	s_addc_u32 s41, s41, 0
	s_add_i32 s44, s67, s47
	global_load_lds_dwordx4 v[202:203], off
	v_lshl_add_u64 v[202:203], s[40:41], 0, v[180:181]
	s_mov_b32 m0, s44
	s_nop 0
	global_load_lds_dwordx4 v[202:203], off
	v_lshl_add_u64 v[202:203], s[40:41], 0, v[184:185]
	s_add_i32 m0, s44, 0x2000
	s_nop 0
	global_load_lds_dwordx4 v[202:203], off
	v_lshl_add_u64 v[202:203], v[222:223], 0, s[12:13]
	s_mov_b32 m0, s56
	s_nop 0
	global_load_lds_dwordx4 v[202:203], off
	v_lshl_add_u64 v[202:203], v[224:225], 0, s[12:13]
	s_mov_b32 m0, s57
	s_nop 0
	global_load_lds_dwordx4 v[202:203], off
	s_waitcnt vmcnt(8)
	s_waitcnt lgkmcnt(0)
	s_barrier
	s_waitcnt lgkmcnt(0)
	v_mfma_f32_16x16x32_f16 v[60:63], v[80:83], v[160:163], v[60:63]
	v_mfma_f32_16x16x32_f16 v[56:59], v[88:91], v[160:163], v[56:59]
	v_mfma_f32_16x16x32_f16 v[44:47], v[80:83], v[168:171], v[44:47]
	v_mfma_f32_16x16x32_f16 v[40:43], v[88:91], v[168:171], v[40:43]
	v_mfma_f32_16x16x32_f16 v[28:31], v[80:83], v[194:197], v[28:31]
	v_mfma_f32_16x16x32_f16 v[24:27], v[88:91], v[194:197], v[24:27]
	v_mfma_f32_16x16x32_f16 v[12:15], v[80:83], v[212:215], v[12:15]
	v_mfma_f32_16x16x32_f16 v[8:11], v[88:91], v[212:215], v[8:11]
	v_mfma_f32_16x16x32_f16 v[60:63], v[84:87], v[164:167], v[60:63]
	v_mfma_f32_16x16x32_f16 v[56:59], v[92:95], v[164:167], v[56:59]
	v_mfma_f32_16x16x32_f16 v[44:47], v[84:87], v[172:175], v[44:47]
	v_mfma_f32_16x16x32_f16 v[40:43], v[92:95], v[172:175], v[40:43]
	v_mfma_f32_16x16x32_f16 v[28:31], v[84:87], v[198:201], v[28:31]
	v_mfma_f32_16x16x32_f16 v[24:27], v[92:95], v[198:201], v[24:27]
	v_mfma_f32_16x16x32_f16 v[12:15], v[84:87], v[216:219], v[12:15]
	v_mfma_f32_16x16x32_f16 v[8:11], v[92:95], v[216:219], v[8:11]
	v_mfma_f32_16x16x32_f16 v[52:55], v[96:99], v[160:163], v[52:55]
	v_mfma_f32_16x16x32_f16 v[48:51], v[108:111], v[160:163], v[48:51]
	v_mfma_f32_16x16x32_f16 v[36:39], v[96:99], v[168:171], v[36:39]
	v_mfma_f32_16x16x32_f16 v[32:35], v[108:111], v[168:171], v[32:35]
	v_mfma_f32_16x16x32_f16 v[20:23], v[96:99], v[194:197], v[20:23]
	v_mfma_f32_16x16x32_f16 v[16:19], v[108:111], v[194:197], v[16:19]
	v_mfma_f32_16x16x32_f16 v[4:7], v[96:99], v[212:215], v[4:7]
	v_mfma_f32_16x16x32_f16 v[0:3], v[108:111], v[212:215], v[0:3]
	v_mfma_f32_16x16x32_f16 v[52:55], v[104:107], v[164:167], v[52:55]
	v_mfma_f32_16x16x32_f16 v[48:51], v[112:115], v[164:167], v[48:51]
	v_mfma_f32_16x16x32_f16 v[36:39], v[104:107], v[172:175], v[36:39]
	v_mfma_f32_16x16x32_f16 v[32:35], v[112:115], v[172:175], v[32:35]
	v_mfma_f32_16x16x32_f16 v[20:23], v[104:107], v[198:201], v[20:23]
	v_mfma_f32_16x16x32_f16 v[16:19], v[112:115], v[198:201], v[16:19]
	v_mfma_f32_16x16x32_f16 v[4:7], v[104:107], v[216:219], v[4:7]
	v_mfma_f32_16x16x32_f16 v[0:3], v[112:115], v[216:219], v[0:3]
	s_barrier
	s_add_i32 s65, s65, 2
	s_add_u32 s34, s34, 0x100
	s_addc_u32 s35, s35, 0
	s_add_u32 s63, s63, 0x100
	s_addc_u32 s64, s64, 0
	s_cmp_gt_u32 s65, 13

.LBB0_1582:
	ds_read_b128 v[104:107], v171
	ds_read_b128 v[108:111], v171 offset:1024
	ds_read_b128 v[112:115], v171 offset:2048
	ds_read_b128 v[116:119], v171 offset:3072
	ds_read_b128 v[160:163], v172
	ds_read_b128 v[164:167], v172 offset:1024
	ds_read_b128 v[178:181], v172 offset:2048
	ds_read_b128 v[182:185], v172 offset:3072
	ds_read_b128 v[186:189], v173
	ds_read_b128 v[190:193], v173 offset:1024
	ds_read_b128 v[194:197], v173 offset:2048
	ds_read_b128 v[198:201], v173 offset:3072
	ds_read_b128 v[206:209], v173 offset:4096
	ds_read_b128 v[210:213], v173 offset:5120
	ds_read_b128 v[214:217], v173 offset:6144
	ds_read_b128 v[218:221], v173 offset:7168
	s_add_i32 s49, s49, 1
	s_mul_i32 s2, s49, s54
	s_mul_hi_u32 s3, s49, s9
	s_add_i32 s3, s3, s2
	s_mul_i32 s2, s49, s9
	s_add_u32 s18, s2, s8
	s_addc_u32 s19, s3, s44
	v_cmp_gt_i64_e32 vcc, s[18:19], v[158:159]
	v_cmp_lt_i64_e64 s[2:3], s[18:19], v[156:157]
	s_cbranch_vccnz .LBB0_1584
	s_ashr_i32 s14, s18, 31
	s_lshr_b32 s14, s14, 29
	s_add_i32 s14, s18, s14
	s_ashr_i32 s15, s14, 3
	s_and_b32 s14, s14, -8
	s_sub_i32 s14, s18, s14
	s_cmp_lt_i32 s14, 0
	s_cselect_b32 s16, s45, 0xb0
	s_mul_i32 s14, s14, s16
	s_add_i32 s14, s14, s15
	s_mul_hi_i32 s15, s14, 0x2e8ba2e9
	s_lshr_b32 s16, s15, 31
	s_ashr_i32 s15, s15, 5
	s_add_i32 s15, s15, s16
	s_lshl_b32 s16, s15, 3
	s_sub_i32 s17, 64, s16
	s_min_i32 s17, s17, 8
	s_abs_i32 s18, s17
	v_cvt_f32_u32_e32 v0, s18
	s_sub_i32 s20, 0, s18
	s_mulk_i32 s15, 0xb0
	s_sub_i32 s15, s14, s15
	v_rcp_iflag_f32_e32 v0, v0
	s_abs_i32 s14, s15
	s_xor_b32 s19, s15, s17
	s_ashr_i32 s19, s19, 31
	v_mul_f32_e32 v0, 0x4f7ffffe, v0
	v_cvt_u32_f32_e32 v0, v0
	s_nop 0
	v_readfirstlane_b32 s21, v0
	s_mul_i32 s20, s20, s21
	s_mul_hi_u32 s20, s21, s20
	s_add_i32 s21, s21, s20
	s_mul_hi_u32 s20, s14, s21
	s_mul_i32 s21, s20, s18
	s_sub_i32 s14, s14, s21
	s_add_i32 s34, s20, 1
	s_sub_i32 s21, s14, s18
	s_cmp_ge_u32 s14, s18
	s_cselect_b32 s20, s34, s20
	s_cselect_b32 s14, s21, s14
	s_add_i32 s21, s20, 1
	s_cmp_ge_u32 s14, s18
	s_cselect_b32 s14, s21, s20
	s_xor_b32 s14, s14, s19
	s_sub_i32 s14, s14, s19
	s_mul_i32 s17, s14, s17
	s_sub_i32 s15, s15, s17
	s_add_i32 s16, s16, s15
.LBB0_1584:
	s_ashr_i32 s17, s16, 31
	s_lshl_b64 s[18:19], s[16:17], 19
	s_add_u32 s18, s42, s18
	s_addc_u32 s19, s43, s19
	s_and_b64 s[20:21], s[2:3], exec
	s_cselect_b32 s17, s19, s25
	s_cselect_b32 s60, s18, s24
	s_ashr_i32 s15, s14, 31
	s_lshl_b64 s[20:21], s[14:15], 19
	s_add_u32 s20, s33, s20
	s_addc_u32 s21, s40, s21
	s_and_b64 s[34:35], s[2:3], exec
	s_cselect_b32 s15, s21, s27
	s_cselect_b32 s61, s20, s26
	s_add_u32 s24, s24, 0x40080
	s_addc_u32 s25, s25, 0
	s_add_u32 s62, s26, 0x100
	s_addc_u32 s63, s27, 0
	s_mov_b32 s64, -2
	s_add_u32 s26, s24, 0xfffc0080
	s_addc_u32 s27, s25, -1
	s_cmp_eq_u32 s64, 12
	s_cselect_b32 s35, s17, s27
	s_cselect_b32 s34, s60, s26
	s_cselect_b32 s27, s15, s63
	s_cselect_b32 s26, s61, s62
	v_lshl_add_u64 v[202:203], s[24:25], 0, v[152:153]
	s_add_i32 m0, s23, 0xc000
	global_load_lds_dwordx4 v[202:203], off
	v_lshl_add_u64 v[202:203], s[24:25], 0, v[154:155]
	s_add_i32 m0, s23, 0xe000
	s_nop 0
	global_load_lds_dwordx4 v[202:203], off
	s_waitcnt vmcnt(8)
	s_waitcnt lgkmcnt(0)
	s_barrier
	s_waitcnt lgkmcnt(0)
	v_mfma_f32_16x16x32_f16 v[140:143], v[104:107], v[186:189], 0
	v_mfma_f32_16x16x32_f16 v[136:139], v[112:115], v[186:189], 0
	v_mfma_f32_16x16x32_f16 v[124:127], v[104:107], v[194:197], 0
	v_mfma_f32_16x16x32_f16 v[120:123], v[112:115], v[194:197], 0
	v_mfma_f32_16x16x32_f16 v[92:95], v[104:107], v[206:209], 0
	v_mfma_f32_16x16x32_f16 v[88:91], v[112:115], v[206:209], 0
	v_mfma_f32_16x16x32_f16 v[76:79], v[104:107], v[214:217], 0
	v_mfma_f32_16x16x32_f16 v[72:75], v[112:115], v[214:217], 0
	v_mfma_f32_16x16x32_f16 v[140:143], v[108:111], v[190:193], v[140:143]
	v_mfma_f32_16x16x32_f16 v[136:139], v[116:119], v[190:193], v[136:139]
	v_mfma_f32_16x16x32_f16 v[124:127], v[108:111], v[198:201], v[124:127]
	v_mfma_f32_16x16x32_f16 v[120:123], v[116:119], v[198:201], v[120:123]
	v_mfma_f32_16x16x32_f16 v[92:95], v[108:111], v[210:213], v[92:95]
	v_mfma_f32_16x16x32_f16 v[88:91], v[116:119], v[210:213], v[88:91]
	v_mfma_f32_16x16x32_f16 v[76:79], v[108:111], v[218:221], v[76:79]
	v_mfma_f32_16x16x32_f16 v[72:75], v[116:119], v[218:221], v[72:75]
	v_mfma_f32_16x16x32_f16 v[132:135], v[160:163], v[186:189], 0
	v_mfma_f32_16x16x32_f16 v[128:131], v[178:181], v[186:189], 0
	v_mfma_f32_16x16x32_f16 v[100:103], v[160:163], v[194:197], 0
	v_mfma_f32_16x16x32_f16 v[96:99], v[178:181], v[194:197], 0
	v_mfma_f32_16x16x32_f16 v[84:87], v[160:163], v[206:209], 0
	v_mfma_f32_16x16x32_f16 v[80:83], v[178:181], v[206:209], 0
	v_mfma_f32_16x16x32_f16 v[68:71], v[160:163], v[214:217], 0
	v_mfma_f32_16x16x32_f16 v[64:67], v[178:181], v[214:217], 0
	v_mfma_f32_16x16x32_f16 v[132:135], v[164:167], v[190:193], v[132:135]
	v_mfma_f32_16x16x32_f16 v[128:131], v[182:185], v[190:193], v[128:131]
	v_mfma_f32_16x16x32_f16 v[100:103], v[164:167], v[198:201], v[100:103]
	v_mfma_f32_16x16x32_f16 v[96:99], v[182:185], v[198:201], v[96:99]
	v_mfma_f32_16x16x32_f16 v[84:87], v[164:167], v[210:213], v[84:87]
	v_mfma_f32_16x16x32_f16 v[80:83], v[182:185], v[210:213], v[80:83]
	v_mfma_f32_16x16x32_f16 v[68:71], v[164:167], v[218:221], v[68:71]
	v_mfma_f32_16x16x32_f16 v[64:67], v[182:185], v[218:221], v[64:67]
	s_barrier
	s_add_i32 s65, s55, s41
	v_lshl_add_u64 v[202:203], s[26:27], 0, v[148:149]
	s_mov_b32 m0, s65
	ds_read_b128 v[186:189], v173 offset:16384
	ds_read_b128 v[190:193], v173 offset:17408
	ds_read_b128 v[194:197], v173 offset:18432
	ds_read_b128 v[198:201], v173 offset:19456
	ds_read_b128 v[206:209], v173 offset:20480
	ds_read_b128 v[210:213], v173 offset:21504
	ds_read_b128 v[214:217], v173 offset:22528
	ds_read_b128 v[218:221], v173 offset:23552
	global_load_lds_dwordx4 v[202:203], off
	s_add_i32 m0, s65, 0x2000
	s_add_u32 s66, s26, 0x40000
	v_lshl_add_u64 v[222:223], s[26:27], 0, v[144:145]
	s_addc_u32 s67, s27, 0
	s_add_i32 s65, s56, s41
	global_load_lds_dwordx4 v[222:223], off
	v_lshl_add_u64 v[224:225], s[66:67], 0, v[148:149]
	s_mov_b32 m0, s65
	v_lshl_add_u64 v[226:227], s[34:35], 0, v[146:147]
	global_load_lds_dwordx4 v[224:225], off
	v_lshl_add_u64 v[224:225], s[66:67], 0, v[144:145]
	s_add_i32 m0, s65, 0x2000
	s_nop 0
	global_load_lds_dwordx4 v[224:225], off
	v_lshl_add_u64 v[224:225], s[34:35], 0, v[150:151]
	s_mov_b32 m0, s23
	s_nop 0
	global_load_lds_dwordx4 v[224:225], off
	s_mov_b32 m0, s46
	s_nop 0
	global_load_lds_dwordx4 v[226:227], off
	s_waitcnt vmcnt(8)
	s_waitcnt lgkmcnt(0)
	s_barrier
	s_waitcnt lgkmcnt(0)
	v_mfma_f32_16x16x32_f16 v[60:63], v[104:107], v[186:189], 0
	v_mfma_f32_16x16x32_f16 v[56:59], v[112:115], v[186:189], 0
	v_mfma_f32_16x16x32_f16 v[44:47], v[104:107], v[194:197], 0
	v_mfma_f32_16x16x32_f16 v[40:43], v[112:115], v[194:197], 0
	v_mfma_f32_16x16x32_f16 v[28:31], v[104:107], v[206:209], 0
	v_mfma_f32_16x16x32_f16 v[24:27], v[112:115], v[206:209], 0
	v_mfma_f32_16x16x32_f16 v[12:15], v[104:107], v[214:217], 0
	v_mfma_f32_16x16x32_f16 v[8:11], v[112:115], v[214:217], 0
	v_mfma_f32_16x16x32_f16 v[60:63], v[108:111], v[190:193], v[60:63]
	v_mfma_f32_16x16x32_f16 v[56:59], v[116:119], v[190:193], v[56:59]
	v_mfma_f32_16x16x32_f16 v[44:47], v[108:111], v[198:201], v[44:47]
	v_mfma_f32_16x16x32_f16 v[40:43], v[116:119], v[198:201], v[40:43]
	v_mfma_f32_16x16x32_f16 v[28:31], v[108:111], v[210:213], v[28:31]
	v_mfma_f32_16x16x32_f16 v[24:27], v[116:119], v[210:213], v[24:27]
	v_mfma_f32_16x16x32_f16 v[12:15], v[108:111], v[218:221], v[12:15]
	v_mfma_f32_16x16x32_f16 v[8:11], v[116:119], v[218:221], v[8:11]
	v_mfma_f32_16x16x32_f16 v[52:55], v[160:163], v[186:189], 0
	v_mfma_f32_16x16x32_f16 v[48:51], v[178:181], v[186:189], 0
	v_mfma_f32_16x16x32_f16 v[36:39], v[160:163], v[194:197], 0
	v_mfma_f32_16x16x32_f16 v[32:35], v[178:181], v[194:197], 0
	v_mfma_f32_16x16x32_f16 v[20:23], v[160:163], v[206:209], 0
	v_mfma_f32_16x16x32_f16 v[16:19], v[178:181], v[206:209], 0
	v_mfma_f32_16x16x32_f16 v[4:7], v[160:163], v[214:217], 0
	v_mfma_f32_16x16x32_f16 v[0:3], v[178:181], v[214:217], 0
	v_mfma_f32_16x16x32_f16 v[52:55], v[164:167], v[190:193], v[52:55]
	v_mfma_f32_16x16x32_f16 v[48:51], v[182:185], v[190:193], v[48:51]
	v_mfma_f32_16x16x32_f16 v[36:39], v[164:167], v[198:201], v[36:39]
	v_mfma_f32_16x16x32_f16 v[32:35], v[182:185], v[198:201], v[32:35]
	v_mfma_f32_16x16x32_f16 v[20:23], v[164:167], v[210:213], v[20:23]
	v_mfma_f32_16x16x32_f16 v[16:19], v[182:185], v[210:213], v[16:19]
	v_mfma_f32_16x16x32_f16 v[4:7], v[164:167], v[218:221], v[4:7]
	v_mfma_f32_16x16x32_f16 v[0:3], v[182:185], v[218:221], v[0:3]
	s_barrier
	s_add_i32 s65, 0, 0x18000
	s_add_i32 s66, 0, 0x1c000
	v_add_u32_e32 v116, s65, v169
	v_add_u32_e32 v177, s66, v169
	ds_read_b128 v[104:107], v116
	ds_read_b128 v[108:111], v116 offset:1024
	ds_read_b128 v[112:115], v116 offset:2048
	ds_read_b128 v[116:119], v116 offset:3072
	ds_read_b128 v[160:163], v177
	ds_read_b128 v[164:167], v177 offset:1024
	ds_read_b128 v[178:181], v177 offset:2048
	ds_read_b128 v[182:185], v177 offset:3072
	s_add_u32 s34, s34, 0x40000
	s_addc_u32 s35, s35, 0
	s_mov_b32 m0, s47
	v_lshl_add_u64 v[228:229], s[34:35], 0, v[150:151]
	ds_read_b128 v[186:189], v173 offset:32768
	ds_read_b128 v[190:193], v173 offset:33792
	ds_read_b128 v[194:197], v173 offset:34816
	ds_read_b128 v[198:201], v173 offset:35840
	ds_read_b128 v[206:209], v173 offset:36864
	ds_read_b128 v[210:213], v173 offset:37888
	ds_read_b128 v[214:217], v173 offset:38912
	ds_read_b128 v[218:221], v173 offset:39936
	global_load_lds_dwordx4 v[228:229], off
	v_lshl_add_u64 v[228:229], s[34:35], 0, v[146:147]
	s_mov_b32 m0, s48
	s_nop 0
	global_load_lds_dwordx4 v[228:229], off
	s_waitcnt vmcnt(8)
	s_waitcnt lgkmcnt(0)
	s_barrier
	s_waitcnt lgkmcnt(0)
	v_mfma_f32_16x16x32_f16 v[140:143], v[104:107], v[186:189], v[140:143]
	v_mfma_f32_16x16x32_f16 v[136:139], v[112:115], v[186:189], v[136:139]
	v_mfma_f32_16x16x32_f16 v[124:127], v[104:107], v[194:197], v[124:127]
	v_mfma_f32_16x16x32_f16 v[120:123], v[112:115], v[194:197], v[120:123]
	v_mfma_f32_16x16x32_f16 v[92:95], v[104:107], v[206:209], v[92:95]
	v_mfma_f32_16x16x32_f16 v[88:91], v[112:115], v[206:209], v[88:91]
	v_mfma_f32_16x16x32_f16 v[76:79], v[104:107], v[214:217], v[76:79]
	v_mfma_f32_16x16x32_f16 v[72:75], v[112:115], v[214:217], v[72:75]
	v_mfma_f32_16x16x32_f16 v[140:143], v[108:111], v[190:193], v[140:143]
	v_mfma_f32_16x16x32_f16 v[136:139], v[116:119], v[190:193], v[136:139]
	v_mfma_f32_16x16x32_f16 v[124:127], v[108:111], v[198:201], v[124:127]
	v_mfma_f32_16x16x32_f16 v[120:123], v[116:119], v[198:201], v[120:123]
	v_mfma_f32_16x16x32_f16 v[92:95], v[108:111], v[210:213], v[92:95]
	v_mfma_f32_16x16x32_f16 v[88:91], v[116:119], v[210:213], v[88:91]
	v_mfma_f32_16x16x32_f16 v[76:79], v[108:111], v[218:221], v[76:79]
	v_mfma_f32_16x16x32_f16 v[72:75], v[116:119], v[218:221], v[72:75]
	v_mfma_f32_16x16x32_f16 v[132:135], v[160:163], v[186:189], v[132:135]
	v_mfma_f32_16x16x32_f16 v[128:131], v[178:181], v[186:189], v[128:131]
	v_mfma_f32_16x16x32_f16 v[100:103], v[160:163], v[194:197], v[100:103]
	v_mfma_f32_16x16x32_f16 v[96:99], v[178:181], v[194:197], v[96:99]
	v_mfma_f32_16x16x32_f16 v[84:87], v[160:163], v[206:209], v[84:87]
	v_mfma_f32_16x16x32_f16 v[80:83], v[178:181], v[206:209], v[80:83]
	v_mfma_f32_16x16x32_f16 v[68:71], v[160:163], v[214:217], v[68:71]
	v_mfma_f32_16x16x32_f16 v[64:67], v[178:181], v[214:217], v[64:67]
	v_mfma_f32_16x16x32_f16 v[132:135], v[164:167], v[190:193], v[132:135]
	v_mfma_f32_16x16x32_f16 v[128:131], v[182:185], v[190:193], v[128:131]
	v_mfma_f32_16x16x32_f16 v[100:103], v[164:167], v[198:201], v[100:103]
	v_mfma_f32_16x16x32_f16 v[96:99], v[182:185], v[198:201], v[96:99]
	v_mfma_f32_16x16x32_f16 v[84:87], v[164:167], v[210:213], v[84:87]
	v_mfma_f32_16x16x32_f16 v[80:83], v[182:185], v[210:213], v[80:83]
	v_mfma_f32_16x16x32_f16 v[68:71], v[164:167], v[218:221], v[68:71]
	v_mfma_f32_16x16x32_f16 v[64:67], v[182:185], v[218:221], v[64:67]
	s_barrier
	s_add_i32 s34, s65, s41
	v_lshl_add_u64 v[202:203], v[202:203], 0, s[10:11]
	s_mov_b32 m0, s34
	ds_read_b128 v[186:189], v173 offset:49152
	ds_read_b128 v[190:193], v173 offset:50176
	ds_read_b128 v[194:197], v173 offset:51200
	ds_read_b128 v[198:201], v173 offset:52224
	ds_read_b128 v[206:209], v173 offset:53248
	ds_read_b128 v[210:213], v173 offset:54272
	ds_read_b128 v[214:217], v173 offset:55296
	ds_read_b128 v[218:221], v173 offset:56320
	global_load_lds_dwordx4 v[202:203], off
	s_add_i32 m0, s34, 0x2000
	s_add_u32 s26, s26, 0x40080
	v_lshl_add_u64 v[202:203], v[222:223], 0, s[10:11]
	s_addc_u32 s27, s27, 0
	s_add_i32 s34, s66, s41
	global_load_lds_dwordx4 v[202:203], off
	v_lshl_add_u64 v[202:203], s[26:27], 0, v[148:149]
	s_mov_b32 m0, s34
	s_nop 0
	global_load_lds_dwordx4 v[202:203], off
	v_lshl_add_u64 v[202:203], s[26:27], 0, v[144:145]
	s_add_i32 m0, s34, 0x2000
	s_nop 0
	global_load_lds_dwordx4 v[202:203], off
	v_lshl_add_u64 v[202:203], v[224:225], 0, s[10:11]
	s_mov_b32 m0, s52
	s_nop 0
	global_load_lds_dwordx4 v[202:203], off
	v_lshl_add_u64 v[202:203], v[226:227], 0, s[10:11]
	s_mov_b32 m0, s53
	s_nop 0
	global_load_lds_dwordx4 v[202:203], off
	s_waitcnt vmcnt(8)
	s_waitcnt lgkmcnt(0)
	s_barrier
	s_waitcnt lgkmcnt(0)
	v_mfma_f32_16x16x32_f16 v[60:63], v[104:107], v[186:189], v[60:63]
	v_mfma_f32_16x16x32_f16 v[56:59], v[112:115], v[186:189], v[56:59]
	v_mfma_f32_16x16x32_f16 v[44:47], v[104:107], v[194:197], v[44:47]
	v_mfma_f32_16x16x32_f16 v[40:43], v[112:115], v[194:197], v[40:43]
	v_mfma_f32_16x16x32_f16 v[28:31], v[104:107], v[206:209], v[28:31]
	v_mfma_f32_16x16x32_f16 v[24:27], v[112:115], v[206:209], v[24:27]
	v_mfma_f32_16x16x32_f16 v[12:15], v[104:107], v[214:217], v[12:15]
	v_mfma_f32_16x16x32_f16 v[8:11], v[112:115], v[214:217], v[8:11]
	v_mfma_f32_16x16x32_f16 v[60:63], v[108:111], v[190:193], v[60:63]
	v_mfma_f32_16x16x32_f16 v[56:59], v[116:119], v[190:193], v[56:59]
	v_mfma_f32_16x16x32_f16 v[44:47], v[108:111], v[198:201], v[44:47]
	v_mfma_f32_16x16x32_f16 v[40:43], v[116:119], v[198:201], v[40:43]
	v_mfma_f32_16x16x32_f16 v[28:31], v[108:111], v[210:213], v[28:31]
	v_mfma_f32_16x16x32_f16 v[24:27], v[116:119], v[210:213], v[24:27]
	v_mfma_f32_16x16x32_f16 v[12:15], v[108:111], v[218:221], v[12:15]
	v_mfma_f32_16x16x32_f16 v[8:11], v[116:119], v[218:221], v[8:11]
	v_mfma_f32_16x16x32_f16 v[52:55], v[160:163], v[186:189], v[52:55]
	v_mfma_f32_16x16x32_f16 v[48:51], v[178:181], v[186:189], v[48:51]
	v_mfma_f32_16x16x32_f16 v[36:39], v[160:163], v[194:197], v[36:39]
	v_mfma_f32_16x16x32_f16 v[32:35], v[178:181], v[194:197], v[32:35]
	v_mfma_f32_16x16x32_f16 v[20:23], v[160:163], v[206:209], v[20:23]
	v_mfma_f32_16x16x32_f16 v[16:19], v[178:181], v[206:209], v[16:19]
	v_mfma_f32_16x16x32_f16 v[4:7], v[160:163], v[214:217], v[4:7]
	v_mfma_f32_16x16x32_f16 v[0:3], v[178:181], v[214:217], v[0:3]
	v_mfma_f32_16x16x32_f16 v[52:55], v[164:167], v[190:193], v[52:55]
	v_mfma_f32_16x16x32_f16 v[48:51], v[182:185], v[190:193], v[48:51]
	v_mfma_f32_16x16x32_f16 v[36:39], v[164:167], v[198:201], v[36:39]
	v_mfma_f32_16x16x32_f16 v[32:35], v[182:185], v[198:201], v[32:35]
	v_mfma_f32_16x16x32_f16 v[20:23], v[164:167], v[210:213], v[20:23]
	v_mfma_f32_16x16x32_f16 v[16:19], v[182:185], v[210:213], v[16:19]
	v_mfma_f32_16x16x32_f16 v[4:7], v[164:167], v[218:221], v[4:7]
	v_mfma_f32_16x16x32_f16 v[0:3], v[182:185], v[218:221], v[0:3]
	s_barrier
	s_add_i32 s64, s64, 2
	s_add_u32 s24, s24, 0x100
	s_addc_u32 s25, s25, 0
	s_add_u32 s62, s62, 0x100
	s_addc_u32 s63, s63, 0
	s_cmp_gt_u32 s64, 13

.LBB0_1657:
	ds_read_b128 v[144:147], v169
	ds_read_b128 v[148:151], v169 offset:1024
	ds_read_b128 v[152:155], v169 offset:2048
	ds_read_b128 v[156:159], v169 offset:3072
	ds_read_b128 v[160:163], v170
	ds_read_b128 v[172:175], v170 offset:1024
	ds_read_b128 v[176:179], v170 offset:2048
	ds_read_b128 v[180:183], v170 offset:3072
	ds_read_b128 v[184:187], v171
	ds_read_b128 v[188:191], v171 offset:1024
	ds_read_b128 v[192:195], v171 offset:2048
	ds_read_b128 v[196:199], v171 offset:3072
	ds_read_b128 v[200:203], v171 offset:4096
	ds_read_b128 v[204:207], v171 offset:5120
	ds_read_b128 v[208:211], v171 offset:6144
	ds_read_b128 v[212:215], v171 offset:7168
	s_add_i32 s45, s45, 1
	s_mul_i32 s0, s45, s50
	s_mul_hi_u32 s1, s45, s9
	s_add_i32 s1, s1, s0
	s_mul_i32 s0, s45, s9
	s_add_u32 s0, s0, s8
	s_addc_u32 s1, s1, s33
	v_cmp_gt_i64_e32 vcc, s[0:1], v[142:143]
	v_cmp_lt_i64_e64 s[2:3], s[0:1], v[140:141]
	s_cbranch_vccnz .LBB0_1663
	s_ashr_i32 s1, s0, 31
	s_lshr_b32 s1, s1, 29
	s_add_i32 s20, s0, s1
	s_and_b32 s1, s20, -8
	s_sub_i32 s21, s0, s1
	s_cmp_gt_i32 s21, -1
	s_mov_b64 s[0:1], -1
	s_cbranch_scc0 .LBB0_1660
	s_lshl_b32 s26, s21, 5
	s_mov_b64 s[0:1], 0

.LBB0_1667:
	s_add_u32 s58, s24, 0x100
	s_addc_u32 s59, s25, 0
	s_mov_b32 s60, -2
	s_add_u32 s24, s22, 0x100
	s_addc_u32 s25, s23, 0
	s_cmp_eq_u32 s60, 40
	s_cselect_b32 s31, s3, s25
	s_cselect_b32 s30, s2, s24
	s_cselect_b32 s27, s21, s59
	s_cselect_b32 s26, s20, s58
	v_lshl_add_u64 v[164:165], s[22:23], 0, v[136:137]
	s_add_i32 m0, s41, 0xc000
	global_load_lds_dwordx4 v[164:165], off
	v_lshl_add_u64 v[164:165], s[22:23], 0, v[138:139]
	s_add_i32 m0, s41, 0xe000
	s_nop 0
	global_load_lds_dwordx4 v[164:165], off
	s_waitcnt vmcnt(8)
	s_waitcnt lgkmcnt(0)
	s_barrier
	s_waitcnt lgkmcnt(0)
	v_mfma_f32_16x16x32_f16 v[124:127], v[144:147], v[184:187], 0
	v_mfma_f32_16x16x32_f16 v[120:123], v[152:155], v[184:187], 0
	v_mfma_f32_16x16x32_f16 v[116:119], v[144:147], v[192:195], 0
	v_mfma_f32_16x16x32_f16 v[112:115], v[152:155], v[192:195], 0
	v_mfma_f32_16x16x32_f16 v[92:95], v[144:147], v[200:203], 0
	v_mfma_f32_16x16x32_f16 v[88:91], v[152:155], v[200:203], 0
	v_mfma_f32_16x16x32_f16 v[84:87], v[144:147], v[208:211], 0
	v_mfma_f32_16x16x32_f16 v[80:83], v[152:155], v[208:211], 0
	v_mfma_f32_16x16x32_f16 v[124:127], v[148:151], v[188:191], v[124:127]
	v_mfma_f32_16x16x32_f16 v[120:123], v[156:159], v[188:191], v[120:123]
	v_mfma_f32_16x16x32_f16 v[116:119], v[148:151], v[196:199], v[116:119]
	v_mfma_f32_16x16x32_f16 v[112:115], v[156:159], v[196:199], v[112:115]
	v_mfma_f32_16x16x32_f16 v[92:95], v[148:151], v[204:207], v[92:95]
	v_mfma_f32_16x16x32_f16 v[88:91], v[156:159], v[204:207], v[88:91]
	v_mfma_f32_16x16x32_f16 v[84:87], v[148:151], v[212:215], v[84:87]
	v_mfma_f32_16x16x32_f16 v[80:83], v[156:159], v[212:215], v[80:83]
	v_mfma_f32_16x16x32_f16 v[108:111], v[160:163], v[184:187], 0
	v_mfma_f32_16x16x32_f16 v[104:107], v[176:179], v[184:187], 0
	v_mfma_f32_16x16x32_f16 v[100:103], v[160:163], v[192:195], 0
	v_mfma_f32_16x16x32_f16 v[96:99], v[176:179], v[192:195], 0
	v_mfma_f32_16x16x32_f16 v[76:79], v[160:163], v[200:203], 0
	v_mfma_f32_16x16x32_f16 v[72:75], v[176:179], v[200:203], 0
	v_mfma_f32_16x16x32_f16 v[68:71], v[160:163], v[208:211], 0
	v_mfma_f32_16x16x32_f16 v[64:67], v[176:179], v[208:211], 0
	v_mfma_f32_16x16x32_f16 v[108:111], v[172:175], v[188:191], v[108:111]
	v_mfma_f32_16x16x32_f16 v[104:107], v[180:183], v[188:191], v[104:107]
	v_mfma_f32_16x16x32_f16 v[100:103], v[172:175], v[196:199], v[100:103]
	v_mfma_f32_16x16x32_f16 v[96:99], v[180:183], v[196:199], v[96:99]
	v_mfma_f32_16x16x32_f16 v[76:79], v[172:175], v[204:207], v[76:79]
	v_mfma_f32_16x16x32_f16 v[72:75], v[180:183], v[204:207], v[72:75]
	v_mfma_f32_16x16x32_f16 v[68:71], v[172:175], v[212:215], v[68:71]
	v_mfma_f32_16x16x32_f16 v[64:67], v[180:183], v[212:215], v[64:67]
	s_barrier
	s_add_i32 s22, s51, s40
	v_lshl_add_u64 v[164:165], s[26:27], 0, v[130:131]
	s_mov_b32 m0, s22
	ds_read_b128 v[184:187], v171 offset:16384
	ds_read_b128 v[188:191], v171 offset:17408
	ds_read_b128 v[192:195], v171 offset:18432
	ds_read_b128 v[196:199], v171 offset:19456
	ds_read_b128 v[200:203], v171 offset:20480
	ds_read_b128 v[204:207], v171 offset:21504
	ds_read_b128 v[208:211], v171 offset:22528
	ds_read_b128 v[212:215], v171 offset:23552
	global_load_lds_dwordx4 v[164:165], off
	s_add_i32 m0, s22, 0x2000
	s_add_u32 s22, s26, 0xb0000
	v_lshl_add_u64 v[216:217], s[26:27], 0, v[134:135]
	s_addc_u32 s23, s27, 0
	s_add_i32 s61, s52, s40
	global_load_lds_dwordx4 v[216:217], off
	v_lshl_add_u64 v[218:219], s[22:23], 0, v[130:131]
	s_mov_b32 m0, s61
	v_lshl_add_u64 v[220:221], s[30:31], 0, v[132:133]
	global_load_lds_dwordx4 v[218:219], off
	v_lshl_add_u64 v[218:219], s[22:23], 0, v[134:135]
	s_add_i32 m0, s61, 0x2000
	s_nop 0
	global_load_lds_dwordx4 v[218:219], off
	v_lshl_add_u64 v[218:219], s[30:31], 0, v[128:129]
	s_mov_b32 m0, s41
	s_nop 0
	global_load_lds_dwordx4 v[218:219], off
	s_mov_b32 m0, s42
	s_nop 0
	global_load_lds_dwordx4 v[220:221], off
	s_waitcnt vmcnt(8)
	s_waitcnt lgkmcnt(0)
	s_barrier
	s_waitcnt lgkmcnt(0)
	v_mfma_f32_16x16x32_f16 v[60:63], v[144:147], v[184:187], 0
	v_mfma_f32_16x16x32_f16 v[56:59], v[152:155], v[184:187], 0
	v_mfma_f32_16x16x32_f16 v[52:55], v[144:147], v[192:195], 0
	v_mfma_f32_16x16x32_f16 v[48:51], v[152:155], v[192:195], 0
	v_mfma_f32_16x16x32_f16 v[28:31], v[144:147], v[200:203], 0
	v_mfma_f32_16x16x32_f16 v[24:27], v[152:155], v[200:203], 0
	v_mfma_f32_16x16x32_f16 v[20:23], v[144:147], v[208:211], 0
	v_mfma_f32_16x16x32_f16 v[16:19], v[152:155], v[208:211], 0
	v_mfma_f32_16x16x32_f16 v[60:63], v[148:151], v[188:191], v[60:63]
	v_mfma_f32_16x16x32_f16 v[56:59], v[156:159], v[188:191], v[56:59]
	v_mfma_f32_16x16x32_f16 v[52:55], v[148:151], v[196:199], v[52:55]
	v_mfma_f32_16x16x32_f16 v[48:51], v[156:159], v[196:199], v[48:51]
	v_mfma_f32_16x16x32_f16 v[28:31], v[148:151], v[204:207], v[28:31]
	v_mfma_f32_16x16x32_f16 v[24:27], v[156:159], v[204:207], v[24:27]
	v_mfma_f32_16x16x32_f16 v[20:23], v[148:151], v[212:215], v[20:23]
	v_mfma_f32_16x16x32_f16 v[16:19], v[156:159], v[212:215], v[16:19]
	v_mfma_f32_16x16x32_f16 v[44:47], v[160:163], v[184:187], 0
	v_mfma_f32_16x16x32_f16 v[40:43], v[176:179], v[184:187], 0
	v_mfma_f32_16x16x32_f16 v[36:39], v[160:163], v[192:195], 0
	v_mfma_f32_16x16x32_f16 v[32:35], v[176:179], v[192:195], 0
	v_mfma_f32_16x16x32_f16 v[12:15], v[160:163], v[200:203], 0
	v_mfma_f32_16x16x32_f16 v[8:11], v[176:179], v[200:203], 0
	v_mfma_f32_16x16x32_f16 v[4:7], v[160:163], v[208:211], 0
	v_mfma_f32_16x16x32_f16 v[0:3], v[176:179], v[208:211], 0
	v_mfma_f32_16x16x32_f16 v[44:47], v[172:175], v[188:191], v[44:47]
	v_mfma_f32_16x16x32_f16 v[40:43], v[180:183], v[188:191], v[40:43]
	v_mfma_f32_16x16x32_f16 v[36:39], v[172:175], v[196:199], v[36:39]
	v_mfma_f32_16x16x32_f16 v[32:35], v[180:183], v[196:199], v[32:35]
	v_mfma_f32_16x16x32_f16 v[12:15], v[172:175], v[204:207], v[12:15]
	v_mfma_f32_16x16x32_f16 v[8:11], v[180:183], v[204:207], v[8:11]
	v_mfma_f32_16x16x32_f16 v[4:7], v[172:175], v[212:215], v[4:7]
	v_mfma_f32_16x16x32_f16 v[0:3], v[180:183], v[212:215], v[0:3]
	s_barrier
	s_add_i32 s61, 0, 0x18000
	s_add_i32 s62, 0, 0x1c000
	v_add_u32_e32 v156, s61, v167
	v_add_u32_e32 v180, s62, v167
	ds_read_b128 v[144:147], v156
	ds_read_b128 v[148:151], v156 offset:1024
	ds_read_b128 v[152:155], v156 offset:2048
	ds_read_b128 v[156:159], v156 offset:3072
	ds_read_b128 v[160:163], v180
	ds_read_b128 v[172:175], v180 offset:1024
	ds_read_b128 v[176:179], v180 offset:2048
	ds_read_b128 v[180:183], v180 offset:3072
	s_add_u32 s22, s30, 0xb0000
	s_addc_u32 s23, s31, 0
	s_mov_b32 m0, s43
	v_lshl_add_u64 v[222:223], s[22:23], 0, v[128:129]
	ds_read_b128 v[184:187], v171 offset:32768
	ds_read_b128 v[188:191], v171 offset:33792
	ds_read_b128 v[192:195], v171 offset:34816
	ds_read_b128 v[196:199], v171 offset:35840
	ds_read_b128 v[200:203], v171 offset:36864
	ds_read_b128 v[204:207], v171 offset:37888
	ds_read_b128 v[208:211], v171 offset:38912
	ds_read_b128 v[212:215], v171 offset:39936
	global_load_lds_dwordx4 v[222:223], off
	v_lshl_add_u64 v[222:223], s[22:23], 0, v[132:133]
	s_mov_b32 m0, s44
	s_nop 0
	global_load_lds_dwordx4 v[222:223], off
	s_waitcnt vmcnt(8)
	s_waitcnt lgkmcnt(0)
	s_barrier
	s_waitcnt lgkmcnt(0)
	v_mfma_f32_16x16x32_f16 v[124:127], v[144:147], v[184:187], v[124:127]
	v_mfma_f32_16x16x32_f16 v[120:123], v[152:155], v[184:187], v[120:123]
	v_mfma_f32_16x16x32_f16 v[116:119], v[144:147], v[192:195], v[116:119]
	v_mfma_f32_16x16x32_f16 v[112:115], v[152:155], v[192:195], v[112:115]
	v_mfma_f32_16x16x32_f16 v[92:95], v[144:147], v[200:203], v[92:95]
	v_mfma_f32_16x16x32_f16 v[88:91], v[152:155], v[200:203], v[88:91]
	v_mfma_f32_16x16x32_f16 v[84:87], v[144:147], v[208:211], v[84:87]
	v_mfma_f32_16x16x32_f16 v[80:83], v[152:155], v[208:211], v[80:83]
	v_mfma_f32_16x16x32_f16 v[124:127], v[148:151], v[188:191], v[124:127]
	v_mfma_f32_16x16x32_f16 v[120:123], v[156:159], v[188:191], v[120:123]
	v_mfma_f32_16x16x32_f16 v[116:119], v[148:151], v[196:199], v[116:119]
	v_mfma_f32_16x16x32_f16 v[112:115], v[156:159], v[196:199], v[112:115]
	v_mfma_f32_16x16x32_f16 v[92:95], v[148:151], v[204:207], v[92:95]
	v_mfma_f32_16x16x32_f16 v[88:91], v[156:159], v[204:207], v[88:91]
	v_mfma_f32_16x16x32_f16 v[84:87], v[148:151], v[212:215], v[84:87]
	v_mfma_f32_16x16x32_f16 v[80:83], v[156:159], v[212:215], v[80:83]
	v_mfma_f32_16x16x32_f16 v[108:111], v[160:163], v[184:187], v[108:111]
	v_mfma_f32_16x16x32_f16 v[104:107], v[176:179], v[184:187], v[104:107]
	v_mfma_f32_16x16x32_f16 v[100:103], v[160:163], v[192:195], v[100:103]
	v_mfma_f32_16x16x32_f16 v[96:99], v[176:179], v[192:195], v[96:99]
	v_mfma_f32_16x16x32_f16 v[76:79], v[160:163], v[200:203], v[76:79]
	v_mfma_f32_16x16x32_f16 v[72:75], v[176:179], v[200:203], v[72:75]
	v_mfma_f32_16x16x32_f16 v[68:71], v[160:163], v[208:211], v[68:71]
	v_mfma_f32_16x16x32_f16 v[64:67], v[176:179], v[208:211], v[64:67]
	v_mfma_f32_16x16x32_f16 v[108:111], v[172:175], v[188:191], v[108:111]
	v_mfma_f32_16x16x32_f16 v[104:107], v[180:183], v[188:191], v[104:107]
	v_mfma_f32_16x16x32_f16 v[100:103], v[172:175], v[196:199], v[100:103]
	v_mfma_f32_16x16x32_f16 v[96:99], v[180:183], v[196:199], v[96:99]
	v_mfma_f32_16x16x32_f16 v[76:79], v[172:175], v[204:207], v[76:79]
	v_mfma_f32_16x16x32_f16 v[72:75], v[180:183], v[204:207], v[72:75]
	v_mfma_f32_16x16x32_f16 v[68:71], v[172:175], v[212:215], v[68:71]
	v_mfma_f32_16x16x32_f16 v[64:67], v[180:183], v[212:215], v[64:67]
	s_barrier
	s_add_i32 s22, s61, s40
	v_lshl_add_u64 v[164:165], v[164:165], 0, s[10:11]
	s_mov_b32 m0, s22
	ds_read_b128 v[184:187], v171 offset:49152
	ds_read_b128 v[188:191], v171 offset:50176
	ds_read_b128 v[192:195], v171 offset:51200
	ds_read_b128 v[196:199], v171 offset:52224
	ds_read_b128 v[200:203], v171 offset:53248
	ds_read_b128 v[204:207], v171 offset:54272
	ds_read_b128 v[208:211], v171 offset:55296
	ds_read_b128 v[212:215], v171 offset:56320
	global_load_lds_dwordx4 v[164:165], off
	s_add_i32 m0, s22, 0x2000
	s_add_u32 s22, s26, 0xb0080
	v_lshl_add_u64 v[164:165], v[216:217], 0, s[10:11]
	s_addc_u32 s23, s27, 0
	s_add_i32 s26, s62, s40
	global_load_lds_dwordx4 v[164:165], off
	v_lshl_add_u64 v[164:165], s[22:23], 0, v[130:131]
	s_mov_b32 m0, s26
	s_nop 0
	global_load_lds_dwordx4 v[164:165], off
	v_lshl_add_u64 v[164:165], s[22:23], 0, v[134:135]
	s_add_i32 m0, s26, 0x2000
	s_nop 0
	global_load_lds_dwordx4 v[164:165], off
	v_lshl_add_u64 v[164:165], v[218:219], 0, s[10:11]
	s_mov_b32 m0, s48
	s_nop 0
	global_load_lds_dwordx4 v[164:165], off
	v_lshl_add_u64 v[164:165], v[220:221], 0, s[10:11]
	s_mov_b32 m0, s49
	s_nop 0
	global_load_lds_dwordx4 v[164:165], off
	s_waitcnt vmcnt(8)
	s_waitcnt lgkmcnt(0)
	s_barrier
	s_waitcnt lgkmcnt(0)
	v_mfma_f32_16x16x32_f16 v[60:63], v[144:147], v[184:187], v[60:63]
	v_mfma_f32_16x16x32_f16 v[56:59], v[152:155], v[184:187], v[56:59]
	v_mfma_f32_16x16x32_f16 v[52:55], v[144:147], v[192:195], v[52:55]
	v_mfma_f32_16x16x32_f16 v[48:51], v[152:155], v[192:195], v[48:51]
	v_mfma_f32_16x16x32_f16 v[28:31], v[144:147], v[200:203], v[28:31]
	v_mfma_f32_16x16x32_f16 v[24:27], v[152:155], v[200:203], v[24:27]
	v_mfma_f32_16x16x32_f16 v[20:23], v[144:147], v[208:211], v[20:23]
	v_mfma_f32_16x16x32_f16 v[16:19], v[152:155], v[208:211], v[16:19]
	v_mfma_f32_16x16x32_f16 v[60:63], v[148:151], v[188:191], v[60:63]
	v_mfma_f32_16x16x32_f16 v[56:59], v[156:159], v[188:191], v[56:59]
	v_mfma_f32_16x16x32_f16 v[52:55], v[148:151], v[196:199], v[52:55]
	v_mfma_f32_16x16x32_f16 v[48:51], v[156:159], v[196:199], v[48:51]
	v_mfma_f32_16x16x32_f16 v[28:31], v[148:151], v[204:207], v[28:31]
	v_mfma_f32_16x16x32_f16 v[24:27], v[156:159], v[204:207], v[24:27]
	v_mfma_f32_16x16x32_f16 v[20:23], v[148:151], v[212:215], v[20:23]
	v_mfma_f32_16x16x32_f16 v[16:19], v[156:159], v[212:215], v[16:19]
	v_mfma_f32_16x16x32_f16 v[44:47], v[160:163], v[184:187], v[44:47]
	v_mfma_f32_16x16x32_f16 v[40:43], v[176:179], v[184:187], v[40:43]
	v_mfma_f32_16x16x32_f16 v[36:39], v[160:163], v[192:195], v[36:39]
	v_mfma_f32_16x16x32_f16 v[32:35], v[176:179], v[192:195], v[32:35]
	v_mfma_f32_16x16x32_f16 v[12:15], v[160:163], v[200:203], v[12:15]
	v_mfma_f32_16x16x32_f16 v[8:11], v[176:179], v[200:203], v[8:11]
	v_mfma_f32_16x16x32_f16 v[4:7], v[160:163], v[208:211], v[4:7]
	v_mfma_f32_16x16x32_f16 v[0:3], v[176:179], v[208:211], v[0:3]
	v_mfma_f32_16x16x32_f16 v[44:47], v[172:175], v[188:191], v[44:47]
	v_mfma_f32_16x16x32_f16 v[40:43], v[180:183], v[188:191], v[40:43]
	v_mfma_f32_16x16x32_f16 v[36:39], v[172:175], v[196:199], v[36:39]
	v_mfma_f32_16x16x32_f16 v[32:35], v[180:183], v[196:199], v[32:35]
	v_mfma_f32_16x16x32_f16 v[12:15], v[172:175], v[204:207], v[12:15]
	v_mfma_f32_16x16x32_f16 v[8:11], v[180:183], v[204:207], v[8:11]
	v_mfma_f32_16x16x32_f16 v[4:7], v[172:175], v[212:215], v[4:7]
	v_mfma_f32_16x16x32_f16 v[0:3], v[180:183], v[212:215], v[0:3]
	s_barrier
	s_add_i32 s60, s60, 2
	s_add_u32 s58, s58, 0x100
	s_addc_u32 s59, s59, 0
	s_cmp_gt_u32 s60, 41
	s_mov_b64 s[22:23], s[24:25]
